# K-loops: s_setprio 1 before the opening barrier, duplicate lgkmcnt(0) after it deleted, s_setprio 0 behind the closing barrier (3 fewer issue slots per MFMA section on its rendezvous-to-rendezvous pat
# speedup vs baseline: 1.0053x; 1.0053x over previous
; #define PG8_STAGE(bufoff, gbase, voff) do { _Pragma("unroll") for (int _i = 0; _i < 2; ++_i) \
;         __builtin_amdgcn_global_load_lds((const unsigned*)((const char*)(gbase) + (voff)[_i]), (LAS unsigned*)(lds + (bufoff) + ldsw + _i * 8192), 16, 0, 0); } while (0)
; #define PG8_LDA(dst, b, h) do { _Pragma("unroll") for (int m = 0; m < NM; ++m) _Pragma("unroll") for (int k = 0; k < 2; ++k) dst[m][k] = *(const LAS bf16x8*)(lds + PG8_SA(b, h) + aoff + m * 2048 + k * 1024); } while (0)
; #define PG8_LDB(dst, b, h) do { _Pragma("unroll") for (int n = 0; n < 2; ++n) _Pragma("unroll") for (int k = 0; k < 2; ++k) dst[n][k] = *(const LAS bf16x8*)(lds + PG8_SB(b, h) + boff + n * 2048 + k * 1024); } while (0)
; #define PG8_MMA(ai, bj, At, Bt) do { __builtin_amdgcn_s_setprio(1); _Pragma("unroll") for (int m = 0; m < NM; ++m) _Pragma("unroll") for (int n = 0; n < 2; ++n) _Pragma("unroll") for (int k = 0; k < 2; ++k) \
;         acc[ai][bj][m][n] = __builtin_amdgcn_mfma_f32_16x16x32_bf16(Bt[n][k], At[m][k], acc[ai][bj][m][n], 0, 0, 0); __builtin_amdgcn_s_setprio(0); } while (0)
; #define PG8_WAIT_V(n) asm volatile("s_waitcnt vmcnt(" #n ")" ::: "memory")
; #define PG8_WAIT_L(n) asm volatile("s_waitcnt lgkmcnt(" #n ")" ::: "memory")
; #define PG8_BAR __builtin_amdgcn_s_barrier()
; #define PG8_SCHED __builtin_amdgcn_sched_barrier(0)
;     ...
;             PG8_LDB(B0, 0, 0); PG8_LDB(B1, 0, 1); PG8_SCHED; PG8_LDA(At, 0, 0); PG8_STAGE(PG8_SA(1, 1), a1 + hstepA, voffA);
;             PG8_WAIT_V(8); PG8_WAIT_L(0); PG8_BAR; PG8_MMA(0, 0, At, B0); PG8_MMA(0, 1, At, B1); PG8_BAR; PG8_SCHED;
;             PG8_LDA(At, 0, 1); PG8_STAGE(PG8_SB(0, 0), b2, voffB); PG8_STAGE(PG8_SB(0, 1), b2 + hstepB, voffB); PG8_STAGE(PG8_SA(0, 0), a2, voffA);
.LBB0_200:
	ds_read_b128 v[26:29], v172
	ds_read_b128 v[30:33], v172 offset:1024
	ds_read_b128 v[42:45], v172 offset:2048
	ds_read_b128 v[46:49], v172 offset:3072
	ds_read_b128 v[146:149], v173
	ds_read_b128 v[150:153], v173 offset:1024
	ds_read_b128 v[164:167], v173 offset:2048
	ds_read_b128 v[168:171], v173 offset:3072
	s_add_u32 s30, s28, 0xfff80080
	s_addc_u32 s31, s29, -1
	s_cmp_eq_u32 s56, 28
	s_cselect_b32 s35, s2, s31
	s_cselect_b32 s34, s3, s30
	s_cselect_b32 s31, s9, s54
	s_cselect_b32 s30, s21, s23
	s_cselect_b32 s100, -1, 0
	s_andn2_b32 s100, s100, s101
	s_add_i32 m0, s43, 0xc000
	ds_read_b128 v[178:181], v174
	ds_read_b128 v[182:185], v174 offset:1024
	ds_read_b128 v[186:189], v174 offset:2048
	ds_read_b128 v[190:193], v174 offset:3072
	ds_read_b128 v[194:197], v174 offset:4096
	ds_read_b128 v[198:201], v174 offset:5120
	ds_read_b128 v[202:205], v174 offset:6144
	ds_read_b128 v[206:209], v174 offset:7168
	global_load_lds_dwordx4 v160, s[28:29]
	s_add_i32 m0, s43, 0xe000
	s_nop 0
	global_load_lds_dwordx4 v162, s[28:29]
	s_waitcnt vmcnt(8)
	s_waitcnt lgkmcnt(0)
	s_setprio 1
	s_barrier
	v_mfma_f32_16x16x32_bf16 v[142:145], v[26:29], v[178:181], v[142:145]
	v_mfma_f32_16x16x32_bf16 v[138:141], v[42:45], v[178:181], v[138:141]
	v_mfma_f32_16x16x32_bf16 v[126:129], v[26:29], v[186:189], v[126:129]
	v_mfma_f32_16x16x32_bf16 v[122:125], v[42:45], v[186:189], v[122:125]
	v_mfma_f32_16x16x32_bf16 v[110:113], v[26:29], v[194:197], v[110:113]
	v_mfma_f32_16x16x32_bf16 v[106:109], v[42:45], v[194:197], v[106:109]
	v_mfma_f32_16x16x32_bf16 v[94:97], v[26:29], v[202:205], v[94:97]
	v_mfma_f32_16x16x32_bf16 v[90:93], v[42:45], v[202:205], v[90:93]
	v_mfma_f32_16x16x32_bf16 v[142:145], v[30:33], v[182:185], v[142:145]
	v_mfma_f32_16x16x32_bf16 v[138:141], v[46:49], v[182:185], v[138:141]
	v_mfma_f32_16x16x32_bf16 v[126:129], v[30:33], v[190:193], v[126:129]
	v_mfma_f32_16x16x32_bf16 v[122:125], v[46:49], v[190:193], v[122:125]
	v_mfma_f32_16x16x32_bf16 v[110:113], v[30:33], v[198:201], v[110:113]
	v_mfma_f32_16x16x32_bf16 v[106:109], v[46:49], v[198:201], v[106:109]
	v_mfma_f32_16x16x32_bf16 v[94:97], v[30:33], v[206:209], v[94:97]
	v_mfma_f32_16x16x32_bf16 v[90:93], v[46:49], v[206:209], v[90:93]
	s_setprio 0
	s_setprio 1
	v_mfma_f32_16x16x32_bf16 v[134:137], v[146:149], v[178:181], v[134:137]
	v_mfma_f32_16x16x32_bf16 v[130:133], v[164:167], v[178:181], v[130:133]
	v_mfma_f32_16x16x32_bf16 v[118:121], v[146:149], v[186:189], v[118:121]
	v_mfma_f32_16x16x32_bf16 v[114:117], v[164:167], v[186:189], v[114:117]
	v_mfma_f32_16x16x32_bf16 v[102:105], v[146:149], v[194:197], v[102:105]
	v_mfma_f32_16x16x32_bf16 v[98:101], v[164:167], v[194:197], v[98:101]
	v_mfma_f32_16x16x32_bf16 v[86:89], v[146:149], v[202:205], v[86:89]
	v_mfma_f32_16x16x32_bf16 v[82:85], v[164:167], v[202:205], v[82:85]
	v_mfma_f32_16x16x32_bf16 v[134:137], v[150:153], v[182:185], v[134:137]
	v_mfma_f32_16x16x32_bf16 v[130:133], v[168:171], v[182:185], v[130:133]
	v_mfma_f32_16x16x32_bf16 v[118:121], v[150:153], v[190:193], v[118:121]
	v_mfma_f32_16x16x32_bf16 v[114:117], v[168:171], v[190:193], v[114:117]
	v_mfma_f32_16x16x32_bf16 v[102:105], v[150:153], v[198:201], v[102:105]
	v_mfma_f32_16x16x32_bf16 v[98:101], v[168:171], v[198:201], v[98:101]
	v_mfma_f32_16x16x32_bf16 v[86:89], v[150:153], v[206:209], v[86:89]
	v_mfma_f32_16x16x32_bf16 v[82:85], v[168:171], v[206:209], v[82:85]
	s_barrier
	s_setprio 0
	s_mov_b32 m0, s39
	v_lshl_add_u64 v[210:211], s[30:31], 0, v[0:1]
	s_add_u32 s72, s30, 0x80000
	s_addc_u32 s73, s31, 0
	ds_read_b128 v[178:181], v174 offset:16384
	ds_read_b128 v[182:185], v174 offset:17408
	ds_read_b128 v[186:189], v174 offset:18432
	ds_read_b128 v[190:193], v174 offset:19456
	ds_read_b128 v[194:197], v174 offset:20480
	ds_read_b128 v[198:201], v174 offset:21504
	ds_read_b128 v[202:205], v174 offset:22528
	ds_read_b128 v[206:209], v174 offset:23552
	s_cmp_lg_u32 s100, 0
	s_cbranch_scc1 .Ltl_ic_0s
	global_load_lds_dwordx4 v0, s[30:31]
	v_lshl_add_u64 v[212:213], s[30:31], 0, v[158:159]
	s_mov_b32 m0, s40
	s_nop 0
	global_load_lds_dwordx4 v158, s[30:31]
	s_mov_b32 m0, s41
	v_lshl_add_u64 v[216:217], s[34:35], 0, v[156:157]
	global_load_lds_dwordx4 v0, s[72:73]
	s_mov_b32 m0, s42
	s_nop 0
	global_load_lds_dwordx4 v158, s[72:73]
	v_lshl_add_u64 v[214:215], s[34:35], 0, v[154:155]
	s_mov_b32 m0, s43
	s_nop 0
	global_load_lds_dwordx4 v154, s[34:35]
	s_mov_b32 m0, s44
	s_nop 0
	global_load_lds_dwordx4 v156, s[34:35]
	s_waitcnt vmcnt(8)
	s_branch .Ltl_ic_0d

; #define PG8_STAGE(bufoff, gbase, voff) do { _Pragma("unroll") for (int _i = 0; _i < 2; ++_i) \
;         __builtin_amdgcn_global_load_lds((const unsigned*)((const char*)(gbase) + (voff)[_i]), (LAS unsigned*)(lds + (bufoff) + ldsw + _i * 8192), 16, 0, 0); } while (0)
; #define PG8_LDA(dst, b, h) do { _Pragma("unroll") for (int m = 0; m < NM; ++m) _Pragma("unroll") for (int k = 0; k < 2; ++k) dst[m][k] = *(const LAS bf16x8*)(lds + PG8_SA(b, h) + aoff + m * 2048 + k * 1024); } while (0)
; #define PG8_LDB(dst, b, h) do { _Pragma("unroll") for (int n = 0; n < 2; ++n) _Pragma("unroll") for (int k = 0; k < 2; ++k) dst[n][k] = *(const LAS bf16x8*)(lds + PG8_SB(b, h) + boff + n * 2048 + k * 1024); } while (0)
; #define PG8_MMA(ai, bj, At, Bt) do { __builtin_amdgcn_s_setprio(1); _Pragma("unroll") for (int m = 0; m < NM; ++m) _Pragma("unroll") for (int n = 0; n < 2; ++n) _Pragma("unroll") for (int k = 0; k < 2; ++k) \
;         acc[ai][bj][m][n] = __builtin_amdgcn_mfma_f32_16x16x32_bf16(Bt[n][k], At[m][k], acc[ai][bj][m][n], 0, 0, 0); __builtin_amdgcn_s_setprio(0); } while (0)
; #define PG8_WAIT_V(n) asm volatile("s_waitcnt vmcnt(" #n ")" ::: "memory")
; #define PG8_WAIT_L(n) asm volatile("s_waitcnt lgkmcnt(" #n ")" ::: "memory")
; #define PG8_BAR __builtin_amdgcn_s_barrier()
; #define PG8_SCHED __builtin_amdgcn_sched_barrier(0)
;     ...
;             PG8_WAIT_V(8); PG8_WAIT_L(0); PG8_BAR; PG8_MMA(1, 0, At, B0); PG8_MMA(1, 1, At, B1); PG8_BAR; PG8_SCHED;
;             PG8_LDB(B0, 1, 0); PG8_LDB(B1, 1, 1); PG8_SCHED; PG8_LDA(At, 1, 0); PG8_STAGE(PG8_SA(0, 1), a2 + hstepA, voffA);
.Ltl_ic_0d:
	s_waitcnt lgkmcnt(0)
	s_setprio 1
	s_barrier
	v_mfma_f32_16x16x32_bf16 v[78:81], v[26:29], v[178:181], v[78:81]
	v_mfma_f32_16x16x32_bf16 v[74:77], v[42:45], v[178:181], v[74:77]
	v_mfma_f32_16x16x32_bf16 v[62:65], v[26:29], v[186:189], v[62:65]
	v_mfma_f32_16x16x32_bf16 v[58:61], v[42:45], v[186:189], v[58:61]
	v_mfma_f32_16x16x32_bf16 v[38:41], v[26:29], v[194:197], v[38:41]
	v_mfma_f32_16x16x32_bf16 v[34:37], v[42:45], v[194:197], v[34:37]
	v_mfma_f32_16x16x32_bf16 v[14:17], v[26:29], v[202:205], v[14:17]
	v_mfma_f32_16x16x32_bf16 v[10:13], v[42:45], v[202:205], v[10:13]
	v_mfma_f32_16x16x32_bf16 v[78:81], v[30:33], v[182:185], v[78:81]
	v_mfma_f32_16x16x32_bf16 v[74:77], v[46:49], v[182:185], v[74:77]
	v_mfma_f32_16x16x32_bf16 v[62:65], v[30:33], v[190:193], v[62:65]
	v_mfma_f32_16x16x32_bf16 v[58:61], v[46:49], v[190:193], v[58:61]
	v_mfma_f32_16x16x32_bf16 v[38:41], v[30:33], v[198:201], v[38:41]
	v_mfma_f32_16x16x32_bf16 v[34:37], v[46:49], v[198:201], v[34:37]
	v_mfma_f32_16x16x32_bf16 v[14:17], v[30:33], v[206:209], v[14:17]
	v_mfma_f32_16x16x32_bf16 v[10:13], v[46:49], v[206:209], v[10:13]
	s_setprio 0
	s_setprio 1
	v_mfma_f32_16x16x32_bf16 v[22:25], v[146:149], v[194:197], v[22:25]
	v_mfma_f32_16x16x32_bf16 v[18:21], v[164:167], v[194:197], v[18:21]
	v_mfma_f32_16x16x32_bf16 v[6:9], v[146:149], v[202:205], v[6:9]
	v_mfma_f32_16x16x32_bf16 v[2:5], v[164:167], v[202:205], v[2:5]
	v_mfma_f32_16x16x32_bf16 v[26:29], v[146:149], v[178:181], v[70:73]
	v_mfma_f32_16x16x32_bf16 v[30:33], v[164:167], v[178:181], v[66:69]
	v_mfma_f32_16x16x32_bf16 v[42:45], v[146:149], v[186:189], v[54:57]
	v_mfma_f32_16x16x32_bf16 v[46:49], v[164:167], v[186:189], v[50:53]
	v_mfma_f32_16x16x32_bf16 v[22:25], v[150:153], v[198:201], v[22:25]
	v_mfma_f32_16x16x32_bf16 v[18:21], v[168:171], v[198:201], v[18:21]
	v_mfma_f32_16x16x32_bf16 v[6:9], v[150:153], v[206:209], v[6:9]
	v_mfma_f32_16x16x32_bf16 v[2:5], v[168:171], v[206:209], v[2:5]
	v_mfma_f32_16x16x32_bf16 v[26:29], v[150:153], v[182:185], v[26:29]
	v_mfma_f32_16x16x32_bf16 v[30:33], v[168:171], v[182:185], v[30:33]
	v_mfma_f32_16x16x32_bf16 v[42:45], v[150:153], v[190:193], v[42:45]
	v_mfma_f32_16x16x32_bf16 v[46:49], v[168:171], v[190:193], v[46:49]
	s_barrier
	s_setprio 0
	ds_read_b128 v[50:53], v175
	ds_read_b128 v[54:57], v175 offset:1024
	ds_read_b128 v[66:69], v175 offset:2048
	ds_read_b128 v[70:73], v175 offset:3072
	ds_read_b128 v[146:149], v176
	ds_read_b128 v[150:153], v176 offset:1024
	ds_read_b128 v[164:167], v176 offset:2048
	ds_read_b128 v[168:171], v176 offset:3072
	s_add_u32 s34, s34, 0x80000
	s_addc_u32 s35, s35, 0
	s_mov_b32 m0, s45
	ds_read_b128 v[178:181], v174 offset:32768
	ds_read_b128 v[182:185], v174 offset:33792
	ds_read_b128 v[186:189], v174 offset:34816
	ds_read_b128 v[190:193], v174 offset:35840
	ds_read_b128 v[194:197], v174 offset:36864
	ds_read_b128 v[198:201], v174 offset:37888
	ds_read_b128 v[202:205], v174 offset:38912
	ds_read_b128 v[206:209], v174 offset:39936
	s_cmp_lg_u32 s100, 0
	s_cbranch_scc1 .Ltl_ic_1s
	global_load_lds_dwordx4 v154, s[34:35]
	s_mov_b32 m0, s46
	s_nop 0
	global_load_lds_dwordx4 v156, s[34:35]
	s_waitcnt vmcnt(8)
	s_branch .Ltl_ic_1d

; #define PG8_STAGE(bufoff, gbase, voff) do { _Pragma("unroll") for (int _i = 0; _i < 2; ++_i) \
;         __builtin_amdgcn_global_load_lds((const unsigned*)((const char*)(gbase) + (voff)[_i]), (LAS unsigned*)(lds + (bufoff) + ldsw + _i * 8192), 16, 0, 0); } while (0)
; #define PG8_LDA(dst, b, h) do { _Pragma("unroll") for (int m = 0; m < NM; ++m) _Pragma("unroll") for (int k = 0; k < 2; ++k) dst[m][k] = *(const LAS bf16x8*)(lds + PG8_SA(b, h) + aoff + m * 2048 + k * 1024); } while (0)
; #define PG8_MMA(ai, bj, At, Bt) do { __builtin_amdgcn_s_setprio(1); _Pragma("unroll") for (int m = 0; m < NM; ++m) _Pragma("unroll") for (int n = 0; n < 2; ++n) _Pragma("unroll") for (int k = 0; k < 2; ++k) \
;         acc[ai][bj][m][n] = __builtin_amdgcn_mfma_f32_16x16x32_bf16(Bt[n][k], At[m][k], acc[ai][bj][m][n], 0, 0, 0); __builtin_amdgcn_s_setprio(0); } while (0)
; #define PG8_WAIT_V(n) asm volatile("s_waitcnt vmcnt(" #n ")" ::: "memory")
; #define PG8_WAIT_L(n) asm volatile("s_waitcnt lgkmcnt(" #n ")" ::: "memory")
; #define PG8_BAR __builtin_amdgcn_s_barrier()
; #define PG8_SCHED __builtin_amdgcn_sched_barrier(0)
;     ...
;             PG8_WAIT_V(8); PG8_WAIT_L(0); PG8_BAR; PG8_MMA(0, 0, At, B0); PG8_MMA(0, 1, At, B1); PG8_BAR; PG8_SCHED;
;             PG8_LDA(At, 1, 1); PG8_STAGE(PG8_SB(1, 0), b3, voffB); PG8_STAGE(PG8_SB(1, 1), b3 + hstepB, voffB); PG8_STAGE(PG8_SA(1, 0), a3, voffA);
.Ltl_ic_1d:
	s_waitcnt lgkmcnt(0)
	s_setprio 1
	s_barrier
	v_mfma_f32_16x16x32_bf16 v[142:145], v[50:53], v[178:181], v[142:145]
	v_mfma_f32_16x16x32_bf16 v[138:141], v[66:69], v[178:181], v[138:141]
	v_mfma_f32_16x16x32_bf16 v[126:129], v[50:53], v[186:189], v[126:129]
	v_mfma_f32_16x16x32_bf16 v[122:125], v[66:69], v[186:189], v[122:125]
	v_mfma_f32_16x16x32_bf16 v[110:113], v[50:53], v[194:197], v[110:113]
	v_mfma_f32_16x16x32_bf16 v[106:109], v[66:69], v[194:197], v[106:109]
	v_mfma_f32_16x16x32_bf16 v[94:97], v[50:53], v[202:205], v[94:97]
	v_mfma_f32_16x16x32_bf16 v[90:93], v[66:69], v[202:205], v[90:93]
	v_mfma_f32_16x16x32_bf16 v[142:145], v[54:57], v[182:185], v[142:145]
	v_mfma_f32_16x16x32_bf16 v[138:141], v[70:73], v[182:185], v[138:141]
	v_mfma_f32_16x16x32_bf16 v[126:129], v[54:57], v[190:193], v[126:129]
	v_mfma_f32_16x16x32_bf16 v[122:125], v[70:73], v[190:193], v[122:125]
	v_mfma_f32_16x16x32_bf16 v[110:113], v[54:57], v[198:201], v[110:113]
	v_mfma_f32_16x16x32_bf16 v[106:109], v[70:73], v[198:201], v[106:109]
	v_mfma_f32_16x16x32_bf16 v[94:97], v[54:57], v[206:209], v[94:97]
	v_mfma_f32_16x16x32_bf16 v[90:93], v[70:73], v[206:209], v[90:93]
	s_setprio 0
	s_setprio 1
	v_mfma_f32_16x16x32_bf16 v[134:137], v[146:149], v[178:181], v[134:137]
	v_mfma_f32_16x16x32_bf16 v[130:133], v[164:167], v[178:181], v[130:133]
	v_mfma_f32_16x16x32_bf16 v[118:121], v[146:149], v[186:189], v[118:121]
	v_mfma_f32_16x16x32_bf16 v[114:117], v[164:167], v[186:189], v[114:117]
	v_mfma_f32_16x16x32_bf16 v[102:105], v[146:149], v[194:197], v[102:105]
	v_mfma_f32_16x16x32_bf16 v[98:101], v[164:167], v[194:197], v[98:101]
	v_mfma_f32_16x16x32_bf16 v[86:89], v[146:149], v[202:205], v[86:89]
	v_mfma_f32_16x16x32_bf16 v[82:85], v[164:167], v[202:205], v[82:85]
	v_mfma_f32_16x16x32_bf16 v[134:137], v[150:153], v[182:185], v[134:137]
	v_mfma_f32_16x16x32_bf16 v[130:133], v[168:171], v[182:185], v[130:133]
	v_mfma_f32_16x16x32_bf16 v[118:121], v[150:153], v[190:193], v[118:121]
	v_mfma_f32_16x16x32_bf16 v[114:117], v[168:171], v[190:193], v[114:117]
	v_mfma_f32_16x16x32_bf16 v[102:105], v[150:153], v[198:201], v[102:105]
	v_mfma_f32_16x16x32_bf16 v[98:101], v[168:171], v[198:201], v[98:101]
	v_mfma_f32_16x16x32_bf16 v[86:89], v[150:153], v[206:209], v[86:89]
	v_mfma_f32_16x16x32_bf16 v[82:85], v[168:171], v[206:209], v[82:85]
	s_barrier
	s_setprio 0
	s_mov_b32 m0, s49
	v_lshl_add_u64 v[210:211], v[210:211], 0, s[66:67]
	s_add_u32 s30, s30, 0x80080
	s_addc_u32 s31, s31, 0
	ds_read_b128 v[178:181], v174 offset:49152
	ds_read_b128 v[182:185], v174 offset:50176
	ds_read_b128 v[186:189], v174 offset:51200
	ds_read_b128 v[190:193], v174 offset:52224
	ds_read_b128 v[194:197], v174 offset:53248
	ds_read_b128 v[198:201], v174 offset:54272
	ds_read_b128 v[202:205], v174 offset:55296
	ds_read_b128 v[206:209], v174 offset:56320
	s_cmp_lg_u32 s100, 0
	s_cbranch_scc1 .Ltl_ic_2s
	global_load_lds_dwordx4 v[210:211], off
	v_lshl_add_u64 v[210:211], v[212:213], 0, s[66:67]
	s_mov_b32 m0, s50
	s_nop 0
	global_load_lds_dwordx4 v[210:211], off
	s_mov_b32 m0, s58
	s_nop 0
	global_load_lds_dwordx4 v0, s[30:31]
	s_mov_b32 m0, s59
	s_nop 0
	global_load_lds_dwordx4 v158, s[30:31]
	v_lshl_add_u64 v[210:211], v[214:215], 0, s[66:67]
	s_mov_b32 m0, s51
	s_nop 0
	global_load_lds_dwordx4 v[210:211], off
	v_lshl_add_u64 v[210:211], v[216:217], 0, s[66:67]
	s_mov_b32 m0, s52
	s_nop 0
	global_load_lds_dwordx4 v[210:211], off
	s_waitcnt vmcnt(8)
	s_branch .Ltl_ic_2d

; #define PG8_STAGE(bufoff, gbase, voff) do { _Pragma("unroll") for (int _i = 0; _i < 2; ++_i) \
;         __builtin_amdgcn_global_load_lds((const unsigned*)((const char*)(gbase) + (voff)[_i]), (LAS unsigned*)(lds + (bufoff) + ldsw + _i * 8192), 16, 0, 0); } while (0)
; #define PG8_LDA(dst, b, h) do { _Pragma("unroll") for (int m = 0; m < NM; ++m) _Pragma("unroll") for (int k = 0; k < 2; ++k) dst[m][k] = *(const LAS bf16x8*)(lds + PG8_SA(b, h) + aoff + m * 2048 + k * 1024); } while (0)
; #define PG8_MMA(ai, bj, At, Bt) do { __builtin_amdgcn_s_setprio(1); _Pragma("unroll") for (int m = 0; m < NM; ++m) _Pragma("unroll") for (int n = 0; n < 2; ++n) _Pragma("unroll") for (int k = 0; k < 2; ++k) \
;         acc[ai][bj][m][n] = __builtin_amdgcn_mfma_f32_16x16x32_bf16(Bt[n][k], At[m][k], acc[ai][bj][m][n], 0, 0, 0); __builtin_amdgcn_s_setprio(0); } while (0)
; #define PG8_WAIT_V(n) asm volatile("s_waitcnt vmcnt(" #n ")" ::: "memory")
; #define PG8_WAIT_L(n) asm volatile("s_waitcnt lgkmcnt(" #n ")" ::: "memory")
; #define PG8_BAR __builtin_amdgcn_s_barrier()
; #define PG8_SCHED __builtin_amdgcn_sched_barrier(0)
;     ...
;             PG8_WAIT_V(8); PG8_WAIT_L(0); PG8_BAR; PG8_MMA(0, 0, At, B0); PG8_MMA(0, 1, At, B1); PG8_BAR; PG8_SCHED;
;             PG8_LDA(At, 1, 1); PG8_STAGE(PG8_SB(1, 0), b3, voffB); PG8_STAGE(PG8_SB(1, 1), b3 + hstepB, voffB); PG8_STAGE(PG8_SA(1, 0), a3, voffA);
;             PG8_WAIT_V(8); PG8_WAIT_L(0); PG8_BAR; PG8_MMA(1, 0, At, B0); PG8_MMA(1, 1, At, B1); PG8_BAR; PG8_SCHED;
.Ltl_ic_2d:
	s_waitcnt lgkmcnt(0)
	s_setprio 1
	s_barrier
	v_mfma_f32_16x16x32_bf16 v[78:81], v[50:53], v[178:181], v[78:81]
	v_mfma_f32_16x16x32_bf16 v[74:77], v[66:69], v[178:181], v[74:77]
	v_mfma_f32_16x16x32_bf16 v[62:65], v[50:53], v[186:189], v[62:65]
	v_mfma_f32_16x16x32_bf16 v[58:61], v[66:69], v[186:189], v[58:61]
	v_mfma_f32_16x16x32_bf16 v[38:41], v[50:53], v[194:197], v[38:41]
	v_mfma_f32_16x16x32_bf16 v[34:37], v[66:69], v[194:197], v[34:37]
	v_mfma_f32_16x16x32_bf16 v[14:17], v[50:53], v[202:205], v[14:17]
	v_mfma_f32_16x16x32_bf16 v[10:13], v[66:69], v[202:205], v[10:13]
	v_mfma_f32_16x16x32_bf16 v[78:81], v[54:57], v[182:185], v[78:81]
	v_mfma_f32_16x16x32_bf16 v[74:77], v[70:73], v[182:185], v[74:77]
	v_mfma_f32_16x16x32_bf16 v[62:65], v[54:57], v[190:193], v[62:65]
	v_mfma_f32_16x16x32_bf16 v[58:61], v[70:73], v[190:193], v[58:61]
	v_mfma_f32_16x16x32_bf16 v[38:41], v[54:57], v[198:201], v[38:41]
	v_mfma_f32_16x16x32_bf16 v[34:37], v[70:73], v[198:201], v[34:37]
	v_mfma_f32_16x16x32_bf16 v[14:17], v[54:57], v[206:209], v[14:17]
	v_mfma_f32_16x16x32_bf16 v[10:13], v[70:73], v[206:209], v[10:13]
	s_setprio 0
	s_setprio 1
	v_mfma_f32_16x16x32_bf16 v[26:29], v[146:149], v[178:181], v[26:29]
	v_mfma_f32_16x16x32_bf16 v[70:73], v[150:153], v[182:185], v[26:29]
	v_mfma_f32_16x16x32_bf16 v[26:29], v[164:167], v[178:181], v[30:33]
	v_mfma_f32_16x16x32_bf16 v[66:69], v[168:171], v[182:185], v[26:29]
	v_mfma_f32_16x16x32_bf16 v[26:29], v[146:149], v[186:189], v[42:45]
	v_mfma_f32_16x16x32_bf16 v[54:57], v[150:153], v[190:193], v[26:29]
	v_mfma_f32_16x16x32_bf16 v[26:29], v[164:167], v[186:189], v[46:49]
	v_mfma_f32_16x16x32_bf16 v[22:25], v[146:149], v[194:197], v[22:25]
	v_mfma_f32_16x16x32_bf16 v[18:21], v[164:167], v[194:197], v[18:21]
	v_mfma_f32_16x16x32_bf16 v[6:9], v[146:149], v[202:205], v[6:9]
	v_mfma_f32_16x16x32_bf16 v[2:5], v[164:167], v[202:205], v[2:5]
	v_mfma_f32_16x16x32_bf16 v[50:53], v[168:171], v[190:193], v[26:29]
	v_mfma_f32_16x16x32_bf16 v[22:25], v[150:153], v[198:201], v[22:25]
	v_mfma_f32_16x16x32_bf16 v[18:21], v[168:171], v[198:201], v[18:21]
	v_mfma_f32_16x16x32_bf16 v[6:9], v[150:153], v[206:209], v[6:9]
	v_mfma_f32_16x16x32_bf16 v[2:5], v[168:171], v[206:209], v[2:5]
	s_barrier
	s_setprio 0
	s_add_i32 s56, s56, 2
	s_add_u32 s28, s28, 0x100
	s_addc_u32 s29, s29, 0
	s_add_u32 s23, s23, 0x100
	s_addc_u32 s54, s54, 0
	s_cmp_gt_u32 s56, 29
	s_cbranch_scc0 .LBB0_200
	s_and_b64 vcc, exec, s[14:15]
	s_cbranch_vccz .LBB0_203
	s_barrier

; #define PG8_STAGE(bufoff, gbase, voff) do { _Pragma("unroll") for (int _i = 0; _i < 2; ++_i) \
;         __builtin_amdgcn_global_load_lds((const unsigned*)((const char*)(gbase) + (voff)[_i]), (LAS unsigned*)(lds + (bufoff) + ldsw + _i * 8192), 16, 0, 0); } while (0)
; #define PG8_LDA(dst, b, h) do { _Pragma("unroll") for (int m = 0; m < NM; ++m) _Pragma("unroll") for (int k = 0; k < 2; ++k) dst[m][k] = *(const LAS bf16x8*)(lds + PG8_SA(b, h) + aoff + m * 2048 + k * 1024); } while (0)
; #define PG8_LDB(dst, b, h) do { _Pragma("unroll") for (int n = 0; n < 2; ++n) _Pragma("unroll") for (int k = 0; k < 2; ++k) dst[n][k] = *(const LAS bf16x8*)(lds + PG8_SB(b, h) + boff + n * 2048 + k * 1024); } while (0)
; #define PG8_MMA(ai, bj, At, Bt) do { __builtin_amdgcn_s_setprio(1); _Pragma("unroll") for (int m = 0; m < NM; ++m) _Pragma("unroll") for (int n = 0; n < 2; ++n) _Pragma("unroll") for (int k = 0; k < 2; ++k) \
;         acc[ai][bj][m][n] = __builtin_amdgcn_mfma_f32_16x16x32_bf16(Bt[n][k], At[m][k], acc[ai][bj][m][n], 0, 0, 0); __builtin_amdgcn_s_setprio(0); } while (0)
; #define PG8_WAIT_V(n) asm volatile("s_waitcnt vmcnt(" #n ")" ::: "memory")
; #define PG8_WAIT_L(n) asm volatile("s_waitcnt lgkmcnt(" #n ")" ::: "memory")
; #define PG8_BAR __builtin_amdgcn_s_barrier()
; #define PG8_SCHED __builtin_amdgcn_sched_barrier(0)
;     ...
;             PG8_LDB(B0, 0, 0); PG8_LDB(B1, 0, 1); PG8_SCHED; PG8_LDA(At, 0, 0); PG8_STAGE(PG8_SA(1, 1), a1 + hstepA, voffA);
;             PG8_WAIT_V(8); PG8_WAIT_L(0); PG8_BAR; PG8_MMA(0, 0, At, B0); PG8_MMA(0, 1, At, B1); PG8_BAR; PG8_SCHED;
;             PG8_LDA(At, 0, 1); PG8_STAGE(PG8_SB(0, 0), b2, voffB); PG8_STAGE(PG8_SB(0, 1), b2 + hstepB, voffB); PG8_STAGE(PG8_SA(0, 0), a2, voffA);
.LBB0_703:
	v_add_u32_e32 v0, s50, v146
	ds_read_b128 v[138:141], v0
	ds_read_b128 v[142:145], v0 offset:1024
	ds_read_b128 v[148:151], v0 offset:2048
	ds_read_b128 v[152:155], v0 offset:3072
	v_add_u32_e32 v0, s54, v146
	ds_read_b128 v[156:159], v0
	ds_read_b128 v[160:163], v0 offset:1024
	ds_read_b128 v[164:167], v0 offset:2048
	ds_read_b128 v[168:171], v0 offset:3072
	s_add_u32 s12, s10, 0xfff80080
	s_addc_u32 s13, s11, -1
	s_cmp_eq_u32 s39, 28
	s_cselect_b32 s37, s2, s13
	s_cselect_b32 s36, s3, s12
	s_cselect_b32 s13, s9, s38
	s_cselect_b32 s12, s27, s29
	s_cselect_b32 s100, -1, 0
	s_andn2_b32 s100, s100, s101
	s_add_i32 m0, s58, 0xc000
	ds_read_b128 v[172:175], v147
	ds_read_b128 v[176:179], v147 offset:1024
	ds_read_b128 v[180:183], v147 offset:2048
	ds_read_b128 v[184:187], v147 offset:3072
	ds_read_b128 v[188:191], v147 offset:4096
	ds_read_b128 v[192:195], v147 offset:5120
	ds_read_b128 v[196:199], v147 offset:6144
	ds_read_b128 v[200:203], v147 offset:7168
	global_load_lds_dwordx4 v134, s[10:11]
	s_add_i32 m0, s58, 0xe000
	s_nop 0
	global_load_lds_dwordx4 v136, s[10:11]
	s_waitcnt vmcnt(8)
	s_waitcnt lgkmcnt(0)
	s_setprio 1
	s_barrier
	v_mfma_f32_16x16x32_bf16 v[126:129], v[138:141], v[172:175], v[126:129]
	v_mfma_f32_16x16x32_bf16 v[122:125], v[148:151], v[172:175], v[122:125]
	v_mfma_f32_16x16x32_bf16 v[110:113], v[138:141], v[180:183], v[110:113]
	v_mfma_f32_16x16x32_bf16 v[106:109], v[148:151], v[180:183], v[106:109]
	v_mfma_f32_16x16x32_bf16 v[94:97], v[138:141], v[188:191], v[94:97]
	v_mfma_f32_16x16x32_bf16 v[90:93], v[148:151], v[188:191], v[90:93]
	v_mfma_f32_16x16x32_bf16 v[78:81], v[138:141], v[196:199], v[78:81]
	v_mfma_f32_16x16x32_bf16 v[74:77], v[148:151], v[196:199], v[74:77]
	v_mfma_f32_16x16x32_bf16 v[126:129], v[142:145], v[176:179], v[126:129]
	v_mfma_f32_16x16x32_bf16 v[122:125], v[152:155], v[176:179], v[122:125]
	v_mfma_f32_16x16x32_bf16 v[110:113], v[142:145], v[184:187], v[110:113]
	v_mfma_f32_16x16x32_bf16 v[106:109], v[152:155], v[184:187], v[106:109]
	v_mfma_f32_16x16x32_bf16 v[94:97], v[142:145], v[192:195], v[94:97]
	v_mfma_f32_16x16x32_bf16 v[90:93], v[152:155], v[192:195], v[90:93]
	v_mfma_f32_16x16x32_bf16 v[78:81], v[142:145], v[200:203], v[78:81]
	v_mfma_f32_16x16x32_bf16 v[74:77], v[152:155], v[200:203], v[74:77]
	s_setprio 0
	s_setprio 1
	v_mfma_f32_16x16x32_bf16 v[118:121], v[156:159], v[172:175], v[118:121]
	v_mfma_f32_16x16x32_bf16 v[114:117], v[164:167], v[172:175], v[114:117]
	v_mfma_f32_16x16x32_bf16 v[102:105], v[156:159], v[180:183], v[102:105]
	v_mfma_f32_16x16x32_bf16 v[98:101], v[164:167], v[180:183], v[98:101]
	v_mfma_f32_16x16x32_bf16 v[86:89], v[156:159], v[188:191], v[86:89]
	v_mfma_f32_16x16x32_bf16 v[82:85], v[164:167], v[188:191], v[82:85]
	v_mfma_f32_16x16x32_bf16 v[70:73], v[156:159], v[196:199], v[70:73]
	v_mfma_f32_16x16x32_bf16 v[66:69], v[164:167], v[196:199], v[66:69]
	v_mfma_f32_16x16x32_bf16 v[118:121], v[160:163], v[176:179], v[118:121]
	v_mfma_f32_16x16x32_bf16 v[114:117], v[168:171], v[176:179], v[114:117]
	v_mfma_f32_16x16x32_bf16 v[102:105], v[160:163], v[184:187], v[102:105]
	v_mfma_f32_16x16x32_bf16 v[98:101], v[168:171], v[184:187], v[98:101]
	v_mfma_f32_16x16x32_bf16 v[86:89], v[160:163], v[192:195], v[86:89]
	v_mfma_f32_16x16x32_bf16 v[82:85], v[168:171], v[192:195], v[82:85]
	v_mfma_f32_16x16x32_bf16 v[70:73], v[160:163], v[200:203], v[70:73]
	v_mfma_f32_16x16x32_bf16 v[66:69], v[168:171], v[200:203], v[66:69]
	s_barrier
	s_setprio 0
	s_mov_b32 m0, s51
	v_lshl_add_u64 v[204:205], s[12:13], 0, v[130:131]
	s_add_u32 s40, s12, 0x80000
	s_addc_u32 s41, s13, 0
	ds_read_b128 v[172:175], v147 offset:16384
	ds_read_b128 v[176:179], v147 offset:17408
	ds_read_b128 v[180:183], v147 offset:18432
	ds_read_b128 v[184:187], v147 offset:19456
	ds_read_b128 v[188:191], v147 offset:20480
	ds_read_b128 v[192:195], v147 offset:21504
	ds_read_b128 v[196:199], v147 offset:22528
	ds_read_b128 v[200:203], v147 offset:23552
	s_cmp_lg_u32 s100, 0
	s_cbranch_scc1 .Ltl_ia_0s
	global_load_lds_dwordx4 v130, s[12:13]
	v_lshl_add_u64 v[206:207], s[12:13], 0, v[132:133]
	s_mov_b32 m0, s52
	s_nop 0
	global_load_lds_dwordx4 v132, s[12:13]
	s_mov_b32 m0, s56
	v_lshl_add_u64 v[210:211], s[36:37], 0, v[132:133]
	global_load_lds_dwordx4 v130, s[40:41]
	s_mov_b32 m0, s57
	s_nop 0
	global_load_lds_dwordx4 v132, s[40:41]
	v_lshl_add_u64 v[208:209], s[36:37], 0, v[130:131]
	s_mov_b32 m0, s58
	s_nop 0
	global_load_lds_dwordx4 v130, s[36:37]
	s_mov_b32 m0, s59
	s_nop 0
	global_load_lds_dwordx4 v132, s[36:37]
	s_waitcnt vmcnt(8)
	s_branch .Ltl_ia_0d

; #define PG8_STAGE(bufoff, gbase, voff) do { _Pragma("unroll") for (int _i = 0; _i < 2; ++_i) \
;         __builtin_amdgcn_global_load_lds((const unsigned*)((const char*)(gbase) + (voff)[_i]), (LAS unsigned*)(lds + (bufoff) + ldsw + _i * 8192), 16, 0, 0); } while (0)
; #define PG8_LDA(dst, b, h) do { _Pragma("unroll") for (int m = 0; m < NM; ++m) _Pragma("unroll") for (int k = 0; k < 2; ++k) dst[m][k] = *(const LAS bf16x8*)(lds + PG8_SA(b, h) + aoff + m * 2048 + k * 1024); } while (0)
; #define PG8_LDB(dst, b, h) do { _Pragma("unroll") for (int n = 0; n < 2; ++n) _Pragma("unroll") for (int k = 0; k < 2; ++k) dst[n][k] = *(const LAS bf16x8*)(lds + PG8_SB(b, h) + boff + n * 2048 + k * 1024); } while (0)
; #define PG8_MMA(ai, bj, At, Bt) do { __builtin_amdgcn_s_setprio(1); _Pragma("unroll") for (int m = 0; m < NM; ++m) _Pragma("unroll") for (int n = 0; n < 2; ++n) _Pragma("unroll") for (int k = 0; k < 2; ++k) \
;         acc[ai][bj][m][n] = __builtin_amdgcn_mfma_f32_16x16x32_bf16(Bt[n][k], At[m][k], acc[ai][bj][m][n], 0, 0, 0); __builtin_amdgcn_s_setprio(0); } while (0)
; #define PG8_WAIT_V(n) asm volatile("s_waitcnt vmcnt(" #n ")" ::: "memory")
; #define PG8_WAIT_L(n) asm volatile("s_waitcnt lgkmcnt(" #n ")" ::: "memory")
; #define PG8_BAR __builtin_amdgcn_s_barrier()
; #define PG8_SCHED __builtin_amdgcn_sched_barrier(0)
;     ...
;             PG8_WAIT_V(8); PG8_WAIT_L(0); PG8_BAR; PG8_MMA(1, 0, At, B0); PG8_MMA(1, 1, At, B1); PG8_BAR; PG8_SCHED;
;             PG8_LDB(B0, 1, 0); PG8_LDB(B1, 1, 1); PG8_SCHED; PG8_LDA(At, 1, 0); PG8_STAGE(PG8_SA(0, 1), a2 + hstepA, voffA);
.Ltl_ia_0d:
	s_waitcnt lgkmcnt(0)
	s_setprio 1
	s_barrier
	v_mfma_f32_16x16x32_bf16 v[62:65], v[138:141], v[172:175], v[62:65]
	v_mfma_f32_16x16x32_bf16 v[58:61], v[148:151], v[172:175], v[58:61]
	v_mfma_f32_16x16x32_bf16 v[46:49], v[138:141], v[180:183], v[46:49]
	v_mfma_f32_16x16x32_bf16 v[42:45], v[148:151], v[180:183], v[42:45]
	v_mfma_f32_16x16x32_bf16 v[30:33], v[138:141], v[188:191], v[30:33]
	v_mfma_f32_16x16x32_bf16 v[26:29], v[148:151], v[188:191], v[26:29]
	v_mfma_f32_16x16x32_bf16 v[14:17], v[138:141], v[196:199], v[14:17]
	v_mfma_f32_16x16x32_bf16 v[10:13], v[148:151], v[196:199], v[10:13]
	v_mfma_f32_16x16x32_bf16 v[62:65], v[142:145], v[176:179], v[62:65]
	v_mfma_f32_16x16x32_bf16 v[58:61], v[152:155], v[176:179], v[58:61]
	v_mfma_f32_16x16x32_bf16 v[46:49], v[142:145], v[184:187], v[46:49]
	v_mfma_f32_16x16x32_bf16 v[42:45], v[152:155], v[184:187], v[42:45]
	v_mfma_f32_16x16x32_bf16 v[30:33], v[142:145], v[192:195], v[30:33]
	v_mfma_f32_16x16x32_bf16 v[26:29], v[152:155], v[192:195], v[26:29]
	v_mfma_f32_16x16x32_bf16 v[14:17], v[142:145], v[200:203], v[14:17]
	v_mfma_f32_16x16x32_bf16 v[10:13], v[152:155], v[200:203], v[10:13]
	s_setprio 0
	s_setprio 1
	v_mfma_f32_16x16x32_bf16 v[54:57], v[156:159], v[172:175], v[54:57]
	v_mfma_f32_16x16x32_bf16 v[50:53], v[164:167], v[172:175], v[50:53]
	v_mfma_f32_16x16x32_bf16 v[38:41], v[156:159], v[180:183], v[38:41]
	v_mfma_f32_16x16x32_bf16 v[34:37], v[164:167], v[180:183], v[34:37]
	v_mfma_f32_16x16x32_bf16 v[22:25], v[156:159], v[188:191], v[22:25]
	v_mfma_f32_16x16x32_bf16 v[18:21], v[164:167], v[188:191], v[18:21]
	v_mfma_f32_16x16x32_bf16 v[6:9], v[156:159], v[196:199], v[6:9]
	v_mfma_f32_16x16x32_bf16 v[2:5], v[164:167], v[196:199], v[2:5]
	v_mfma_f32_16x16x32_bf16 v[54:57], v[160:163], v[176:179], v[54:57]
	v_mfma_f32_16x16x32_bf16 v[50:53], v[168:171], v[176:179], v[50:53]
	v_mfma_f32_16x16x32_bf16 v[38:41], v[160:163], v[184:187], v[38:41]
	v_mfma_f32_16x16x32_bf16 v[34:37], v[168:171], v[184:187], v[34:37]
	v_mfma_f32_16x16x32_bf16 v[22:25], v[160:163], v[192:195], v[22:25]
	v_mfma_f32_16x16x32_bf16 v[18:21], v[168:171], v[192:195], v[18:21]
	v_mfma_f32_16x16x32_bf16 v[6:9], v[160:163], v[200:203], v[6:9]
	v_mfma_f32_16x16x32_bf16 v[2:5], v[168:171], v[200:203], v[2:5]
	s_barrier
	s_setprio 0
	v_add_u32_e32 v0, s64, v146
	ds_read_b128 v[138:141], v0
	ds_read_b128 v[142:145], v0 offset:1024
	ds_read_b128 v[148:151], v0 offset:2048
	ds_read_b128 v[152:155], v0 offset:3072
	v_add_u32_e32 v0, s71, v146
	ds_read_b128 v[156:159], v0
	ds_read_b128 v[160:163], v0 offset:1024
	ds_read_b128 v[164:167], v0 offset:2048
	ds_read_b128 v[168:171], v0 offset:3072
	s_add_u32 s36, s36, 0x80000
	s_addc_u32 s37, s37, 0
	s_mov_b32 m0, s62
	ds_read_b128 v[172:175], v147 offset:32768
	ds_read_b128 v[176:179], v147 offset:33792
	ds_read_b128 v[180:183], v147 offset:34816
	ds_read_b128 v[184:187], v147 offset:35840
	ds_read_b128 v[188:191], v147 offset:36864
	ds_read_b128 v[192:195], v147 offset:37888
	ds_read_b128 v[196:199], v147 offset:38912
	ds_read_b128 v[200:203], v147 offset:39936
	s_cmp_lg_u32 s100, 0
	s_cbranch_scc1 .Ltl_ia_1s
	global_load_lds_dwordx4 v130, s[36:37]
	s_mov_b32 m0, s63
	s_nop 0
	global_load_lds_dwordx4 v132, s[36:37]
	s_waitcnt vmcnt(8)
	s_branch .Ltl_ia_1d

; #define PG8_STAGE(bufoff, gbase, voff) do { _Pragma("unroll") for (int _i = 0; _i < 2; ++_i) \
;         __builtin_amdgcn_global_load_lds((const unsigned*)((const char*)(gbase) + (voff)[_i]), (LAS unsigned*)(lds + (bufoff) + ldsw + _i * 8192), 16, 0, 0); } while (0)
; #define PG8_LDA(dst, b, h) do { _Pragma("unroll") for (int m = 0; m < NM; ++m) _Pragma("unroll") for (int k = 0; k < 2; ++k) dst[m][k] = *(const LAS bf16x8*)(lds + PG8_SA(b, h) + aoff + m * 2048 + k * 1024); } while (0)
; #define PG8_MMA(ai, bj, At, Bt) do { __builtin_amdgcn_s_setprio(1); _Pragma("unroll") for (int m = 0; m < NM; ++m) _Pragma("unroll") for (int n = 0; n < 2; ++n) _Pragma("unroll") for (int k = 0; k < 2; ++k) \
;         acc[ai][bj][m][n] = __builtin_amdgcn_mfma_f32_16x16x32_bf16(Bt[n][k], At[m][k], acc[ai][bj][m][n], 0, 0, 0); __builtin_amdgcn_s_setprio(0); } while (0)
; #define PG8_WAIT_V(n) asm volatile("s_waitcnt vmcnt(" #n ")" ::: "memory")
; #define PG8_WAIT_L(n) asm volatile("s_waitcnt lgkmcnt(" #n ")" ::: "memory")
; #define PG8_BAR __builtin_amdgcn_s_barrier()
; #define PG8_SCHED __builtin_amdgcn_sched_barrier(0)
;     ...
;             PG8_WAIT_V(8); PG8_WAIT_L(0); PG8_BAR; PG8_MMA(0, 0, At, B0); PG8_MMA(0, 1, At, B1); PG8_BAR; PG8_SCHED;
;             PG8_LDA(At, 1, 1); PG8_STAGE(PG8_SB(1, 0), b3, voffB); PG8_STAGE(PG8_SB(1, 1), b3 + hstepB, voffB); PG8_STAGE(PG8_SA(1, 0), a3, voffA);
.Ltl_ia_1d:
	s_waitcnt lgkmcnt(0)
	s_setprio 1
	s_barrier
	v_mfma_f32_16x16x32_bf16 v[126:129], v[138:141], v[172:175], v[126:129]
	v_mfma_f32_16x16x32_bf16 v[122:125], v[148:151], v[172:175], v[122:125]
	v_mfma_f32_16x16x32_bf16 v[110:113], v[138:141], v[180:183], v[110:113]
	v_mfma_f32_16x16x32_bf16 v[106:109], v[148:151], v[180:183], v[106:109]
	v_mfma_f32_16x16x32_bf16 v[94:97], v[138:141], v[188:191], v[94:97]
	v_mfma_f32_16x16x32_bf16 v[90:93], v[148:151], v[188:191], v[90:93]
	v_mfma_f32_16x16x32_bf16 v[78:81], v[138:141], v[196:199], v[78:81]
	v_mfma_f32_16x16x32_bf16 v[74:77], v[148:151], v[196:199], v[74:77]
	v_mfma_f32_16x16x32_bf16 v[126:129], v[142:145], v[176:179], v[126:129]
	v_mfma_f32_16x16x32_bf16 v[122:125], v[152:155], v[176:179], v[122:125]
	v_mfma_f32_16x16x32_bf16 v[110:113], v[142:145], v[184:187], v[110:113]
	v_mfma_f32_16x16x32_bf16 v[106:109], v[152:155], v[184:187], v[106:109]
	v_mfma_f32_16x16x32_bf16 v[94:97], v[142:145], v[192:195], v[94:97]
	v_mfma_f32_16x16x32_bf16 v[90:93], v[152:155], v[192:195], v[90:93]
	v_mfma_f32_16x16x32_bf16 v[78:81], v[142:145], v[200:203], v[78:81]
	v_mfma_f32_16x16x32_bf16 v[74:77], v[152:155], v[200:203], v[74:77]
	s_setprio 0
	s_setprio 1
	v_mfma_f32_16x16x32_bf16 v[118:121], v[156:159], v[172:175], v[118:121]
	v_mfma_f32_16x16x32_bf16 v[114:117], v[164:167], v[172:175], v[114:117]
	v_mfma_f32_16x16x32_bf16 v[102:105], v[156:159], v[180:183], v[102:105]
	v_mfma_f32_16x16x32_bf16 v[98:101], v[164:167], v[180:183], v[98:101]
	v_mfma_f32_16x16x32_bf16 v[86:89], v[156:159], v[188:191], v[86:89]
	v_mfma_f32_16x16x32_bf16 v[82:85], v[164:167], v[188:191], v[82:85]
	v_mfma_f32_16x16x32_bf16 v[70:73], v[156:159], v[196:199], v[70:73]
	v_mfma_f32_16x16x32_bf16 v[66:69], v[164:167], v[196:199], v[66:69]
	v_mfma_f32_16x16x32_bf16 v[118:121], v[160:163], v[176:179], v[118:121]
	v_mfma_f32_16x16x32_bf16 v[114:117], v[168:171], v[176:179], v[114:117]
	v_mfma_f32_16x16x32_bf16 v[102:105], v[160:163], v[184:187], v[102:105]
	v_mfma_f32_16x16x32_bf16 v[98:101], v[168:171], v[184:187], v[98:101]
	v_mfma_f32_16x16x32_bf16 v[86:89], v[160:163], v[192:195], v[86:89]
	v_mfma_f32_16x16x32_bf16 v[82:85], v[168:171], v[192:195], v[82:85]
	v_mfma_f32_16x16x32_bf16 v[70:73], v[160:163], v[200:203], v[70:73]
	v_mfma_f32_16x16x32_bf16 v[66:69], v[168:171], v[200:203], v[66:69]
	s_barrier
	s_setprio 0
	s_mov_b32 m0, s65
	v_lshl_add_u64 v[204:205], v[204:205], 0, s[66:67]
	s_add_u32 s12, s12, 0x80080
	s_addc_u32 s13, s13, 0
	ds_read_b128 v[172:175], v147 offset:49152
	ds_read_b128 v[176:179], v147 offset:50176
	ds_read_b128 v[180:183], v147 offset:51200
	ds_read_b128 v[184:187], v147 offset:52224
	ds_read_b128 v[188:191], v147 offset:53248
	ds_read_b128 v[192:195], v147 offset:54272
	ds_read_b128 v[196:199], v147 offset:55296
	ds_read_b128 v[200:203], v147 offset:56320
	s_cmp_lg_u32 s100, 0
	s_cbranch_scc1 .Ltl_ia_2s
	global_load_lds_dwordx4 v[204:205], off
	v_lshl_add_u64 v[204:205], v[206:207], 0, s[66:67]
	s_mov_b32 m0, s68
	s_nop 0
	global_load_lds_dwordx4 v[204:205], off
	s_mov_b32 m0, s72
	s_nop 0
	global_load_lds_dwordx4 v130, s[12:13]
	s_mov_b32 m0, s73
	s_nop 0
	global_load_lds_dwordx4 v132, s[12:13]
	v_lshl_add_u64 v[204:205], v[208:209], 0, s[66:67]
	s_mov_b32 m0, s69
	s_nop 0
	global_load_lds_dwordx4 v[204:205], off
	v_lshl_add_u64 v[204:205], v[210:211], 0, s[66:67]
	s_mov_b32 m0, s70
	s_nop 0
	global_load_lds_dwordx4 v[204:205], off
	s_waitcnt vmcnt(8)
	s_branch .Ltl_ia_2d

; #define PG8_STAGE(bufoff, gbase, voff) do { _Pragma("unroll") for (int _i = 0; _i < 2; ++_i) \
;         __builtin_amdgcn_global_load_lds((const unsigned*)((const char*)(gbase) + (voff)[_i]), (LAS unsigned*)(lds + (bufoff) + ldsw + _i * 8192), 16, 0, 0); } while (0)
; #define PG8_LDA(dst, b, h) do { _Pragma("unroll") for (int m = 0; m < NM; ++m) _Pragma("unroll") for (int k = 0; k < 2; ++k) dst[m][k] = *(const LAS bf16x8*)(lds + PG8_SA(b, h) + aoff + m * 2048 + k * 1024); } while (0)
; #define PG8_MMA(ai, bj, At, Bt) do { __builtin_amdgcn_s_setprio(1); _Pragma("unroll") for (int m = 0; m < NM; ++m) _Pragma("unroll") for (int n = 0; n < 2; ++n) _Pragma("unroll") for (int k = 0; k < 2; ++k) \
;         acc[ai][bj][m][n] = __builtin_amdgcn_mfma_f32_16x16x32_bf16(Bt[n][k], At[m][k], acc[ai][bj][m][n], 0, 0, 0); __builtin_amdgcn_s_setprio(0); } while (0)
; #define PG8_WAIT_V(n) asm volatile("s_waitcnt vmcnt(" #n ")" ::: "memory")
; #define PG8_WAIT_L(n) asm volatile("s_waitcnt lgkmcnt(" #n ")" ::: "memory")
; #define PG8_BAR __builtin_amdgcn_s_barrier()
; #define PG8_SCHED __builtin_amdgcn_sched_barrier(0)
;     ...
;             PG8_WAIT_V(8); PG8_WAIT_L(0); PG8_BAR; PG8_MMA(0, 0, At, B0); PG8_MMA(0, 1, At, B1); PG8_BAR; PG8_SCHED;
;             PG8_LDA(At, 1, 1); PG8_STAGE(PG8_SB(1, 0), b3, voffB); PG8_STAGE(PG8_SB(1, 1), b3 + hstepB, voffB); PG8_STAGE(PG8_SA(1, 0), a3, voffA);
;             PG8_WAIT_V(8); PG8_WAIT_L(0); PG8_BAR; PG8_MMA(1, 0, At, B0); PG8_MMA(1, 1, At, B1); PG8_BAR; PG8_SCHED;
.Ltl_ia_2d:
	s_waitcnt lgkmcnt(0)
	s_setprio 1
	s_barrier
	v_mfma_f32_16x16x32_bf16 v[62:65], v[138:141], v[172:175], v[62:65]
	v_mfma_f32_16x16x32_bf16 v[58:61], v[148:151], v[172:175], v[58:61]
	v_mfma_f32_16x16x32_bf16 v[46:49], v[138:141], v[180:183], v[46:49]
	v_mfma_f32_16x16x32_bf16 v[42:45], v[148:151], v[180:183], v[42:45]
	v_mfma_f32_16x16x32_bf16 v[30:33], v[138:141], v[188:191], v[30:33]
	v_mfma_f32_16x16x32_bf16 v[26:29], v[148:151], v[188:191], v[26:29]
	v_mfma_f32_16x16x32_bf16 v[14:17], v[138:141], v[196:199], v[14:17]
	v_mfma_f32_16x16x32_bf16 v[10:13], v[148:151], v[196:199], v[10:13]
	v_mfma_f32_16x16x32_bf16 v[62:65], v[142:145], v[176:179], v[62:65]
	v_mfma_f32_16x16x32_bf16 v[58:61], v[152:155], v[176:179], v[58:61]
	v_mfma_f32_16x16x32_bf16 v[46:49], v[142:145], v[184:187], v[46:49]
	v_mfma_f32_16x16x32_bf16 v[42:45], v[152:155], v[184:187], v[42:45]
	v_mfma_f32_16x16x32_bf16 v[30:33], v[142:145], v[192:195], v[30:33]
	v_mfma_f32_16x16x32_bf16 v[26:29], v[152:155], v[192:195], v[26:29]
	v_mfma_f32_16x16x32_bf16 v[14:17], v[142:145], v[200:203], v[14:17]
	v_mfma_f32_16x16x32_bf16 v[10:13], v[152:155], v[200:203], v[10:13]
	s_setprio 0
	s_setprio 1
	v_mfma_f32_16x16x32_bf16 v[54:57], v[156:159], v[172:175], v[54:57]
	v_mfma_f32_16x16x32_bf16 v[50:53], v[164:167], v[172:175], v[50:53]
	v_mfma_f32_16x16x32_bf16 v[38:41], v[156:159], v[180:183], v[38:41]
	v_mfma_f32_16x16x32_bf16 v[34:37], v[164:167], v[180:183], v[34:37]
	v_mfma_f32_16x16x32_bf16 v[22:25], v[156:159], v[188:191], v[22:25]
	v_mfma_f32_16x16x32_bf16 v[18:21], v[164:167], v[188:191], v[18:21]
	v_mfma_f32_16x16x32_bf16 v[6:9], v[156:159], v[196:199], v[6:9]
	v_mfma_f32_16x16x32_bf16 v[2:5], v[164:167], v[196:199], v[2:5]
	v_mfma_f32_16x16x32_bf16 v[54:57], v[160:163], v[176:179], v[54:57]
	v_mfma_f32_16x16x32_bf16 v[50:53], v[168:171], v[176:179], v[50:53]
	v_mfma_f32_16x16x32_bf16 v[38:41], v[160:163], v[184:187], v[38:41]
	v_mfma_f32_16x16x32_bf16 v[34:37], v[168:171], v[184:187], v[34:37]
	v_mfma_f32_16x16x32_bf16 v[22:25], v[160:163], v[192:195], v[22:25]
	v_mfma_f32_16x16x32_bf16 v[18:21], v[168:171], v[192:195], v[18:21]
	v_mfma_f32_16x16x32_bf16 v[6:9], v[160:163], v[200:203], v[6:9]
	v_mfma_f32_16x16x32_bf16 v[2:5], v[168:171], v[200:203], v[2:5]
	s_barrier
	s_setprio 0
	s_add_i32 s39, s39, 2
	s_add_u32 s10, s10, 0x100
	s_addc_u32 s11, s11, 0
	s_add_u32 s29, s29, 0x100
	s_addc_u32 s38, s38, 0
	s_cmp_gt_u32 s39, 29
	s_cbranch_scc0 .LBB0_703
	s_and_b64 vcc, exec, s[18:19]
	s_cbranch_vccz .LBB0_706
	s_barrier

; #define PG8_STAGE(bufoff, gbase, voff) do { _Pragma("unroll") for (int _i = 0; _i < 2; ++_i) \
;         __builtin_amdgcn_global_load_lds((const unsigned*)((const char*)(gbase) + (voff)[_i]), (LAS unsigned*)(lds + (bufoff) + ldsw + _i * 8192), 16, 0, 0); } while (0)
; #define PG8_LDA(dst, b, h) do { _Pragma("unroll") for (int m = 0; m < NM; ++m) _Pragma("unroll") for (int k = 0; k < 2; ++k) dst[m][k] = *(const LAS bf16x8*)(lds + PG8_SA(b, h) + aoff + m * 2048 + k * 1024); } while (0)
; #define PG8_LDB(dst, b, h) do { _Pragma("unroll") for (int n = 0; n < 2; ++n) _Pragma("unroll") for (int k = 0; k < 2; ++k) dst[n][k] = *(const LAS bf16x8*)(lds + PG8_SB(b, h) + boff + n * 2048 + k * 1024); } while (0)
; #define PG8_MMA(ai, bj, At, Bt) do { __builtin_amdgcn_s_setprio(1); _Pragma("unroll") for (int m = 0; m < NM; ++m) _Pragma("unroll") for (int n = 0; n < 2; ++n) _Pragma("unroll") for (int k = 0; k < 2; ++k) \
;         acc[ai][bj][m][n] = __builtin_amdgcn_mfma_f32_16x16x32_bf16(Bt[n][k], At[m][k], acc[ai][bj][m][n], 0, 0, 0); __builtin_amdgcn_s_setprio(0); } while (0)
; #define PG8_WAIT_V(n) asm volatile("s_waitcnt vmcnt(" #n ")" ::: "memory")
; #define PG8_WAIT_L(n) asm volatile("s_waitcnt lgkmcnt(" #n ")" ::: "memory")
; #define PG8_BAR __builtin_amdgcn_s_barrier()
; #define PG8_SCHED __builtin_amdgcn_sched_barrier(0)
;     ...
;             PG8_LDB(B0, 0, 0); PG8_LDB(B1, 0, 1); PG8_SCHED; PG8_LDA(At, 0, 0); PG8_STAGE(PG8_SA(1, 1), a1 + hstepA, voffA);
;             PG8_WAIT_V(8); PG8_WAIT_L(0); PG8_BAR; PG8_MMA(0, 0, At, B0); PG8_MMA(0, 1, At, B1); PG8_BAR; PG8_SCHED;
;             PG8_LDA(At, 0, 1); PG8_STAGE(PG8_SB(0, 0), b2, voffB); PG8_STAGE(PG8_SB(0, 1), b2 + hstepB, voffB); PG8_STAGE(PG8_SA(0, 0), a2, voffA);
.LBB0_1192:
	v_add_u32_e32 v0, s49, v216
	ds_read_b128 v[10:13], v0
	ds_read_b128 v[14:17], v0 offset:1024
	ds_read_b128 v[18:21], v0 offset:2048
	ds_read_b128 v[22:25], v0 offset:3072
	v_add_u32_e32 v0, s58, v216
	ds_read_b128 v[26:29], v0
	ds_read_b128 v[30:33], v0 offset:1024
	ds_read_b128 v[42:45], v0 offset:2048
	ds_read_b128 v[46:49], v0 offset:3072
	s_add_u32 s12, s10, 0xfffe0080
	s_addc_u32 s13, s11, -1
	s_cmp_eq_u32 s54, 4
	s_cselect_b32 s35, s2, s13
	s_cselect_b32 s34, s3, s12
	s_cselect_b32 s13, s7, s52
	s_cselect_b32 s12, s27, s9
	s_cselect_b32 s100, -1, 0
	s_andn2_b32 s100, s100, s101
	s_add_i32 m0, s62, 0xc000
	ds_read_b128 v[50:53], v217
	ds_read_b128 v[54:57], v217 offset:1024
	ds_read_b128 v[58:61], v217 offset:2048
	ds_read_b128 v[62:65], v217 offset:3072
	ds_read_b128 v[178:181], v217 offset:4096
	ds_read_b128 v[182:185], v217 offset:5120
	ds_read_b128 v[198:201], v217 offset:6144
	ds_read_b128 v[208:211], v217 offset:7168
	global_load_lds_dwordx4 v194, s[10:11]
	s_add_i32 m0, s62, 0xe000
	s_nop 0
	global_load_lds_dwordx4 v196, s[10:11]
	s_waitcnt vmcnt(8)
	s_waitcnt lgkmcnt(0)
	s_setprio 1
	s_barrier
	v_mfma_f32_16x16x32_bf16 v[38:41], v[10:13], v[50:53], v[38:41]
	v_mfma_f32_16x16x32_bf16 v[34:37], v[18:21], v[50:53], v[34:37]
	v_mfma_f32_16x16x32_bf16 v[174:177], v[10:13], v[58:61], v[174:177]
	v_mfma_f32_16x16x32_bf16 v[170:173], v[18:21], v[58:61], v[170:173]
	v_mfma_f32_16x16x32_bf16 v[158:161], v[10:13], v[178:181], v[158:161]
	v_mfma_f32_16x16x32_bf16 v[154:157], v[18:21], v[178:181], v[154:157]
	v_mfma_f32_16x16x32_bf16 v[142:145], v[10:13], v[198:201], v[142:145]
	v_mfma_f32_16x16x32_bf16 v[138:141], v[18:21], v[198:201], v[138:141]
	v_mfma_f32_16x16x32_bf16 v[38:41], v[14:17], v[54:57], v[38:41]
	v_mfma_f32_16x16x32_bf16 v[34:37], v[22:25], v[54:57], v[34:37]
	v_mfma_f32_16x16x32_bf16 v[174:177], v[14:17], v[62:65], v[174:177]
	v_mfma_f32_16x16x32_bf16 v[170:173], v[22:25], v[62:65], v[170:173]
	v_mfma_f32_16x16x32_bf16 v[158:161], v[14:17], v[182:185], v[158:161]
	v_mfma_f32_16x16x32_bf16 v[154:157], v[22:25], v[182:185], v[154:157]
	v_mfma_f32_16x16x32_bf16 v[142:145], v[14:17], v[208:211], v[142:145]
	v_mfma_f32_16x16x32_bf16 v[138:141], v[22:25], v[208:211], v[138:141]
	s_setprio 0
	s_setprio 1
	v_mfma_f32_16x16x32_bf16 v[6:9], v[26:29], v[50:53], v[6:9]
	v_mfma_f32_16x16x32_bf16 v[2:5], v[42:45], v[50:53], v[2:5]
	v_mfma_f32_16x16x32_bf16 v[6:9], v[30:33], v[54:57], v[6:9]
	v_mfma_f32_16x16x32_bf16 v[2:5], v[46:49], v[54:57], v[2:5]
	v_mfma_f32_16x16x32_bf16 v[50:53], v[26:29], v[58:61], v[166:169]
	v_mfma_f32_16x16x32_bf16 v[54:57], v[42:45], v[58:61], v[162:165]
	v_mfma_f32_16x16x32_bf16 v[134:137], v[26:29], v[198:201], v[134:137]
	v_mfma_f32_16x16x32_bf16 v[130:133], v[42:45], v[198:201], v[130:133]
	v_mfma_f32_16x16x32_bf16 v[50:53], v[30:33], v[62:65], v[50:53]
	v_mfma_f32_16x16x32_bf16 v[54:57], v[46:49], v[62:65], v[54:57]
	v_mfma_f32_16x16x32_bf16 v[58:61], v[26:29], v[178:181], v[150:153]
	v_mfma_f32_16x16x32_bf16 v[62:65], v[42:45], v[178:181], v[146:149]
	v_mfma_f32_16x16x32_bf16 v[134:137], v[30:33], v[208:211], v[134:137]
	v_mfma_f32_16x16x32_bf16 v[130:133], v[46:49], v[208:211], v[130:133]
	v_mfma_f32_16x16x32_bf16 v[58:61], v[30:33], v[182:185], v[58:61]
	v_mfma_f32_16x16x32_bf16 v[62:65], v[46:49], v[182:185], v[62:65]
	s_barrier
	s_setprio 0
	s_mov_b32 m0, s50
	v_lshl_add_u64 v[202:203], s[12:13], 0, v[188:189]
	s_add_u32 s56, s12, 0x20000
	s_addc_u32 s57, s13, 0
	ds_read_b128 v[146:149], v217 offset:16384
	ds_read_b128 v[150:153], v217 offset:17408
	ds_read_b128 v[162:165], v217 offset:18432
	ds_read_b128 v[166:169], v217 offset:19456
	ds_read_b128 v[178:181], v217 offset:20480
	ds_read_b128 v[182:185], v217 offset:21504
	ds_read_b128 v[198:201], v217 offset:22528
	ds_read_b128 v[208:211], v217 offset:23552
	s_cmp_lg_u32 s100, 0
	s_cbranch_scc1 .Ltl_qp_0s
	global_load_lds_dwordx4 v188, s[12:13]
	v_lshl_add_u64 v[204:205], s[12:13], 0, v[192:193]
	s_mov_b32 m0, s51
	s_nop 0
	global_load_lds_dwordx4 v192, s[12:13]
	s_mov_b32 m0, s59
	v_lshl_add_u64 v[222:223], s[34:35], 0, v[190:191]
	global_load_lds_dwordx4 v188, s[56:57]
	s_mov_b32 m0, s60
	s_nop 0
	global_load_lds_dwordx4 v192, s[56:57]
	v_lshl_add_u64 v[206:207], s[34:35], 0, v[186:187]
	s_mov_b32 m0, s62
	s_nop 0
	global_load_lds_dwordx4 v186, s[34:35]
	s_mov_b32 m0, s63
	s_nop 0
	global_load_lds_dwordx4 v190, s[34:35]
	s_waitcnt vmcnt(8)
	s_branch .Ltl_qp_0d

; #define PG8_STAGE(bufoff, gbase, voff) do { _Pragma("unroll") for (int _i = 0; _i < 2; ++_i) \
;         __builtin_amdgcn_global_load_lds((const unsigned*)((const char*)(gbase) + (voff)[_i]), (LAS unsigned*)(lds + (bufoff) + ldsw + _i * 8192), 16, 0, 0); } while (0)
; #define PG8_LDA(dst, b, h) do { _Pragma("unroll") for (int m = 0; m < NM; ++m) _Pragma("unroll") for (int k = 0; k < 2; ++k) dst[m][k] = *(const LAS bf16x8*)(lds + PG8_SA(b, h) + aoff + m * 2048 + k * 1024); } while (0)
; #define PG8_LDB(dst, b, h) do { _Pragma("unroll") for (int n = 0; n < 2; ++n) _Pragma("unroll") for (int k = 0; k < 2; ++k) dst[n][k] = *(const LAS bf16x8*)(lds + PG8_SB(b, h) + boff + n * 2048 + k * 1024); } while (0)
; #define PG8_MMA(ai, bj, At, Bt) do { __builtin_amdgcn_s_setprio(1); _Pragma("unroll") for (int m = 0; m < NM; ++m) _Pragma("unroll") for (int n = 0; n < 2; ++n) _Pragma("unroll") for (int k = 0; k < 2; ++k) \
;         acc[ai][bj][m][n] = __builtin_amdgcn_mfma_f32_16x16x32_bf16(Bt[n][k], At[m][k], acc[ai][bj][m][n], 0, 0, 0); __builtin_amdgcn_s_setprio(0); } while (0)
; #define PG8_WAIT_V(n) asm volatile("s_waitcnt vmcnt(" #n ")" ::: "memory")
; #define PG8_WAIT_L(n) asm volatile("s_waitcnt lgkmcnt(" #n ")" ::: "memory")
; #define PG8_BAR __builtin_amdgcn_s_barrier()
; #define PG8_SCHED __builtin_amdgcn_sched_barrier(0)
;     ...
;             PG8_WAIT_V(8); PG8_WAIT_L(0); PG8_BAR; PG8_MMA(1, 0, At, B0); PG8_MMA(1, 1, At, B1); PG8_BAR; PG8_SCHED;
;             PG8_LDB(B0, 1, 0); PG8_LDB(B1, 1, 1); PG8_SCHED; PG8_LDA(At, 1, 0); PG8_STAGE(PG8_SA(0, 1), a2 + hstepA, voffA);
.Ltl_qp_0d:
	s_waitcnt lgkmcnt(0)
	s_setprio 1
	s_barrier
	v_mfma_f32_16x16x32_bf16 v[126:129], v[10:13], v[146:149], v[126:129]
	v_mfma_f32_16x16x32_bf16 v[122:125], v[18:21], v[146:149], v[122:125]
	v_mfma_f32_16x16x32_bf16 v[110:113], v[10:13], v[162:165], v[110:113]
	v_mfma_f32_16x16x32_bf16 v[106:109], v[18:21], v[162:165], v[106:109]
	v_mfma_f32_16x16x32_bf16 v[94:97], v[10:13], v[178:181], v[94:97]
	v_mfma_f32_16x16x32_bf16 v[90:93], v[18:21], v[178:181], v[90:93]
	v_mfma_f32_16x16x32_bf16 v[10:13], v[10:13], v[198:201], v[78:81]
	v_mfma_f32_16x16x32_bf16 v[126:129], v[14:17], v[150:153], v[126:129]
	v_mfma_f32_16x16x32_bf16 v[122:125], v[22:25], v[150:153], v[122:125]
	v_mfma_f32_16x16x32_bf16 v[110:113], v[14:17], v[166:169], v[110:113]
	v_mfma_f32_16x16x32_bf16 v[106:109], v[22:25], v[166:169], v[106:109]
	v_mfma_f32_16x16x32_bf16 v[94:97], v[14:17], v[182:185], v[94:97]
	v_mfma_f32_16x16x32_bf16 v[90:93], v[22:25], v[182:185], v[90:93]
	v_mfma_f32_16x16x32_bf16 v[10:13], v[14:17], v[208:211], v[10:13]
	v_mfma_f32_16x16x32_bf16 v[14:17], v[18:21], v[198:201], v[74:77]
	v_mfma_f32_16x16x32_bf16 v[14:17], v[22:25], v[208:211], v[14:17]
	s_setprio 0
	s_setprio 1
	v_mfma_f32_16x16x32_bf16 v[74:77], v[26:29], v[162:165], v[102:105]
	v_mfma_f32_16x16x32_bf16 v[102:105], v[30:33], v[166:169], v[74:77]
	v_mfma_f32_16x16x32_bf16 v[74:77], v[42:45], v[162:165], v[98:101]
	v_mfma_f32_16x16x32_bf16 v[98:101], v[46:49], v[166:169], v[74:77]
	v_mfma_f32_16x16x32_bf16 v[74:77], v[26:29], v[178:181], v[86:89]
	v_mfma_f32_16x16x32_bf16 v[18:21], v[26:29], v[146:149], v[118:121]
	v_mfma_f32_16x16x32_bf16 v[86:89], v[30:33], v[182:185], v[74:77]
	v_mfma_f32_16x16x32_bf16 v[74:77], v[42:45], v[178:181], v[82:85]
	v_mfma_f32_16x16x32_bf16 v[26:29], v[26:29], v[198:201], v[70:73]
	v_mfma_f32_16x16x32_bf16 v[18:21], v[30:33], v[150:153], v[18:21]
	v_mfma_f32_16x16x32_bf16 v[22:25], v[42:45], v[146:149], v[114:117]
	v_mfma_f32_16x16x32_bf16 v[82:85], v[46:49], v[182:185], v[74:77]
	v_mfma_f32_16x16x32_bf16 v[26:29], v[30:33], v[208:211], v[26:29]
	v_mfma_f32_16x16x32_bf16 v[30:33], v[42:45], v[198:201], v[66:69]
	v_mfma_f32_16x16x32_bf16 v[22:25], v[46:49], v[150:153], v[22:25]
	v_mfma_f32_16x16x32_bf16 v[30:33], v[46:49], v[208:211], v[30:33]
	s_barrier
	s_setprio 0
	v_add_u32_e32 v0, s69, v216
	ds_read_b128 v[42:45], v0
	ds_read_b128 v[46:49], v0 offset:1024
	ds_read_b128 v[66:69], v0 offset:2048
	ds_read_b128 v[70:73], v0 offset:3072
	v_add_u32_e32 v0, s74, v216
	ds_read_b128 v[178:181], v0
	ds_read_b128 v[182:185], v0 offset:1024
	ds_read_b128 v[198:201], v0 offset:2048
	ds_read_b128 v[208:211], v0 offset:3072
	s_add_u32 s34, s34, 0x20000
	s_addc_u32 s35, s35, 0
	s_mov_b32 m0, s64
	ds_read_b128 v[74:77], v217 offset:32768
	ds_read_b128 v[78:81], v217 offset:33792
	ds_read_b128 v[114:117], v217 offset:34816
	ds_read_b128 v[118:121], v217 offset:35840
	ds_read_b128 v[146:149], v217 offset:36864
	ds_read_b128 v[212:215], v217 offset:37888
	ds_read_b128 v[218:221], v217 offset:38912
	ds_read_b128 v[226:229], v217 offset:39936
	s_cmp_lg_u32 s100, 0
	s_cbranch_scc1 .Ltl_qp_1s
	global_load_lds_dwordx4 v186, s[34:35]
	s_mov_b32 m0, s68
	s_nop 0
	global_load_lds_dwordx4 v190, s[34:35]
	s_waitcnt vmcnt(8)
	s_branch .Ltl_qp_1d

; #define PG8_STAGE(bufoff, gbase, voff) do { _Pragma("unroll") for (int _i = 0; _i < 2; ++_i) \
;         __builtin_amdgcn_global_load_lds((const unsigned*)((const char*)(gbase) + (voff)[_i]), (LAS unsigned*)(lds + (bufoff) + ldsw + _i * 8192), 16, 0, 0); } while (0)
; #define PG8_LDA(dst, b, h) do { _Pragma("unroll") for (int m = 0; m < NM; ++m) _Pragma("unroll") for (int k = 0; k < 2; ++k) dst[m][k] = *(const LAS bf16x8*)(lds + PG8_SA(b, h) + aoff + m * 2048 + k * 1024); } while (0)
; #define PG8_MMA(ai, bj, At, Bt) do { __builtin_amdgcn_s_setprio(1); _Pragma("unroll") for (int m = 0; m < NM; ++m) _Pragma("unroll") for (int n = 0; n < 2; ++n) _Pragma("unroll") for (int k = 0; k < 2; ++k) \
;         acc[ai][bj][m][n] = __builtin_amdgcn_mfma_f32_16x16x32_bf16(Bt[n][k], At[m][k], acc[ai][bj][m][n], 0, 0, 0); __builtin_amdgcn_s_setprio(0); } while (0)
; #define PG8_WAIT_V(n) asm volatile("s_waitcnt vmcnt(" #n ")" ::: "memory")
; #define PG8_WAIT_L(n) asm volatile("s_waitcnt lgkmcnt(" #n ")" ::: "memory")
; #define PG8_BAR __builtin_amdgcn_s_barrier()
; #define PG8_SCHED __builtin_amdgcn_sched_barrier(0)
;     ...
;             PG8_WAIT_V(8); PG8_WAIT_L(0); PG8_BAR; PG8_MMA(0, 0, At, B0); PG8_MMA(0, 1, At, B1); PG8_BAR; PG8_SCHED;
;             PG8_LDA(At, 1, 1); PG8_STAGE(PG8_SB(1, 0), b3, voffB); PG8_STAGE(PG8_SB(1, 1), b3 + hstepB, voffB); PG8_STAGE(PG8_SA(1, 0), a3, voffA);
.Ltl_qp_1d:
	s_waitcnt lgkmcnt(0)
	s_setprio 1
	s_barrier
	v_mfma_f32_16x16x32_bf16 v[150:153], v[42:45], v[114:117], v[174:177]
	v_mfma_f32_16x16x32_bf16 v[174:177], v[46:49], v[118:121], v[150:153]
	v_mfma_f32_16x16x32_bf16 v[150:153], v[66:69], v[114:117], v[170:173]
	v_mfma_f32_16x16x32_bf16 v[170:173], v[70:73], v[118:121], v[150:153]
	v_mfma_f32_16x16x32_bf16 v[150:153], v[42:45], v[146:149], v[158:161]
	v_mfma_f32_16x16x32_bf16 v[38:41], v[42:45], v[74:77], v[38:41]
	v_mfma_f32_16x16x32_bf16 v[34:37], v[66:69], v[74:77], v[34:37]
	v_mfma_f32_16x16x32_bf16 v[158:161], v[46:49], v[212:215], v[150:153]
	v_mfma_f32_16x16x32_bf16 v[150:153], v[66:69], v[146:149], v[154:157]
	v_mfma_f32_16x16x32_bf16 v[142:145], v[42:45], v[218:221], v[142:145]
	v_mfma_f32_16x16x32_bf16 v[138:141], v[66:69], v[218:221], v[138:141]
	v_mfma_f32_16x16x32_bf16 v[38:41], v[46:49], v[78:81], v[38:41]
	v_mfma_f32_16x16x32_bf16 v[34:37], v[70:73], v[78:81], v[34:37]
	v_mfma_f32_16x16x32_bf16 v[154:157], v[70:73], v[212:215], v[150:153]
	v_mfma_f32_16x16x32_bf16 v[142:145], v[46:49], v[226:229], v[142:145]
	v_mfma_f32_16x16x32_bf16 v[138:141], v[70:73], v[226:229], v[138:141]
	s_setprio 0
	s_setprio 1
	v_mfma_f32_16x16x32_bf16 v[50:53], v[178:181], v[114:117], v[50:53]
	v_mfma_f32_16x16x32_bf16 v[166:169], v[182:185], v[118:121], v[50:53]
	v_mfma_f32_16x16x32_bf16 v[50:53], v[198:201], v[114:117], v[54:57]
	v_mfma_f32_16x16x32_bf16 v[162:165], v[208:211], v[118:121], v[50:53]
	v_mfma_f32_16x16x32_bf16 v[50:53], v[178:181], v[146:149], v[58:61]
	v_mfma_f32_16x16x32_bf16 v[150:153], v[182:185], v[212:215], v[50:53]
	v_mfma_f32_16x16x32_bf16 v[50:53], v[198:201], v[146:149], v[62:65]
	v_mfma_f32_16x16x32_bf16 v[146:149], v[208:211], v[212:215], v[50:53]
	v_mfma_f32_16x16x32_bf16 v[50:53], v[178:181], v[218:221], v[134:137]
	v_mfma_f32_16x16x32_bf16 v[6:9], v[178:181], v[74:77], v[6:9]
	v_mfma_f32_16x16x32_bf16 v[2:5], v[198:201], v[74:77], v[2:5]
	v_mfma_f32_16x16x32_bf16 v[134:137], v[182:185], v[226:229], v[50:53]
	v_mfma_f32_16x16x32_bf16 v[50:53], v[198:201], v[218:221], v[130:133]
	v_mfma_f32_16x16x32_bf16 v[6:9], v[182:185], v[78:81], v[6:9]
	v_mfma_f32_16x16x32_bf16 v[2:5], v[208:211], v[78:81], v[2:5]
	v_mfma_f32_16x16x32_bf16 v[130:133], v[208:211], v[226:229], v[50:53]
	s_barrier
	s_setprio 0
	s_mov_b32 m0, s70
	v_lshl_add_u64 v[74:75], v[202:203], 0, s[66:67]
	s_add_u32 s12, s12, 0x20080
	s_addc_u32 s13, s13, 0
	ds_read_b128 v[50:53], v217 offset:49152
	ds_read_b128 v[54:57], v217 offset:50176
	ds_read_b128 v[58:61], v217 offset:51200
	ds_read_b128 v[62:65], v217 offset:52224
	ds_read_b128 v[212:215], v217 offset:53248
	ds_read_b128 v[218:221], v217 offset:54272
	ds_read_b128 v[226:229], v217 offset:55296
	ds_read_b128 v[230:233], v217 offset:56320
	s_cmp_lg_u32 s100, 0
	s_cbranch_scc1 .Ltl_qp_2s
	global_load_lds_dwordx4 v[74:75], off
	v_lshl_add_u64 v[74:75], v[204:205], 0, s[66:67]
	s_mov_b32 m0, s71
	s_nop 0
	global_load_lds_dwordx4 v[74:75], off
	s_mov_b32 m0, s75
	s_nop 0
	global_load_lds_dwordx4 v188, s[12:13]
	s_mov_b32 m0, s80
	s_nop 0
	global_load_lds_dwordx4 v192, s[12:13]
	v_lshl_add_u64 v[74:75], v[206:207], 0, s[66:67]
	s_mov_b32 m0, s72
	s_nop 0
	global_load_lds_dwordx4 v[74:75], off
	v_lshl_add_u64 v[74:75], v[222:223], 0, s[66:67]
	s_mov_b32 m0, s73
	s_nop 0
	global_load_lds_dwordx4 v[74:75], off
	s_waitcnt vmcnt(8)
	s_branch .Ltl_qp_2d

; #define PG8_STAGE(bufoff, gbase, voff) do { _Pragma("unroll") for (int _i = 0; _i < 2; ++_i) \
;         __builtin_amdgcn_global_load_lds((const unsigned*)((const char*)(gbase) + (voff)[_i]), (LAS unsigned*)(lds + (bufoff) + ldsw + _i * 8192), 16, 0, 0); } while (0)
; #define PG8_LDA(dst, b, h) do { _Pragma("unroll") for (int m = 0; m < NM; ++m) _Pragma("unroll") for (int k = 0; k < 2; ++k) dst[m][k] = *(const LAS bf16x8*)(lds + PG8_SA(b, h) + aoff + m * 2048 + k * 1024); } while (0)
; #define PG8_MMA(ai, bj, At, Bt) do { __builtin_amdgcn_s_setprio(1); _Pragma("unroll") for (int m = 0; m < NM; ++m) _Pragma("unroll") for (int n = 0; n < 2; ++n) _Pragma("unroll") for (int k = 0; k < 2; ++k) \
;         acc[ai][bj][m][n] = __builtin_amdgcn_mfma_f32_16x16x32_bf16(Bt[n][k], At[m][k], acc[ai][bj][m][n], 0, 0, 0); __builtin_amdgcn_s_setprio(0); } while (0)
; #define PG8_WAIT_V(n) asm volatile("s_waitcnt vmcnt(" #n ")" ::: "memory")
; #define PG8_WAIT_L(n) asm volatile("s_waitcnt lgkmcnt(" #n ")" ::: "memory")
; #define PG8_BAR __builtin_amdgcn_s_barrier()
; #define PG8_SCHED __builtin_amdgcn_sched_barrier(0)
;     ...
;             PG8_WAIT_V(8); PG8_WAIT_L(0); PG8_BAR; PG8_MMA(0, 0, At, B0); PG8_MMA(0, 1, At, B1); PG8_BAR; PG8_SCHED;
;             PG8_LDA(At, 1, 1); PG8_STAGE(PG8_SB(1, 0), b3, voffB); PG8_STAGE(PG8_SB(1, 1), b3 + hstepB, voffB); PG8_STAGE(PG8_SA(1, 0), a3, voffA);
;             PG8_WAIT_V(8); PG8_WAIT_L(0); PG8_BAR; PG8_MMA(1, 0, At, B0); PG8_MMA(1, 1, At, B1); PG8_BAR; PG8_SCHED;
.Ltl_qp_2d:
	s_waitcnt lgkmcnt(0)
	s_setprio 1
	s_barrier
	v_mfma_f32_16x16x32_bf16 v[74:77], v[42:45], v[50:53], v[126:129]
	v_mfma_f32_16x16x32_bf16 v[126:129], v[46:49], v[54:57], v[74:77]
	v_mfma_f32_16x16x32_bf16 v[74:77], v[66:69], v[50:53], v[122:125]
	v_mfma_f32_16x16x32_bf16 v[122:125], v[70:73], v[54:57], v[74:77]
	v_mfma_f32_16x16x32_bf16 v[74:77], v[42:45], v[58:61], v[110:113]
	v_mfma_f32_16x16x32_bf16 v[110:113], v[46:49], v[62:65], v[74:77]
	v_mfma_f32_16x16x32_bf16 v[74:77], v[66:69], v[58:61], v[106:109]
	v_mfma_f32_16x16x32_bf16 v[106:109], v[70:73], v[62:65], v[74:77]
	v_mfma_f32_16x16x32_bf16 v[74:77], v[42:45], v[212:215], v[94:97]
	v_mfma_f32_16x16x32_bf16 v[10:13], v[42:45], v[226:229], v[10:13]
	v_mfma_f32_16x16x32_bf16 v[94:97], v[46:49], v[218:221], v[74:77]
	v_mfma_f32_16x16x32_bf16 v[74:77], v[66:69], v[212:215], v[90:93]
	v_mfma_f32_16x16x32_bf16 v[78:81], v[46:49], v[230:233], v[10:13]
	v_mfma_f32_16x16x32_bf16 v[10:13], v[66:69], v[226:229], v[14:17]
	v_mfma_f32_16x16x32_bf16 v[90:93], v[70:73], v[218:221], v[74:77]
	v_mfma_f32_16x16x32_bf16 v[74:77], v[70:73], v[230:233], v[10:13]
	s_setprio 0
	s_setprio 1
	v_mfma_f32_16x16x32_bf16 v[10:13], v[178:181], v[50:53], v[18:21]
	v_mfma_f32_16x16x32_bf16 v[118:121], v[182:185], v[54:57], v[10:13]
	v_mfma_f32_16x16x32_bf16 v[10:13], v[198:201], v[50:53], v[22:25]
	v_mfma_f32_16x16x32_bf16 v[114:117], v[208:211], v[54:57], v[10:13]
	v_mfma_f32_16x16x32_bf16 v[10:13], v[178:181], v[58:61], v[102:105]
	v_mfma_f32_16x16x32_bf16 v[102:105], v[182:185], v[62:65], v[10:13]
	v_mfma_f32_16x16x32_bf16 v[10:13], v[198:201], v[58:61], v[98:101]
	v_mfma_f32_16x16x32_bf16 v[98:101], v[208:211], v[62:65], v[10:13]
	v_mfma_f32_16x16x32_bf16 v[10:13], v[178:181], v[212:215], v[86:89]
	v_mfma_f32_16x16x32_bf16 v[86:89], v[182:185], v[218:221], v[10:13]
	v_mfma_f32_16x16x32_bf16 v[10:13], v[198:201], v[212:215], v[82:85]
	v_mfma_f32_16x16x32_bf16 v[82:85], v[208:211], v[218:221], v[10:13]
	v_mfma_f32_16x16x32_bf16 v[10:13], v[178:181], v[226:229], v[26:29]
	v_mfma_f32_16x16x32_bf16 v[70:73], v[182:185], v[230:233], v[10:13]
	v_mfma_f32_16x16x32_bf16 v[10:13], v[198:201], v[226:229], v[30:33]
	v_mfma_f32_16x16x32_bf16 v[66:69], v[208:211], v[230:233], v[10:13]
	s_barrier
	s_setprio 0
	s_add_i32 s54, s54, 2
	s_add_u32 s10, s10, 0x100
	s_addc_u32 s11, s11, 0
	s_add_u32 s9, s9, 0x100
	s_addc_u32 s52, s52, 0
	s_cmp_gt_u32 s54, 5
	s_cbranch_scc0 .LBB0_1192
	s_and_b64 vcc, exec, s[16:17]
	s_cbranch_vccz .LBB0_1195
	s_barrier

; #define PG8_STAGE(bufoff, gbase, voff) do { _Pragma("unroll") for (int _i = 0; _i < 2; ++_i) \
;         __builtin_amdgcn_global_load_lds((const unsigned*)((const char*)(gbase) + (voff)[_i]), (LAS unsigned*)(lds + (bufoff) + ldsw + _i * 8192), 16, 0, 0); } while (0)
; #define PG8_LDA(dst, b, h) do { _Pragma("unroll") for (int m = 0; m < NM; ++m) _Pragma("unroll") for (int k = 0; k < 2; ++k) dst[m][k] = *(const LAS bf16x8*)(lds + PG8_SA(b, h) + aoff + m * 2048 + k * 1024); } while (0)
; #define PG8_LDB(dst, b, h) do { _Pragma("unroll") for (int n = 0; n < 2; ++n) _Pragma("unroll") for (int k = 0; k < 2; ++k) dst[n][k] = *(const LAS bf16x8*)(lds + PG8_SB(b, h) + boff + n * 2048 + k * 1024); } while (0)
; #define PG8_MMA(ai, bj, At, Bt) do { __builtin_amdgcn_s_setprio(1); _Pragma("unroll") for (int m = 0; m < NM; ++m) _Pragma("unroll") for (int n = 0; n < 2; ++n) _Pragma("unroll") for (int k = 0; k < 2; ++k) \
;         acc[ai][bj][m][n] = __builtin_amdgcn_mfma_f32_16x16x32_bf16(Bt[n][k], At[m][k], acc[ai][bj][m][n], 0, 0, 0); __builtin_amdgcn_s_setprio(0); } while (0)
; #define PG8_WAIT_V(n) asm volatile("s_waitcnt vmcnt(" #n ")" ::: "memory")
; #define PG8_WAIT_L(n) asm volatile("s_waitcnt lgkmcnt(" #n ")" ::: "memory")
; #define PG8_BAR __builtin_amdgcn_s_barrier()
; #define PG8_SCHED __builtin_amdgcn_sched_barrier(0)
;     ...
;             PG8_LDB(B0, 0, 0); PG8_LDB(B1, 0, 1); PG8_SCHED; PG8_LDA(At, 0, 0); PG8_STAGE(PG8_SA(1, 1), a1 + hstepA, voffA);
;             PG8_WAIT_V(8); PG8_WAIT_L(0); PG8_BAR; PG8_MMA(0, 0, At, B0); PG8_MMA(0, 1, At, B1); PG8_BAR; PG8_SCHED;
;             PG8_LDA(At, 0, 1); PG8_STAGE(PG8_SB(0, 0), b2, voffB); PG8_STAGE(PG8_SB(0, 1), b2 + hstepB, voffB); PG8_STAGE(PG8_SA(0, 0), a2, voffA);
.LBB0_1454:
	v_add_u32_e32 v140, s31, v142
	ds_read_b128 v[144:147], v140
	ds_read_b128 v[148:151], v140 offset:1024
	ds_read_b128 v[152:155], v140 offset:2048
	ds_read_b128 v[156:159], v140 offset:3072
	v_add_u32_e32 v140, s35, v142
	ds_read_b128 v[160:163], v140
	ds_read_b128 v[164:167], v140 offset:1024
	ds_read_b128 v[168:171], v140 offset:2048
	ds_read_b128 v[172:175], v140 offset:3072
	s_add_u32 s6, s20, 0x100
	s_addc_u32 s7, s21, 0
	s_cmp_eq_u32 s73, 4
	s_cselect_b32 s25, s17, s7
	s_cselect_b32 s24, s16, s6
	s_cselect_b32 s23, s2, s60
	s_cselect_b32 s22, s3, s15
	s_cselect_b32 s100, -1, 0
	s_andn2_b32 s100, s100, s101
	s_add_i32 m0, s45, 0xc000
	ds_read_b128 v[176:179], v143
	ds_read_b128 v[180:183], v143 offset:1024
	ds_read_b128 v[184:187], v143 offset:2048
	ds_read_b128 v[188:191], v143 offset:3072
	ds_read_b128 v[192:195], v143 offset:4096
	ds_read_b128 v[196:199], v143 offset:5120
	ds_read_b128 v[200:203], v143 offset:6144
	ds_read_b128 v[208:211], v143 offset:7168
	global_load_lds_dwordx4 v136, s[20:21]
	s_add_i32 m0, s45, 0xe000
	s_nop 0
	global_load_lds_dwordx4 v138, s[20:21]
	s_waitcnt vmcnt(8)
	s_waitcnt lgkmcnt(0)
	s_setprio 1
	s_barrier
	v_mfma_f32_16x16x32_bf16 v[126:129], v[144:147], v[176:179], v[126:129]
	v_mfma_f32_16x16x32_bf16 v[122:125], v[152:155], v[176:179], v[122:125]
	v_mfma_f32_16x16x32_bf16 v[118:121], v[144:147], v[184:187], v[118:121]
	v_mfma_f32_16x16x32_bf16 v[114:117], v[152:155], v[184:187], v[114:117]
	v_mfma_f32_16x16x32_bf16 v[110:113], v[144:147], v[192:195], v[110:113]
	v_mfma_f32_16x16x32_bf16 v[106:109], v[152:155], v[192:195], v[106:109]
	v_mfma_f32_16x16x32_bf16 v[102:105], v[144:147], v[200:203], v[102:105]
	v_mfma_f32_16x16x32_bf16 v[98:101], v[152:155], v[200:203], v[98:101]
	v_mfma_f32_16x16x32_bf16 v[126:129], v[148:151], v[180:183], v[126:129]
	v_mfma_f32_16x16x32_bf16 v[122:125], v[156:159], v[180:183], v[122:125]
	v_mfma_f32_16x16x32_bf16 v[118:121], v[148:151], v[188:191], v[118:121]
	v_mfma_f32_16x16x32_bf16 v[114:117], v[156:159], v[188:191], v[114:117]
	v_mfma_f32_16x16x32_bf16 v[110:113], v[148:151], v[196:199], v[110:113]
	v_mfma_f32_16x16x32_bf16 v[106:109], v[156:159], v[196:199], v[106:109]
	v_mfma_f32_16x16x32_bf16 v[102:105], v[148:151], v[208:211], v[102:105]
	v_mfma_f32_16x16x32_bf16 v[98:101], v[156:159], v[208:211], v[98:101]
	s_setprio 0
	s_setprio 1
	v_mfma_f32_16x16x32_bf16 v[62:65], v[160:163], v[176:179], v[62:65]
	v_mfma_f32_16x16x32_bf16 v[58:61], v[168:171], v[176:179], v[58:61]
	v_mfma_f32_16x16x32_bf16 v[54:57], v[160:163], v[184:187], v[54:57]
	v_mfma_f32_16x16x32_bf16 v[50:53], v[168:171], v[184:187], v[50:53]
	v_mfma_f32_16x16x32_bf16 v[46:49], v[160:163], v[192:195], v[46:49]
	v_mfma_f32_16x16x32_bf16 v[42:45], v[168:171], v[192:195], v[42:45]
	v_mfma_f32_16x16x32_bf16 v[38:41], v[160:163], v[200:203], v[38:41]
	v_mfma_f32_16x16x32_bf16 v[34:37], v[168:171], v[200:203], v[34:37]
	v_mfma_f32_16x16x32_bf16 v[62:65], v[164:167], v[180:183], v[62:65]
	v_mfma_f32_16x16x32_bf16 v[58:61], v[172:175], v[180:183], v[58:61]
	v_mfma_f32_16x16x32_bf16 v[54:57], v[164:167], v[188:191], v[54:57]
	v_mfma_f32_16x16x32_bf16 v[50:53], v[172:175], v[188:191], v[50:53]
	v_mfma_f32_16x16x32_bf16 v[46:49], v[164:167], v[196:199], v[46:49]
	v_mfma_f32_16x16x32_bf16 v[42:45], v[172:175], v[196:199], v[42:45]
	v_mfma_f32_16x16x32_bf16 v[38:41], v[164:167], v[208:211], v[38:41]
	v_mfma_f32_16x16x32_bf16 v[34:37], v[172:175], v[208:211], v[34:37]
	s_barrier
	s_setprio 0
	s_mov_b32 m0, s33
	v_lshl_add_u64 v[140:141], s[22:23], 0, v[0:1]
	s_add_u32 s20, s22, 0x20000
	s_addc_u32 s21, s23, 0
	ds_read_b128 v[176:179], v143 offset:16384
	ds_read_b128 v[180:183], v143 offset:17408
	ds_read_b128 v[184:187], v143 offset:18432
	ds_read_b128 v[188:191], v143 offset:19456
	ds_read_b128 v[192:195], v143 offset:20480
	ds_read_b128 v[196:199], v143 offset:21504
	ds_read_b128 v[200:203], v143 offset:22528
	ds_read_b128 v[208:211], v143 offset:23552
	s_cmp_lg_u32 s100, 0
	s_cbranch_scc1 .Ltl_kv_0s
	global_load_lds_dwordx4 v0, s[22:23]
	v_lshl_add_u64 v[204:205], s[22:23], 0, v[134:135]
	s_mov_b32 m0, s34
	s_nop 0
	global_load_lds_dwordx4 v134, s[22:23]
	s_mov_b32 m0, s43
	v_lshl_add_u64 v[212:213], s[24:25], 0, v[132:133]
	global_load_lds_dwordx4 v0, s[20:21]
	s_mov_b32 m0, s44
	s_nop 0
	global_load_lds_dwordx4 v134, s[20:21]
	v_lshl_add_u64 v[206:207], s[24:25], 0, v[130:131]
	s_mov_b32 m0, s45
	s_nop 0
	global_load_lds_dwordx4 v130, s[24:25]
	s_mov_b32 m0, s47
	s_nop 0
	global_load_lds_dwordx4 v132, s[24:25]
	s_waitcnt vmcnt(8)
	s_branch .Ltl_kv_0d

; #define PG8_STAGE(bufoff, gbase, voff) do { _Pragma("unroll") for (int _i = 0; _i < 2; ++_i) \
;         __builtin_amdgcn_global_load_lds((const unsigned*)((const char*)(gbase) + (voff)[_i]), (LAS unsigned*)(lds + (bufoff) + ldsw + _i * 8192), 16, 0, 0); } while (0)
; #define PG8_LDA(dst, b, h) do { _Pragma("unroll") for (int m = 0; m < NM; ++m) _Pragma("unroll") for (int k = 0; k < 2; ++k) dst[m][k] = *(const LAS bf16x8*)(lds + PG8_SA(b, h) + aoff + m * 2048 + k * 1024); } while (0)
; #define PG8_LDB(dst, b, h) do { _Pragma("unroll") for (int n = 0; n < 2; ++n) _Pragma("unroll") for (int k = 0; k < 2; ++k) dst[n][k] = *(const LAS bf16x8*)(lds + PG8_SB(b, h) + boff + n * 2048 + k * 1024); } while (0)
; #define PG8_MMA(ai, bj, At, Bt) do { __builtin_amdgcn_s_setprio(1); _Pragma("unroll") for (int m = 0; m < NM; ++m) _Pragma("unroll") for (int n = 0; n < 2; ++n) _Pragma("unroll") for (int k = 0; k < 2; ++k) \
;         acc[ai][bj][m][n] = __builtin_amdgcn_mfma_f32_16x16x32_bf16(Bt[n][k], At[m][k], acc[ai][bj][m][n], 0, 0, 0); __builtin_amdgcn_s_setprio(0); } while (0)
; #define PG8_WAIT_V(n) asm volatile("s_waitcnt vmcnt(" #n ")" ::: "memory")
; #define PG8_WAIT_L(n) asm volatile("s_waitcnt lgkmcnt(" #n ")" ::: "memory")
; #define PG8_BAR __builtin_amdgcn_s_barrier()
; #define PG8_SCHED __builtin_amdgcn_sched_barrier(0)
;     ...
;             PG8_WAIT_V(8); PG8_WAIT_L(0); PG8_BAR; PG8_MMA(1, 0, At, B0); PG8_MMA(1, 1, At, B1); PG8_BAR; PG8_SCHED;
;             PG8_LDB(B0, 1, 0); PG8_LDB(B1, 1, 1); PG8_SCHED; PG8_LDA(At, 1, 0); PG8_STAGE(PG8_SA(0, 1), a2 + hstepA, voffA);
.Ltl_kv_0d:
	s_waitcnt lgkmcnt(0)
	s_setprio 1
	s_barrier
	v_mfma_f32_16x16x32_bf16 v[94:97], v[144:147], v[176:179], v[94:97]
	v_mfma_f32_16x16x32_bf16 v[90:93], v[152:155], v[176:179], v[90:93]
	v_mfma_f32_16x16x32_bf16 v[86:89], v[144:147], v[184:187], v[86:89]
	v_mfma_f32_16x16x32_bf16 v[82:85], v[152:155], v[184:187], v[82:85]
	v_mfma_f32_16x16x32_bf16 v[78:81], v[144:147], v[192:195], v[78:81]
	v_mfma_f32_16x16x32_bf16 v[74:77], v[152:155], v[192:195], v[74:77]
	v_mfma_f32_16x16x32_bf16 v[70:73], v[144:147], v[200:203], v[70:73]
	v_mfma_f32_16x16x32_bf16 v[66:69], v[152:155], v[200:203], v[66:69]
	v_mfma_f32_16x16x32_bf16 v[94:97], v[148:151], v[180:183], v[94:97]
	v_mfma_f32_16x16x32_bf16 v[90:93], v[156:159], v[180:183], v[90:93]
	v_mfma_f32_16x16x32_bf16 v[86:89], v[148:151], v[188:191], v[86:89]
	v_mfma_f32_16x16x32_bf16 v[82:85], v[156:159], v[188:191], v[82:85]
	v_mfma_f32_16x16x32_bf16 v[78:81], v[148:151], v[196:199], v[78:81]
	v_mfma_f32_16x16x32_bf16 v[74:77], v[156:159], v[196:199], v[74:77]
	v_mfma_f32_16x16x32_bf16 v[70:73], v[148:151], v[208:211], v[70:73]
	v_mfma_f32_16x16x32_bf16 v[66:69], v[156:159], v[208:211], v[66:69]
	s_setprio 0
	s_setprio 1
	v_mfma_f32_16x16x32_bf16 v[30:33], v[160:163], v[176:179], v[30:33]
	v_mfma_f32_16x16x32_bf16 v[26:29], v[168:171], v[176:179], v[26:29]
	v_mfma_f32_16x16x32_bf16 v[22:25], v[160:163], v[184:187], v[22:25]
	v_mfma_f32_16x16x32_bf16 v[18:21], v[168:171], v[184:187], v[18:21]
	v_mfma_f32_16x16x32_bf16 v[14:17], v[160:163], v[192:195], v[14:17]
	v_mfma_f32_16x16x32_bf16 v[10:13], v[168:171], v[192:195], v[10:13]
	v_mfma_f32_16x16x32_bf16 v[6:9], v[160:163], v[200:203], v[6:9]
	v_mfma_f32_16x16x32_bf16 v[2:5], v[168:171], v[200:203], v[2:5]
	v_mfma_f32_16x16x32_bf16 v[30:33], v[164:167], v[180:183], v[30:33]
	v_mfma_f32_16x16x32_bf16 v[26:29], v[172:175], v[180:183], v[26:29]
	v_mfma_f32_16x16x32_bf16 v[22:25], v[164:167], v[188:191], v[22:25]
	v_mfma_f32_16x16x32_bf16 v[18:21], v[172:175], v[188:191], v[18:21]
	v_mfma_f32_16x16x32_bf16 v[14:17], v[164:167], v[196:199], v[14:17]
	v_mfma_f32_16x16x32_bf16 v[10:13], v[172:175], v[196:199], v[10:13]
	v_mfma_f32_16x16x32_bf16 v[6:9], v[164:167], v[208:211], v[6:9]
	v_mfma_f32_16x16x32_bf16 v[2:5], v[172:175], v[208:211], v[2:5]
	s_barrier
	s_setprio 0
	v_add_u32_e32 v156, s50, v142
	v_add_u32_e32 v172, s57, v142
	ds_read_b128 v[144:147], v156
	ds_read_b128 v[148:151], v156 offset:1024
	ds_read_b128 v[152:155], v156 offset:2048
	ds_read_b128 v[156:159], v156 offset:3072
	ds_read_b128 v[160:163], v172
	ds_read_b128 v[164:167], v172 offset:1024
	ds_read_b128 v[168:171], v172 offset:2048
	ds_read_b128 v[172:175], v172 offset:3072
	s_add_u32 s20, s24, 0x24000
	s_addc_u32 s21, s25, 0
	s_mov_b32 m0, s48
	ds_read_b128 v[176:179], v143 offset:32768
	ds_read_b128 v[180:183], v143 offset:33792
	ds_read_b128 v[184:187], v143 offset:34816
	ds_read_b128 v[188:191], v143 offset:35840
	ds_read_b128 v[192:195], v143 offset:36864
	ds_read_b128 v[196:199], v143 offset:37888
	ds_read_b128 v[200:203], v143 offset:38912
	ds_read_b128 v[208:211], v143 offset:39936
	s_cmp_lg_u32 s100, 0
	s_cbranch_scc1 .Ltl_kv_1s
	global_load_lds_dwordx4 v130, s[20:21]
	s_mov_b32 m0, s49
	s_nop 0
	global_load_lds_dwordx4 v132, s[20:21]
	s_waitcnt vmcnt(8)
	s_branch .Ltl_kv_1d

; #define PG8_STAGE(bufoff, gbase, voff) do { _Pragma("unroll") for (int _i = 0; _i < 2; ++_i) \
;         __builtin_amdgcn_global_load_lds((const unsigned*)((const char*)(gbase) + (voff)[_i]), (LAS unsigned*)(lds + (bufoff) + ldsw + _i * 8192), 16, 0, 0); } while (0)
; #define PG8_LDA(dst, b, h) do { _Pragma("unroll") for (int m = 0; m < NM; ++m) _Pragma("unroll") for (int k = 0; k < 2; ++k) dst[m][k] = *(const LAS bf16x8*)(lds + PG8_SA(b, h) + aoff + m * 2048 + k * 1024); } while (0)
; #define PG8_MMA(ai, bj, At, Bt) do { __builtin_amdgcn_s_setprio(1); _Pragma("unroll") for (int m = 0; m < NM; ++m) _Pragma("unroll") for (int n = 0; n < 2; ++n) _Pragma("unroll") for (int k = 0; k < 2; ++k) \
;         acc[ai][bj][m][n] = __builtin_amdgcn_mfma_f32_16x16x32_bf16(Bt[n][k], At[m][k], acc[ai][bj][m][n], 0, 0, 0); __builtin_amdgcn_s_setprio(0); } while (0)
; #define PG8_WAIT_V(n) asm volatile("s_waitcnt vmcnt(" #n ")" ::: "memory")
; #define PG8_WAIT_L(n) asm volatile("s_waitcnt lgkmcnt(" #n ")" ::: "memory")
; #define PG8_BAR __builtin_amdgcn_s_barrier()
; #define PG8_SCHED __builtin_amdgcn_sched_barrier(0)
;     ...
;             PG8_WAIT_V(8); PG8_WAIT_L(0); PG8_BAR; PG8_MMA(0, 0, At, B0); PG8_MMA(0, 1, At, B1); PG8_BAR; PG8_SCHED;
;             PG8_LDA(At, 1, 1); PG8_STAGE(PG8_SB(1, 0), b3, voffB); PG8_STAGE(PG8_SB(1, 1), b3 + hstepB, voffB); PG8_STAGE(PG8_SA(1, 0), a3, voffA);
.Ltl_kv_1d:
	s_waitcnt lgkmcnt(0)
	s_setprio 1
	s_barrier
	v_mfma_f32_16x16x32_bf16 v[126:129], v[144:147], v[176:179], v[126:129]
	v_mfma_f32_16x16x32_bf16 v[122:125], v[152:155], v[176:179], v[122:125]
	v_mfma_f32_16x16x32_bf16 v[118:121], v[144:147], v[184:187], v[118:121]
	v_mfma_f32_16x16x32_bf16 v[114:117], v[152:155], v[184:187], v[114:117]
	v_mfma_f32_16x16x32_bf16 v[110:113], v[144:147], v[192:195], v[110:113]
	v_mfma_f32_16x16x32_bf16 v[106:109], v[152:155], v[192:195], v[106:109]
	v_mfma_f32_16x16x32_bf16 v[102:105], v[144:147], v[200:203], v[102:105]
	v_mfma_f32_16x16x32_bf16 v[98:101], v[152:155], v[200:203], v[98:101]
	v_mfma_f32_16x16x32_bf16 v[126:129], v[148:151], v[180:183], v[126:129]
	v_mfma_f32_16x16x32_bf16 v[122:125], v[156:159], v[180:183], v[122:125]
	v_mfma_f32_16x16x32_bf16 v[118:121], v[148:151], v[188:191], v[118:121]
	v_mfma_f32_16x16x32_bf16 v[114:117], v[156:159], v[188:191], v[114:117]
	v_mfma_f32_16x16x32_bf16 v[110:113], v[148:151], v[196:199], v[110:113]
	v_mfma_f32_16x16x32_bf16 v[106:109], v[156:159], v[196:199], v[106:109]
	v_mfma_f32_16x16x32_bf16 v[102:105], v[148:151], v[208:211], v[102:105]
	v_mfma_f32_16x16x32_bf16 v[98:101], v[156:159], v[208:211], v[98:101]
	s_setprio 0
	s_setprio 1
	v_mfma_f32_16x16x32_bf16 v[62:65], v[160:163], v[176:179], v[62:65]
	v_mfma_f32_16x16x32_bf16 v[58:61], v[168:171], v[176:179], v[58:61]
	v_mfma_f32_16x16x32_bf16 v[54:57], v[160:163], v[184:187], v[54:57]
	v_mfma_f32_16x16x32_bf16 v[50:53], v[168:171], v[184:187], v[50:53]
	v_mfma_f32_16x16x32_bf16 v[46:49], v[160:163], v[192:195], v[46:49]
	v_mfma_f32_16x16x32_bf16 v[42:45], v[168:171], v[192:195], v[42:45]
	v_mfma_f32_16x16x32_bf16 v[38:41], v[160:163], v[200:203], v[38:41]
	v_mfma_f32_16x16x32_bf16 v[34:37], v[168:171], v[200:203], v[34:37]
	v_mfma_f32_16x16x32_bf16 v[62:65], v[164:167], v[180:183], v[62:65]
	v_mfma_f32_16x16x32_bf16 v[58:61], v[172:175], v[180:183], v[58:61]
	v_mfma_f32_16x16x32_bf16 v[54:57], v[164:167], v[188:191], v[54:57]
	v_mfma_f32_16x16x32_bf16 v[50:53], v[172:175], v[188:191], v[50:53]
	v_mfma_f32_16x16x32_bf16 v[46:49], v[164:167], v[196:199], v[46:49]
	v_mfma_f32_16x16x32_bf16 v[42:45], v[172:175], v[196:199], v[42:45]
	v_mfma_f32_16x16x32_bf16 v[38:41], v[164:167], v[208:211], v[38:41]
	v_mfma_f32_16x16x32_bf16 v[34:37], v[172:175], v[208:211], v[34:37]
	s_barrier
	s_setprio 0
	s_mov_b32 m0, s51
	v_lshl_add_u64 v[140:141], v[140:141], 0, s[66:67]
	s_add_u32 s20, s22, 0x20080
	s_addc_u32 s21, s23, 0
	ds_read_b128 v[176:179], v143 offset:49152
	ds_read_b128 v[180:183], v143 offset:50176
	ds_read_b128 v[184:187], v143 offset:51200
	ds_read_b128 v[188:191], v143 offset:52224
	ds_read_b128 v[192:195], v143 offset:53248
	ds_read_b128 v[196:199], v143 offset:54272
	ds_read_b128 v[200:203], v143 offset:55296
	ds_read_b128 v[208:211], v143 offset:56320
	s_cmp_lg_u32 s100, 0
	s_cbranch_scc1 .Ltl_kv_2s
	global_load_lds_dwordx4 v[140:141], off
	v_lshl_add_u64 v[140:141], v[204:205], 0, s[66:67]
	s_mov_b32 m0, s52
	s_nop 0
	global_load_lds_dwordx4 v[140:141], off
	s_mov_b32 m0, s58
	s_nop 0
	global_load_lds_dwordx4 v0, s[20:21]
	s_mov_b32 m0, s59
	s_nop 0
	global_load_lds_dwordx4 v134, s[20:21]
	v_lshl_add_u64 v[140:141], v[206:207], 0, s[66:67]
	s_mov_b32 m0, s54
	s_nop 0
	global_load_lds_dwordx4 v[140:141], off
	v_lshl_add_u64 v[140:141], v[212:213], 0, s[66:67]
	s_mov_b32 m0, s56
	s_nop 0
	global_load_lds_dwordx4 v[140:141], off
	s_waitcnt vmcnt(8)
	s_branch .Ltl_kv_2d

; #define PG8_STAGE(bufoff, gbase, voff) do { _Pragma("unroll") for (int _i = 0; _i < 2; ++_i) \
;         __builtin_amdgcn_global_load_lds((const unsigned*)((const char*)(gbase) + (voff)[_i]), (LAS unsigned*)(lds + (bufoff) + ldsw + _i * 8192), 16, 0, 0); } while (0)
; #define PG8_LDA(dst, b, h) do { _Pragma("unroll") for (int m = 0; m < NM; ++m) _Pragma("unroll") for (int k = 0; k < 2; ++k) dst[m][k] = *(const LAS bf16x8*)(lds + PG8_SA(b, h) + aoff + m * 2048 + k * 1024); } while (0)
; #define PG8_MMA(ai, bj, At, Bt) do { __builtin_amdgcn_s_setprio(1); _Pragma("unroll") for (int m = 0; m < NM; ++m) _Pragma("unroll") for (int n = 0; n < 2; ++n) _Pragma("unroll") for (int k = 0; k < 2; ++k) \
;         acc[ai][bj][m][n] = __builtin_amdgcn_mfma_f32_16x16x32_bf16(Bt[n][k], At[m][k], acc[ai][bj][m][n], 0, 0, 0); __builtin_amdgcn_s_setprio(0); } while (0)
; #define PG8_WAIT_V(n) asm volatile("s_waitcnt vmcnt(" #n ")" ::: "memory")
; #define PG8_WAIT_L(n) asm volatile("s_waitcnt lgkmcnt(" #n ")" ::: "memory")
; #define PG8_BAR __builtin_amdgcn_s_barrier()
; #define PG8_SCHED __builtin_amdgcn_sched_barrier(0)
;     ...
;             PG8_WAIT_V(8); PG8_WAIT_L(0); PG8_BAR; PG8_MMA(0, 0, At, B0); PG8_MMA(0, 1, At, B1); PG8_BAR; PG8_SCHED;
;             PG8_LDA(At, 1, 1); PG8_STAGE(PG8_SB(1, 0), b3, voffB); PG8_STAGE(PG8_SB(1, 1), b3 + hstepB, voffB); PG8_STAGE(PG8_SA(1, 0), a3, voffA);
;             PG8_WAIT_V(8); PG8_WAIT_L(0); PG8_BAR; PG8_MMA(1, 0, At, B0); PG8_MMA(1, 1, At, B1); PG8_BAR; PG8_SCHED;
.Ltl_kv_2d:
	s_waitcnt lgkmcnt(0)
	s_setprio 1
	s_barrier
	v_mfma_f32_16x16x32_bf16 v[94:97], v[144:147], v[176:179], v[94:97]
	v_mfma_f32_16x16x32_bf16 v[90:93], v[152:155], v[176:179], v[90:93]
	v_mfma_f32_16x16x32_bf16 v[86:89], v[144:147], v[184:187], v[86:89]
	v_mfma_f32_16x16x32_bf16 v[82:85], v[152:155], v[184:187], v[82:85]
	v_mfma_f32_16x16x32_bf16 v[78:81], v[144:147], v[192:195], v[78:81]
	v_mfma_f32_16x16x32_bf16 v[74:77], v[152:155], v[192:195], v[74:77]
	v_mfma_f32_16x16x32_bf16 v[70:73], v[144:147], v[200:203], v[70:73]
	v_mfma_f32_16x16x32_bf16 v[66:69], v[152:155], v[200:203], v[66:69]
	v_mfma_f32_16x16x32_bf16 v[94:97], v[148:151], v[180:183], v[94:97]
	v_mfma_f32_16x16x32_bf16 v[90:93], v[156:159], v[180:183], v[90:93]
	v_mfma_f32_16x16x32_bf16 v[86:89], v[148:151], v[188:191], v[86:89]
	v_mfma_f32_16x16x32_bf16 v[82:85], v[156:159], v[188:191], v[82:85]
	v_mfma_f32_16x16x32_bf16 v[78:81], v[148:151], v[196:199], v[78:81]
	v_mfma_f32_16x16x32_bf16 v[74:77], v[156:159], v[196:199], v[74:77]
	v_mfma_f32_16x16x32_bf16 v[70:73], v[148:151], v[208:211], v[70:73]
	v_mfma_f32_16x16x32_bf16 v[66:69], v[156:159], v[208:211], v[66:69]
	s_setprio 0
	s_setprio 1
	v_mfma_f32_16x16x32_bf16 v[30:33], v[160:163], v[176:179], v[30:33]
	v_mfma_f32_16x16x32_bf16 v[26:29], v[168:171], v[176:179], v[26:29]
	v_mfma_f32_16x16x32_bf16 v[22:25], v[160:163], v[184:187], v[22:25]
	v_mfma_f32_16x16x32_bf16 v[18:21], v[168:171], v[184:187], v[18:21]
	v_mfma_f32_16x16x32_bf16 v[14:17], v[160:163], v[192:195], v[14:17]
	v_mfma_f32_16x16x32_bf16 v[10:13], v[168:171], v[192:195], v[10:13]
	v_mfma_f32_16x16x32_bf16 v[6:9], v[160:163], v[200:203], v[6:9]
	v_mfma_f32_16x16x32_bf16 v[2:5], v[168:171], v[200:203], v[2:5]
	v_mfma_f32_16x16x32_bf16 v[30:33], v[164:167], v[180:183], v[30:33]
	v_mfma_f32_16x16x32_bf16 v[26:29], v[172:175], v[180:183], v[26:29]
	v_mfma_f32_16x16x32_bf16 v[22:25], v[164:167], v[188:191], v[22:25]
	v_mfma_f32_16x16x32_bf16 v[18:21], v[172:175], v[188:191], v[18:21]
	v_mfma_f32_16x16x32_bf16 v[14:17], v[164:167], v[196:199], v[14:17]
	v_mfma_f32_16x16x32_bf16 v[10:13], v[172:175], v[196:199], v[10:13]
	v_mfma_f32_16x16x32_bf16 v[6:9], v[164:167], v[208:211], v[6:9]
	v_mfma_f32_16x16x32_bf16 v[2:5], v[172:175], v[208:211], v[2:5]
	s_barrier
	s_setprio 0
	s_add_i32 s73, s73, 2
	s_add_u32 s15, s15, 0x100
	s_addc_u32 s60, s60, 0
	s_cmp_gt_u32 s73, 5
	s_mov_b64 s[20:21], s[6:7]
	s_cbranch_scc0 .LBB0_1454
	s_and_b64 vcc, exec, s[12:13]
	s_cbranch_vccz .LBB0_1457
	s_barrier

; #define PG8_STAGE(bufoff, gbase, voff) do { _Pragma("unroll") for (int _i = 0; _i < 2; ++_i) \
;         __builtin_amdgcn_global_load_lds((const unsigned*)((const char*)(gbase) + (voff)[_i]), (LAS unsigned*)(lds + (bufoff) + ldsw + _i * 8192), 16, 0, 0); } while (0)
; #define PG8_LDA(dst, b, h) do { _Pragma("unroll") for (int m = 0; m < NM; ++m) _Pragma("unroll") for (int k = 0; k < 2; ++k) dst[m][k] = *(const LAS bf16x8*)(lds + PG8_SA(b, h) + aoff + m * 2048 + k * 1024); } while (0)
; #define PG8_MMA(ai, bj, At, Bt) do { __builtin_amdgcn_s_setprio(1); _Pragma("unroll") for (int m = 0; m < NM; ++m) _Pragma("unroll") for (int n = 0; n < 2; ++n) _Pragma("unroll") for (int k = 0; k < 2; ++k) \
;         acc[ai][bj][m][n] = __builtin_amdgcn_mfma_f32_16x16x32_bf16(Bt[n][k], At[m][k], acc[ai][bj][m][n], 0, 0, 0); __builtin_amdgcn_s_setprio(0); } while (0)
; #define PG8_WAIT_V(n) asm volatile("s_waitcnt vmcnt(" #n ")" ::: "memory")
; #define PG8_WAIT_L(n) asm volatile("s_waitcnt lgkmcnt(" #n ")" ::: "memory")
; #define PG8_BAR __builtin_amdgcn_s_barrier()
; #define PG8_SCHED __builtin_amdgcn_sched_barrier(0)
;     ...
;             PG8_WAIT_V(8); PG8_WAIT_L(0); PG8_BAR; PG8_MMA(0, 0, At, B0); PG8_MMA(0, 1, At, B1); PG8_BAR; PG8_SCHED;
;             PG8_LDA(At, 0, 1); PG8_STAGE(PG8_SB(0, 0), b2, voffB); PG8_STAGE(PG8_SB(0, 1), b2 + hstepB, voffB); PG8_STAGE(PG8_SA(0, 0), a2, voffA);
.Lnm3o_done0:
	s_waitcnt lgkmcnt(0)
	s_setprio 1
	s_barrier
	v_mfma_f32_16x16x32_bf16 v[110:113], v[90:93], v[130:133], v[110:113]
	v_mfma_f32_16x16x32_bf16 v[106:109], v[98:101], v[130:133], v[106:109]
	v_mfma_f32_16x16x32_bf16 v[78:81], v[90:93], v[138:141], v[78:81]
	v_mfma_f32_16x16x32_bf16 v[74:77], v[98:101], v[138:141], v[74:77]
	v_mfma_f32_16x16x32_bf16 v[62:65], v[90:93], v[156:159], v[62:65]
	v_mfma_f32_16x16x32_bf16 v[58:61], v[98:101], v[156:159], v[58:61]
	v_mfma_f32_16x16x32_bf16 v[110:113], v[94:97], v[134:137], v[110:113]
	v_mfma_f32_16x16x32_bf16 v[106:109], v[102:105], v[134:137], v[106:109]
	v_mfma_f32_16x16x32_bf16 v[78:81], v[94:97], v[152:155], v[78:81]
	v_mfma_f32_16x16x32_bf16 v[74:77], v[102:105], v[152:155], v[74:77]
	v_mfma_f32_16x16x32_bf16 v[62:65], v[94:97], v[160:163], v[62:65]
	v_mfma_f32_16x16x32_bf16 v[58:61], v[102:105], v[160:163], v[58:61]
	s_setprio 0
	s_setprio 1
	v_mfma_f32_16x16x32_bf16 v[86:89], v[114:117], v[130:133], v[86:89]
	v_mfma_f32_16x16x32_bf16 v[82:85], v[122:125], v[130:133], v[82:85]
	v_mfma_f32_16x16x32_bf16 v[70:73], v[114:117], v[138:141], v[70:73]
	v_mfma_f32_16x16x32_bf16 v[66:69], v[122:125], v[138:141], v[66:69]
	v_mfma_f32_16x16x32_bf16 v[54:57], v[114:117], v[156:159], v[54:57]
	v_mfma_f32_16x16x32_bf16 v[50:53], v[122:125], v[156:159], v[50:53]
	v_mfma_f32_16x16x32_bf16 v[86:89], v[118:121], v[134:137], v[86:89]
	v_mfma_f32_16x16x32_bf16 v[82:85], v[126:129], v[134:137], v[82:85]
	v_mfma_f32_16x16x32_bf16 v[70:73], v[118:121], v[152:155], v[70:73]
	v_mfma_f32_16x16x32_bf16 v[66:69], v[126:129], v[152:155], v[66:69]
	v_mfma_f32_16x16x32_bf16 v[54:57], v[118:121], v[160:163], v[54:57]
	v_mfma_f32_16x16x32_bf16 v[50:53], v[126:129], v[160:163], v[50:53]
	s_barrier
	s_setprio 0
	s_mov_b32 m0, s29
	v_lshl_add_u64 v[164:165], s[22:23], 0, v[0:1]
	s_add_u32 s62, s22, 0x80000
	s_addc_u32 s63, s23, 0
	ds_read_b128 v[130:133], v167 offset:16384
	ds_read_b128 v[134:137], v167 offset:17408
	ds_read_b128 v[138:141], v167 offset:18432
	ds_read_b128 v[152:155], v167 offset:19456
	ds_read_b128 v[156:159], v167 offset:20480
	ds_read_b128 v[160:163], v167 offset:21504
	s_cmp_lg_u32 s100, 0
	s_cbranch_scc1 .Ltl_ou_0s
	global_load_lds_dwordx4 v0, s[22:23]
	v_lshl_add_u64 v[168:169], s[22:23], 0, v[146:147]
	s_mov_b32 m0, s30
	s_nop 0
	global_load_lds_dwordx4 v146, s[22:23]
	s_mov_b32 m0, s33
	v_lshl_add_u64 v[172:173], s[24:25], 0, v[144:145]
	global_load_lds_dwordx4 v0, s[62:63]
	s_mov_b32 m0, s34
	s_nop 0
	global_load_lds_dwordx4 v146, s[62:63]
	v_lshl_add_u64 v[170:171], s[24:25], 0, v[142:143]
	s_mov_b32 m0, s35
	s_nop 0
	global_load_lds_dwordx4 v142, s[24:25]
	s_mov_b32 m0, s36
	s_nop 0
	s_and_b64 vcc, exec, s[10:11]
	s_cbranch_vccz .Lnm3o_skip1
	global_load_lds_dwordx4 v144, s[24:25]
	s_waitcnt vmcnt(8)
	s_branch .Lnm3o_done1

; #define PG8_STAGE(bufoff, gbase, voff) do { _Pragma("unroll") for (int _i = 0; _i < 2; ++_i) \
;         __builtin_amdgcn_global_load_lds((const unsigned*)((const char*)(gbase) + (voff)[_i]), (LAS unsigned*)(lds + (bufoff) + ldsw + _i * 8192), 16, 0, 0); } while (0)
; #define PG8_LDA(dst, b, h) do { _Pragma("unroll") for (int m = 0; m < NM; ++m) _Pragma("unroll") for (int k = 0; k < 2; ++k) dst[m][k] = *(const LAS bf16x8*)(lds + PG8_SA(b, h) + aoff + m * 2048 + k * 1024); } while (0)
; #define PG8_LDB(dst, b, h) do { _Pragma("unroll") for (int n = 0; n < 2; ++n) _Pragma("unroll") for (int k = 0; k < 2; ++k) dst[n][k] = *(const LAS bf16x8*)(lds + PG8_SB(b, h) + boff + n * 2048 + k * 1024); } while (0)
; #define PG8_MMA(ai, bj, At, Bt) do { __builtin_amdgcn_s_setprio(1); _Pragma("unroll") for (int m = 0; m < NM; ++m) _Pragma("unroll") for (int n = 0; n < 2; ++n) _Pragma("unroll") for (int k = 0; k < 2; ++k) \
;         acc[ai][bj][m][n] = __builtin_amdgcn_mfma_f32_16x16x32_bf16(Bt[n][k], At[m][k], acc[ai][bj][m][n], 0, 0, 0); __builtin_amdgcn_s_setprio(0); } while (0)
; #define PG8_WAIT_V(n) asm volatile("s_waitcnt vmcnt(" #n ")" ::: "memory")
; #define PG8_WAIT_L(n) asm volatile("s_waitcnt lgkmcnt(" #n ")" ::: "memory")
; #define PG8_BAR __builtin_amdgcn_s_barrier()
; #define PG8_SCHED __builtin_amdgcn_sched_barrier(0)
;     ...
;             PG8_WAIT_V(8); PG8_WAIT_L(0); PG8_BAR; PG8_MMA(1, 0, At, B0); PG8_MMA(1, 1, At, B1); PG8_BAR; PG8_SCHED;
;             PG8_LDB(B0, 1, 0); PG8_LDB(B1, 1, 1); PG8_SCHED; PG8_LDA(At, 1, 0); PG8_STAGE(PG8_SA(0, 1), a2 + hstepA, voffA);
.Ltl_ou_0d:
	s_waitcnt lgkmcnt(0)
	s_setprio 1
	s_barrier
	v_mfma_f32_16x16x32_bf16 v[46:49], v[90:93], v[130:133], v[46:49]
	v_mfma_f32_16x16x32_bf16 v[42:45], v[98:101], v[130:133], v[42:45]
	v_mfma_f32_16x16x32_bf16 v[30:33], v[90:93], v[138:141], v[30:33]
	v_mfma_f32_16x16x32_bf16 v[26:29], v[98:101], v[138:141], v[26:29]
	v_mfma_f32_16x16x32_bf16 v[14:17], v[90:93], v[156:159], v[14:17]
	v_mfma_f32_16x16x32_bf16 v[10:13], v[98:101], v[156:159], v[10:13]
	v_mfma_f32_16x16x32_bf16 v[46:49], v[94:97], v[134:137], v[46:49]
	v_mfma_f32_16x16x32_bf16 v[42:45], v[102:105], v[134:137], v[42:45]
	v_mfma_f32_16x16x32_bf16 v[30:33], v[94:97], v[152:155], v[30:33]
	v_mfma_f32_16x16x32_bf16 v[26:29], v[102:105], v[152:155], v[26:29]
	v_mfma_f32_16x16x32_bf16 v[14:17], v[94:97], v[160:163], v[14:17]
	v_mfma_f32_16x16x32_bf16 v[10:13], v[102:105], v[160:163], v[10:13]
	s_setprio 0
	s_setprio 1
	v_mfma_f32_16x16x32_bf16 v[38:41], v[114:117], v[130:133], v[38:41]
	v_mfma_f32_16x16x32_bf16 v[34:37], v[122:125], v[130:133], v[34:37]
	v_mfma_f32_16x16x32_bf16 v[22:25], v[114:117], v[138:141], v[22:25]
	v_mfma_f32_16x16x32_bf16 v[18:21], v[122:125], v[138:141], v[18:21]
	v_mfma_f32_16x16x32_bf16 v[6:9], v[114:117], v[156:159], v[6:9]
	v_mfma_f32_16x16x32_bf16 v[2:5], v[122:125], v[156:159], v[2:5]
	v_mfma_f32_16x16x32_bf16 v[38:41], v[118:121], v[134:137], v[38:41]
	v_mfma_f32_16x16x32_bf16 v[34:37], v[126:129], v[134:137], v[34:37]
	v_mfma_f32_16x16x32_bf16 v[22:25], v[118:121], v[152:155], v[22:25]
	v_mfma_f32_16x16x32_bf16 v[18:21], v[126:129], v[152:155], v[18:21]
	v_mfma_f32_16x16x32_bf16 v[6:9], v[118:121], v[160:163], v[6:9]
	v_mfma_f32_16x16x32_bf16 v[2:5], v[126:129], v[160:163], v[2:5]
	s_barrier
	s_setprio 0
	v_add_u32_e32 v102, s40, v166
	v_add_u32_e32 v126, s45, v166
	ds_read_b128 v[90:93], v102
	ds_read_b128 v[94:97], v102 offset:1024
	ds_read_b128 v[98:101], v102 offset:2048
	ds_read_b128 v[102:105], v102 offset:3072
	ds_read_b128 v[114:117], v126
	ds_read_b128 v[118:121], v126 offset:1024
	ds_read_b128 v[122:125], v126 offset:2048
	ds_read_b128 v[126:129], v126 offset:3072
	s_add_u32 s24, s24, 0x60000
	s_addc_u32 s25, s25, 0
	s_mov_b32 m0, s37
	ds_read_b128 v[130:133], v167 offset:32768
	ds_read_b128 v[134:137], v167 offset:33792
	ds_read_b128 v[138:141], v167 offset:34816
	ds_read_b128 v[152:155], v167 offset:35840
	ds_read_b128 v[156:159], v167 offset:36864
	ds_read_b128 v[160:163], v167 offset:37888
	s_cmp_lg_u32 s100, 0
	s_cbranch_scc1 .Ltl_ou_1s
	global_load_lds_dwordx4 v142, s[24:25]
	s_mov_b32 m0, s38
	s_nop 0
	s_and_b64 vcc, exec, s[10:11]
	s_cbranch_vccz .Lnm3o_skip2
	global_load_lds_dwordx4 v144, s[24:25]
	s_waitcnt vmcnt(8)
	s_branch .Lnm3o_done2

; #define PG8_STAGE(bufoff, gbase, voff) do { _Pragma("unroll") for (int _i = 0; _i < 2; ++_i) \
;         __builtin_amdgcn_global_load_lds((const unsigned*)((const char*)(gbase) + (voff)[_i]), (LAS unsigned*)(lds + (bufoff) + ldsw + _i * 8192), 16, 0, 0); } while (0)
; #define PG8_LDA(dst, b, h) do { _Pragma("unroll") for (int m = 0; m < NM; ++m) _Pragma("unroll") for (int k = 0; k < 2; ++k) dst[m][k] = *(const LAS bf16x8*)(lds + PG8_SA(b, h) + aoff + m * 2048 + k * 1024); } while (0)
; #define PG8_MMA(ai, bj, At, Bt) do { __builtin_amdgcn_s_setprio(1); _Pragma("unroll") for (int m = 0; m < NM; ++m) _Pragma("unroll") for (int n = 0; n < 2; ++n) _Pragma("unroll") for (int k = 0; k < 2; ++k) \
;         acc[ai][bj][m][n] = __builtin_amdgcn_mfma_f32_16x16x32_bf16(Bt[n][k], At[m][k], acc[ai][bj][m][n], 0, 0, 0); __builtin_amdgcn_s_setprio(0); } while (0)
; #define PG8_WAIT_V(n) asm volatile("s_waitcnt vmcnt(" #n ")" ::: "memory")
; #define PG8_WAIT_L(n) asm volatile("s_waitcnt lgkmcnt(" #n ")" ::: "memory")
; #define PG8_BAR __builtin_amdgcn_s_barrier()
; #define PG8_SCHED __builtin_amdgcn_sched_barrier(0)
;     ...
;             PG8_WAIT_V(8); PG8_WAIT_L(0); PG8_BAR; PG8_MMA(0, 0, At, B0); PG8_MMA(0, 1, At, B1); PG8_BAR; PG8_SCHED;
;             PG8_LDA(At, 1, 1); PG8_STAGE(PG8_SB(1, 0), b3, voffB); PG8_STAGE(PG8_SB(1, 1), b3 + hstepB, voffB); PG8_STAGE(PG8_SA(1, 0), a3, voffA);
.Ltl_ou_1d:
	s_waitcnt lgkmcnt(0)
	s_setprio 1
	s_barrier
	v_mfma_f32_16x16x32_bf16 v[110:113], v[90:93], v[130:133], v[110:113]
	v_mfma_f32_16x16x32_bf16 v[106:109], v[98:101], v[130:133], v[106:109]
	v_mfma_f32_16x16x32_bf16 v[78:81], v[90:93], v[138:141], v[78:81]
	v_mfma_f32_16x16x32_bf16 v[74:77], v[98:101], v[138:141], v[74:77]
	v_mfma_f32_16x16x32_bf16 v[62:65], v[90:93], v[156:159], v[62:65]
	v_mfma_f32_16x16x32_bf16 v[58:61], v[98:101], v[156:159], v[58:61]
	v_mfma_f32_16x16x32_bf16 v[110:113], v[94:97], v[134:137], v[110:113]
	v_mfma_f32_16x16x32_bf16 v[106:109], v[102:105], v[134:137], v[106:109]
	v_mfma_f32_16x16x32_bf16 v[78:81], v[94:97], v[152:155], v[78:81]
	v_mfma_f32_16x16x32_bf16 v[74:77], v[102:105], v[152:155], v[74:77]
	v_mfma_f32_16x16x32_bf16 v[62:65], v[94:97], v[160:163], v[62:65]
	v_mfma_f32_16x16x32_bf16 v[58:61], v[102:105], v[160:163], v[58:61]
	s_setprio 0
	s_setprio 1
	v_mfma_f32_16x16x32_bf16 v[86:89], v[114:117], v[130:133], v[86:89]
	v_mfma_f32_16x16x32_bf16 v[82:85], v[122:125], v[130:133], v[82:85]
	v_mfma_f32_16x16x32_bf16 v[70:73], v[114:117], v[138:141], v[70:73]
	v_mfma_f32_16x16x32_bf16 v[66:69], v[122:125], v[138:141], v[66:69]
	v_mfma_f32_16x16x32_bf16 v[54:57], v[114:117], v[156:159], v[54:57]
	v_mfma_f32_16x16x32_bf16 v[50:53], v[122:125], v[156:159], v[50:53]
	v_mfma_f32_16x16x32_bf16 v[86:89], v[118:121], v[134:137], v[86:89]
	v_mfma_f32_16x16x32_bf16 v[82:85], v[126:129], v[134:137], v[82:85]
	v_mfma_f32_16x16x32_bf16 v[70:73], v[118:121], v[152:155], v[70:73]
	v_mfma_f32_16x16x32_bf16 v[66:69], v[126:129], v[152:155], v[66:69]
	v_mfma_f32_16x16x32_bf16 v[54:57], v[118:121], v[160:163], v[54:57]
	v_mfma_f32_16x16x32_bf16 v[50:53], v[126:129], v[160:163], v[50:53]
	s_barrier
	s_setprio 0
	s_mov_b32 m0, s41
	v_lshl_add_u64 v[164:165], v[164:165], 0, s[66:67]
	s_add_u32 s22, s22, 0x80080
	s_addc_u32 s23, s23, 0
	ds_read_b128 v[130:133], v167 offset:49152
	ds_read_b128 v[134:137], v167 offset:50176
	ds_read_b128 v[138:141], v167 offset:51200
	ds_read_b128 v[152:155], v167 offset:52224
	ds_read_b128 v[156:159], v167 offset:53248
	ds_read_b128 v[160:163], v167 offset:54272
	s_cmp_lg_u32 s100, 0
	s_cbranch_scc1 .Ltl_ou_2s
	global_load_lds_dwordx4 v[164:165], off
	v_lshl_add_u64 v[164:165], v[168:169], 0, s[66:67]
	s_mov_b32 m0, s42
	s_nop 0
	global_load_lds_dwordx4 v[164:165], off
	s_mov_b32 m0, s46
	s_nop 0
	global_load_lds_dwordx4 v0, s[22:23]
	s_mov_b32 m0, s47
	s_nop 0
	global_load_lds_dwordx4 v146, s[22:23]
	v_lshl_add_u64 v[164:165], v[170:171], 0, s[66:67]
	s_mov_b32 m0, s43
	s_nop 0
	global_load_lds_dwordx4 v[164:165], off
	v_lshl_add_u64 v[164:165], v[172:173], 0, s[66:67]
	s_mov_b32 m0, s44
	s_nop 0
	s_and_b64 vcc, exec, s[10:11]
	s_cbranch_vccz .Lnm3o_skip3
	global_load_lds_dwordx4 v[164:165], off
	s_waitcnt vmcnt(8)
	s_branch .Lnm3o_done3

; #define PG8_STAGE(bufoff, gbase, voff) do { _Pragma("unroll") for (int _i = 0; _i < 2; ++_i) \
;         __builtin_amdgcn_global_load_lds((const unsigned*)((const char*)(gbase) + (voff)[_i]), (LAS unsigned*)(lds + (bufoff) + ldsw + _i * 8192), 16, 0, 0); } while (0)
; #define PG8_LDA(dst, b, h) do { _Pragma("unroll") for (int m = 0; m < NM; ++m) _Pragma("unroll") for (int k = 0; k < 2; ++k) dst[m][k] = *(const LAS bf16x8*)(lds + PG8_SA(b, h) + aoff + m * 2048 + k * 1024); } while (0)
; #define PG8_MMA(ai, bj, At, Bt) do { __builtin_amdgcn_s_setprio(1); _Pragma("unroll") for (int m = 0; m < NM; ++m) _Pragma("unroll") for (int n = 0; n < 2; ++n) _Pragma("unroll") for (int k = 0; k < 2; ++k) \
;         acc[ai][bj][m][n] = __builtin_amdgcn_mfma_f32_16x16x32_bf16(Bt[n][k], At[m][k], acc[ai][bj][m][n], 0, 0, 0); __builtin_amdgcn_s_setprio(0); } while (0)
; #define PG8_WAIT_V(n) asm volatile("s_waitcnt vmcnt(" #n ")" ::: "memory")
; #define PG8_WAIT_L(n) asm volatile("s_waitcnt lgkmcnt(" #n ")" ::: "memory")
; #define PG8_BAR __builtin_amdgcn_s_barrier()
; #define PG8_SCHED __builtin_amdgcn_sched_barrier(0)
;     ...
;             PG8_LDA(At, 1, 1); PG8_STAGE(PG8_SB(1, 0), b3, voffB); PG8_STAGE(PG8_SB(1, 1), b3 + hstepB, voffB); PG8_STAGE(PG8_SA(1, 0), a3, voffA);
;             PG8_WAIT_V(8); PG8_WAIT_L(0); PG8_BAR; PG8_MMA(1, 0, At, B0); PG8_MMA(1, 1, At, B1); PG8_BAR; PG8_SCHED;
.Ltl_ou_2d:
	s_waitcnt lgkmcnt(0)
	s_setprio 1
	s_barrier
	v_mfma_f32_16x16x32_bf16 v[46:49], v[90:93], v[130:133], v[46:49]
	v_mfma_f32_16x16x32_bf16 v[42:45], v[98:101], v[130:133], v[42:45]
	v_mfma_f32_16x16x32_bf16 v[30:33], v[90:93], v[138:141], v[30:33]
	v_mfma_f32_16x16x32_bf16 v[26:29], v[98:101], v[138:141], v[26:29]
	v_mfma_f32_16x16x32_bf16 v[14:17], v[90:93], v[156:159], v[14:17]
	v_mfma_f32_16x16x32_bf16 v[10:13], v[98:101], v[156:159], v[10:13]
	v_mfma_f32_16x16x32_bf16 v[46:49], v[94:97], v[134:137], v[46:49]
	v_mfma_f32_16x16x32_bf16 v[42:45], v[102:105], v[134:137], v[42:45]
	v_mfma_f32_16x16x32_bf16 v[30:33], v[94:97], v[152:155], v[30:33]
	v_mfma_f32_16x16x32_bf16 v[26:29], v[102:105], v[152:155], v[26:29]
	v_mfma_f32_16x16x32_bf16 v[14:17], v[94:97], v[160:163], v[14:17]
	v_mfma_f32_16x16x32_bf16 v[10:13], v[102:105], v[160:163], v[10:13]
	s_setprio 0
	s_setprio 1
	v_mfma_f32_16x16x32_bf16 v[38:41], v[114:117], v[130:133], v[38:41]
	v_mfma_f32_16x16x32_bf16 v[34:37], v[122:125], v[130:133], v[34:37]
	v_mfma_f32_16x16x32_bf16 v[22:25], v[114:117], v[138:141], v[22:25]
	v_mfma_f32_16x16x32_bf16 v[18:21], v[122:125], v[138:141], v[18:21]
	v_mfma_f32_16x16x32_bf16 v[6:9], v[114:117], v[156:159], v[6:9]
	v_mfma_f32_16x16x32_bf16 v[2:5], v[122:125], v[156:159], v[2:5]
	v_mfma_f32_16x16x32_bf16 v[38:41], v[118:121], v[134:137], v[38:41]
	v_mfma_f32_16x16x32_bf16 v[34:37], v[126:129], v[134:137], v[34:37]
	v_mfma_f32_16x16x32_bf16 v[22:25], v[118:121], v[152:155], v[22:25]
	v_mfma_f32_16x16x32_bf16 v[18:21], v[126:129], v[152:155], v[18:21]
	v_mfma_f32_16x16x32_bf16 v[6:9], v[118:121], v[160:163], v[6:9]
	v_mfma_f32_16x16x32_bf16 v[2:5], v[126:129], v[160:163], v[2:5]
	s_barrier
	s_setprio 0
	s_add_i32 s59, s59, 2
	s_add_u32 s8, s8, 0x100
	s_addc_u32 s9, s9, 0
	s_add_u32 s15, s15, 0x100
	s_addc_u32 s58, s58, 0
	s_cmp_gt_u32 s59, 29
	s_cbranch_scc0 .LBB0_1650
	s_and_b64 vcc, exec, s[10:11]
	s_cbranch_vccz .LBB0_1653
	s_barrier

; #define PG8_STAGE(bufoff, gbase, voff) do { _Pragma("unroll") for (int _i = 0; _i < 2; ++_i) \
;         __builtin_amdgcn_global_load_lds((const unsigned*)((const char*)(gbase) + (voff)[_i]), (LAS unsigned*)(lds + (bufoff) + ldsw + _i * 8192), 16, 0, 0); } while (0)
; #define PG8_LDA(dst, b, h) do { _Pragma("unroll") for (int m = 0; m < NM; ++m) _Pragma("unroll") for (int k = 0; k < 2; ++k) dst[m][k] = *(const LAS bf16x8*)(lds + PG8_SA(b, h) + aoff + m * 2048 + k * 1024); } while (0)
; #define PG8_LDB(dst, b, h) do { _Pragma("unroll") for (int n = 0; n < 2; ++n) _Pragma("unroll") for (int k = 0; k < 2; ++k) dst[n][k] = *(const LAS bf16x8*)(lds + PG8_SB(b, h) + boff + n * 2048 + k * 1024); } while (0)
; #define PG8_MMA(ai, bj, At, Bt) do { __builtin_amdgcn_s_setprio(1); _Pragma("unroll") for (int m = 0; m < NM; ++m) _Pragma("unroll") for (int n = 0; n < 2; ++n) _Pragma("unroll") for (int k = 0; k < 2; ++k) \
;         acc[ai][bj][m][n] = __builtin_amdgcn_mfma_f32_16x16x32_bf16(Bt[n][k], At[m][k], acc[ai][bj][m][n], 0, 0, 0); __builtin_amdgcn_s_setprio(0); } while (0)
; #define PG8_WAIT_V(n) asm volatile("s_waitcnt vmcnt(" #n ")" ::: "memory")
; #define PG8_WAIT_L(n) asm volatile("s_waitcnt lgkmcnt(" #n ")" ::: "memory")
; #define PG8_BAR __builtin_amdgcn_s_barrier()
; #define PG8_SCHED __builtin_amdgcn_sched_barrier(0)
;     ...
;             const bool last = (t == nt - 2);
;             const char* a1 = cA + (size_t)(t + 1) * kstep;
;             const char* a2 = last ? nA : cA + (size_t)(t + 2) * kstep; const char* b2 = last ? nB : cB + (size_t)(t + 2) * kstep;
;             const char* a3 = a2 + kstep; const char* b3 = b2 + kstep;
;             if constexpr (SP2) {
;             PG8_LDB(B0, 0, 0); PG8_LDB(B1, 0, 1); PG8_SCHED; PG8_LDA(At, 0, 0); PG8_STAGE(PG8_SA(1, 1), a1 + hstepA, voffA);
;             PG8_WAIT_V(8); PG8_WAIT_L(0); PG8_BAR; PG8_MMA(0, 0, At, B0); PG8_MMA(0, 1, At, B1); PG8_BAR; PG8_SCHED;
;             PG8_LDA(At, 0, 1); PG8_STAGE(PG8_SB(0, 0), b2, voffB); PG8_STAGE(PG8_SB(0, 1), b2 + hstepB, voffB); PG8_STAGE(PG8_SA(0, 0), a2, voffA);
.LBB0_1783:
	v_add_u32_e32 v0, s64, v208
	ds_read_b128 v[130:133], v0
	ds_read_b128 v[134:137], v0 offset:1024
	ds_read_b128 v[138:141], v0 offset:2048
	ds_read_b128 v[142:145], v0 offset:3072
	v_add_u32_e32 v0, s70, v208
	ds_read_b128 v[146:149], v0
	ds_read_b128 v[150:153], v0 offset:1024
	ds_read_b128 v[154:157], v0 offset:2048
	ds_read_b128 v[158:161], v0 offset:3072
	s_add_u32 s14, s12, 0xfff80080
	s_addc_u32 s15, s13, -1
	s_cmp_eq_u32 vcc_lo, 28
	s_cselect_b32 s47, s2, s15
	s_cselect_b32 s46, s3, s14
	s_cselect_b32 s15, s9, s41
	s_cselect_b32 s14, s11, s37
	s_cselect_b32 s100, -1, 0
	s_andn2_b32 s100, s100, s101
	s_add_i32 m0, s73, 0xc000
	ds_read_b128 v[162:165], v209
	ds_read_b128 v[166:169], v209 offset:1024
	ds_read_b128 v[170:173], v209 offset:2048
	ds_read_b128 v[174:177], v209 offset:3072
	ds_read_b128 v[190:193], v209 offset:4096
	ds_read_b128 v[194:197], v209 offset:5120
	ds_read_b128 v[198:201], v209 offset:6144
	ds_read_b128 v[202:205], v209 offset:7168
	global_load_lds_dwordx4 v186, s[12:13]
	s_add_i32 m0, s73, 0xe000
	s_nop 0
	global_load_lds_dwordx4 v188, s[12:13]
	s_waitcnt vmcnt(8)
	s_waitcnt lgkmcnt(0)
	s_setprio 1
	s_barrier
	v_mfma_f32_16x16x32_bf16 v[126:129], v[130:133], v[162:165], v[126:129]
	v_mfma_f32_16x16x32_bf16 v[94:97], v[138:141], v[162:165], v[94:97]
	v_mfma_f32_16x16x32_bf16 v[110:113], v[130:133], v[170:173], v[110:113]
	v_mfma_f32_16x16x32_bf16 v[70:73], v[138:141], v[170:173], v[70:73]
	v_mfma_f32_16x16x32_bf16 v[106:109], v[130:133], v[190:193], v[106:109]
	v_mfma_f32_16x16x32_bf16 v[66:69], v[138:141], v[190:193], v[66:69]
	v_mfma_f32_16x16x32_bf16 v[118:121], v[130:133], v[198:201], v[118:121]
	v_mfma_f32_16x16x32_bf16 v[86:89], v[138:141], v[198:201], v[86:89]
	v_mfma_f32_16x16x32_bf16 v[126:129], v[134:137], v[166:169], v[126:129]
	v_mfma_f32_16x16x32_bf16 v[94:97], v[142:145], v[166:169], v[94:97]
	v_mfma_f32_16x16x32_bf16 v[110:113], v[134:137], v[174:177], v[110:113]
	v_mfma_f32_16x16x32_bf16 v[70:73], v[142:145], v[174:177], v[70:73]
	v_mfma_f32_16x16x32_bf16 v[106:109], v[134:137], v[194:197], v[106:109]
	v_mfma_f32_16x16x32_bf16 v[66:69], v[142:145], v[194:197], v[66:69]
	v_mfma_f32_16x16x32_bf16 v[118:121], v[134:137], v[202:205], v[118:121]
	v_mfma_f32_16x16x32_bf16 v[86:89], v[142:145], v[202:205], v[86:89]
	s_setprio 0
	s_setprio 1
	v_mfma_f32_16x16x32_bf16 v[122:125], v[146:149], v[162:165], v[122:125]
	v_mfma_f32_16x16x32_bf16 v[90:93], v[154:157], v[162:165], v[90:93]
	v_mfma_f32_16x16x32_bf16 v[102:105], v[146:149], v[170:173], v[102:105]
	v_mfma_f32_16x16x32_bf16 v[62:65], v[154:157], v[170:173], v[62:65]
	v_mfma_f32_16x16x32_bf16 v[98:101], v[146:149], v[190:193], v[98:101]
	v_mfma_f32_16x16x32_bf16 v[58:61], v[154:157], v[190:193], v[58:61]
	v_mfma_f32_16x16x32_bf16 v[114:117], v[146:149], v[198:201], v[114:117]
	v_mfma_f32_16x16x32_bf16 v[82:85], v[154:157], v[198:201], v[82:85]
	v_mfma_f32_16x16x32_bf16 v[122:125], v[150:153], v[166:169], v[122:125]
	v_mfma_f32_16x16x32_bf16 v[90:93], v[158:161], v[166:169], v[90:93]
	v_mfma_f32_16x16x32_bf16 v[102:105], v[150:153], v[174:177], v[102:105]
	v_mfma_f32_16x16x32_bf16 v[62:65], v[158:161], v[174:177], v[62:65]
	v_mfma_f32_16x16x32_bf16 v[98:101], v[150:153], v[194:197], v[98:101]
	v_mfma_f32_16x16x32_bf16 v[58:61], v[158:161], v[194:197], v[58:61]
	v_mfma_f32_16x16x32_bf16 v[114:117], v[150:153], v[202:205], v[114:117]
	v_mfma_f32_16x16x32_bf16 v[82:85], v[158:161], v[202:205], v[82:85]
	s_barrier
	s_setprio 0
	s_mov_b32 m0, s68
	s_add_u32 s22, s14, 0x80000
	s_addc_u32 s23, s15, 0
	ds_read_b128 v[162:165], v209 offset:16384
	ds_read_b128 v[166:169], v209 offset:17408
	ds_read_b128 v[170:173], v209 offset:18432
	ds_read_b128 v[174:177], v209 offset:19456
	ds_read_b128 v[190:193], v209 offset:20480
	ds_read_b128 v[194:197], v209 offset:21504
	ds_read_b128 v[198:201], v209 offset:22528
	ds_read_b128 v[202:205], v209 offset:23552
	s_cmp_lg_u32 s100, 0
	s_cbranch_scc1 .Ltl_up_0s
	global_load_lds_dwordx4 v180, s[14:15]
	s_mov_b32 m0, s69
	s_nop 0
	global_load_lds_dwordx4 v184, s[14:15]
	s_mov_b32 m0, s71
	s_nop 0
	global_load_lds_dwordx4 v180, s[22:23]
	s_mov_b32 m0, s72
	s_nop 0
	global_load_lds_dwordx4 v184, s[22:23]
	s_mov_b32 m0, s73
	s_nop 0
	global_load_lds_dwordx4 v178, s[46:47]
	s_mov_b32 m0, s74
	s_nop 0
	global_load_lds_dwordx4 v182, s[46:47]
	s_waitcnt vmcnt(8)
	s_branch .Ltl_up_0d

; #define PG8_STAGE(bufoff, gbase, voff) do { _Pragma("unroll") for (int _i = 0; _i < 2; ++_i) \
;         __builtin_amdgcn_global_load_lds((const unsigned*)((const char*)(gbase) + (voff)[_i]), (LAS unsigned*)(lds + (bufoff) + ldsw + _i * 8192), 16, 0, 0); } while (0)
; #define PG8_LDA(dst, b, h) do { _Pragma("unroll") for (int m = 0; m < NM; ++m) _Pragma("unroll") for (int k = 0; k < 2; ++k) dst[m][k] = *(const LAS bf16x8*)(lds + PG8_SA(b, h) + aoff + m * 2048 + k * 1024); } while (0)
; #define PG8_LDB(dst, b, h) do { _Pragma("unroll") for (int n = 0; n < 2; ++n) _Pragma("unroll") for (int k = 0; k < 2; ++k) dst[n][k] = *(const LAS bf16x8*)(lds + PG8_SB(b, h) + boff + n * 2048 + k * 1024); } while (0)
; #define PG8_MMA(ai, bj, At, Bt) do { __builtin_amdgcn_s_setprio(1); _Pragma("unroll") for (int m = 0; m < NM; ++m) _Pragma("unroll") for (int n = 0; n < 2; ++n) _Pragma("unroll") for (int k = 0; k < 2; ++k) \
;         acc[ai][bj][m][n] = __builtin_amdgcn_mfma_f32_16x16x32_bf16(Bt[n][k], At[m][k], acc[ai][bj][m][n], 0, 0, 0); __builtin_amdgcn_s_setprio(0); } while (0)
; #define PG8_WAIT_V(n) asm volatile("s_waitcnt vmcnt(" #n ")" ::: "memory")
; #define PG8_WAIT_L(n) asm volatile("s_waitcnt lgkmcnt(" #n ")" ::: "memory")
; #define PG8_BAR __builtin_amdgcn_s_barrier()
; #define PG8_SCHED __builtin_amdgcn_sched_barrier(0)
;     ...
;             PG8_WAIT_V(8); PG8_WAIT_L(0); PG8_BAR; PG8_MMA(1, 0, At, B0); PG8_MMA(1, 1, At, B1); PG8_BAR; PG8_SCHED;
;             PG8_LDB(B0, 1, 0); PG8_LDB(B1, 1, 1); PG8_SCHED; PG8_LDA(At, 1, 0); PG8_STAGE(PG8_SA(0, 1), a2 + hstepA, voffA);
.Ltl_up_0d:
	s_waitcnt lgkmcnt(0)
	s_setprio 1
	s_barrier
	v_mfma_f32_16x16x32_bf16 v[46:49], v[130:133], v[162:165], v[46:49]
	v_mfma_f32_16x16x32_bf16 v[22:25], v[138:141], v[162:165], v[22:25]
	v_mfma_f32_16x16x32_bf16 v[42:45], v[130:133], v[170:173], v[42:45]
	v_mfma_f32_16x16x32_bf16 v[18:21], v[138:141], v[170:173], v[18:21]
	v_mfma_f32_16x16x32_bf16 v[38:41], v[130:133], v[190:193], v[38:41]
	v_mfma_f32_16x16x32_bf16 v[14:17], v[138:141], v[190:193], v[14:17]
	v_mfma_f32_16x16x32_bf16 v[78:81], v[130:133], v[198:201], v[78:81]
	v_mfma_f32_16x16x32_bf16 v[54:57], v[138:141], v[198:201], v[54:57]
	v_mfma_f32_16x16x32_bf16 v[46:49], v[134:137], v[166:169], v[46:49]
	v_mfma_f32_16x16x32_bf16 v[22:25], v[142:145], v[166:169], v[22:25]
	v_mfma_f32_16x16x32_bf16 v[42:45], v[134:137], v[174:177], v[42:45]
	v_mfma_f32_16x16x32_bf16 v[18:21], v[142:145], v[174:177], v[18:21]
	v_mfma_f32_16x16x32_bf16 v[38:41], v[134:137], v[194:197], v[38:41]
	v_mfma_f32_16x16x32_bf16 v[14:17], v[142:145], v[194:197], v[14:17]
	v_mfma_f32_16x16x32_bf16 v[78:81], v[134:137], v[202:205], v[78:81]
	v_mfma_f32_16x16x32_bf16 v[54:57], v[142:145], v[202:205], v[54:57]
	s_setprio 0
	s_setprio 1
	v_mfma_f32_16x16x32_bf16 v[34:37], v[146:149], v[162:165], v[34:37]
	v_mfma_f32_16x16x32_bf16 v[10:13], v[154:157], v[162:165], v[10:13]
	v_mfma_f32_16x16x32_bf16 v[30:33], v[146:149], v[170:173], v[30:33]
	v_mfma_f32_16x16x32_bf16 v[6:9], v[154:157], v[170:173], v[6:9]
	v_mfma_f32_16x16x32_bf16 v[26:29], v[146:149], v[190:193], v[26:29]
	v_mfma_f32_16x16x32_bf16 v[2:5], v[154:157], v[190:193], v[2:5]
	v_mfma_f32_16x16x32_bf16 v[74:77], v[146:149], v[198:201], v[74:77]
	v_mfma_f32_16x16x32_bf16 v[50:53], v[154:157], v[198:201], v[50:53]
	v_mfma_f32_16x16x32_bf16 v[34:37], v[150:153], v[166:169], v[34:37]
	v_mfma_f32_16x16x32_bf16 v[10:13], v[158:161], v[166:169], v[10:13]
	v_mfma_f32_16x16x32_bf16 v[30:33], v[150:153], v[174:177], v[30:33]
	v_mfma_f32_16x16x32_bf16 v[6:9], v[158:161], v[174:177], v[6:9]
	v_mfma_f32_16x16x32_bf16 v[26:29], v[150:153], v[194:197], v[26:29]
	v_mfma_f32_16x16x32_bf16 v[2:5], v[158:161], v[194:197], v[2:5]
	v_mfma_f32_16x16x32_bf16 v[74:77], v[150:153], v[202:205], v[74:77]
	v_mfma_f32_16x16x32_bf16 v[50:53], v[158:161], v[202:205], v[50:53]
	s_barrier
	s_setprio 0
	v_add_u32_e32 v0, s94, v208
	ds_read_b128 v[130:133], v0
	ds_read_b128 v[134:137], v0 offset:1024
	ds_read_b128 v[138:141], v0 offset:2048
	ds_read_b128 v[142:145], v0 offset:3072
	v_add_u32_e32 v0, s62, v208
	ds_read_b128 v[146:149], v0
	ds_read_b128 v[150:153], v0 offset:1024
	ds_read_b128 v[154:157], v0 offset:2048
	ds_read_b128 v[158:161], v0 offset:3072
	s_add_u32 s22, s46, 0x80000
	s_addc_u32 s23, s47, 0
	s_mov_b32 m0, s75
	ds_read_b128 v[162:165], v209 offset:32768
	ds_read_b128 v[166:169], v209 offset:33792
	ds_read_b128 v[170:173], v209 offset:34816
	ds_read_b128 v[174:177], v209 offset:35840
	ds_read_b128 v[190:193], v209 offset:36864
	ds_read_b128 v[194:197], v209 offset:37888
	ds_read_b128 v[198:201], v209 offset:38912
	ds_read_b128 v[202:205], v209 offset:39936
	s_cmp_lg_u32 s100, 0
	s_cbranch_scc1 .Ltl_up_1s
	global_load_lds_dwordx4 v178, s[22:23]
	s_mov_b32 m0, s80
	s_nop 0
	global_load_lds_dwordx4 v182, s[22:23]
	s_waitcnt vmcnt(8)
	s_branch .Ltl_up_1d

; #define PG8_STAGE(bufoff, gbase, voff) do { _Pragma("unroll") for (int _i = 0; _i < 2; ++_i) \
;         __builtin_amdgcn_global_load_lds((const unsigned*)((const char*)(gbase) + (voff)[_i]), (LAS unsigned*)(lds + (bufoff) + ldsw + _i * 8192), 16, 0, 0); } while (0)
; #define PG8_LDA(dst, b, h) do { _Pragma("unroll") for (int m = 0; m < NM; ++m) _Pragma("unroll") for (int k = 0; k < 2; ++k) dst[m][k] = *(const LAS bf16x8*)(lds + PG8_SA(b, h) + aoff + m * 2048 + k * 1024); } while (0)
; #define PG8_MMA(ai, bj, At, Bt) do { __builtin_amdgcn_s_setprio(1); _Pragma("unroll") for (int m = 0; m < NM; ++m) _Pragma("unroll") for (int n = 0; n < 2; ++n) _Pragma("unroll") for (int k = 0; k < 2; ++k) \
;         acc[ai][bj][m][n] = __builtin_amdgcn_mfma_f32_16x16x32_bf16(Bt[n][k], At[m][k], acc[ai][bj][m][n], 0, 0, 0); __builtin_amdgcn_s_setprio(0); } while (0)
; #define PG8_WAIT_V(n) asm volatile("s_waitcnt vmcnt(" #n ")" ::: "memory")
; #define PG8_WAIT_L(n) asm volatile("s_waitcnt lgkmcnt(" #n ")" ::: "memory")
; #define PG8_BAR __builtin_amdgcn_s_barrier()
; #define PG8_SCHED __builtin_amdgcn_sched_barrier(0)
;     ...
;             PG8_WAIT_V(8); PG8_WAIT_L(0); PG8_BAR; PG8_MMA(0, 0, At, B0); PG8_MMA(0, 1, At, B1); PG8_BAR; PG8_SCHED;
;             PG8_LDA(At, 1, 1); PG8_STAGE(PG8_SB(1, 0), b3, voffB); PG8_STAGE(PG8_SB(1, 1), b3 + hstepB, voffB); PG8_STAGE(PG8_SA(1, 0), a3, voffA);
.Ltl_up_1d:
	s_waitcnt lgkmcnt(0)
	s_setprio 1
	s_barrier
	v_mfma_f32_16x16x32_bf16 v[126:129], v[130:133], v[162:165], v[126:129]
	v_mfma_f32_16x16x32_bf16 v[94:97], v[138:141], v[162:165], v[94:97]
	v_mfma_f32_16x16x32_bf16 v[110:113], v[130:133], v[170:173], v[110:113]
	v_mfma_f32_16x16x32_bf16 v[70:73], v[138:141], v[170:173], v[70:73]
	v_mfma_f32_16x16x32_bf16 v[106:109], v[130:133], v[190:193], v[106:109]
	v_mfma_f32_16x16x32_bf16 v[66:69], v[138:141], v[190:193], v[66:69]
	v_mfma_f32_16x16x32_bf16 v[118:121], v[130:133], v[198:201], v[118:121]
	v_mfma_f32_16x16x32_bf16 v[86:89], v[138:141], v[198:201], v[86:89]
	v_mfma_f32_16x16x32_bf16 v[126:129], v[134:137], v[166:169], v[126:129]
	v_mfma_f32_16x16x32_bf16 v[94:97], v[142:145], v[166:169], v[94:97]
	v_mfma_f32_16x16x32_bf16 v[110:113], v[134:137], v[174:177], v[110:113]
	v_mfma_f32_16x16x32_bf16 v[70:73], v[142:145], v[174:177], v[70:73]
	v_mfma_f32_16x16x32_bf16 v[106:109], v[134:137], v[194:197], v[106:109]
	v_mfma_f32_16x16x32_bf16 v[66:69], v[142:145], v[194:197], v[66:69]
	v_mfma_f32_16x16x32_bf16 v[118:121], v[134:137], v[202:205], v[118:121]
	v_mfma_f32_16x16x32_bf16 v[86:89], v[142:145], v[202:205], v[86:89]
	s_setprio 0
	s_setprio 1
	v_mfma_f32_16x16x32_bf16 v[122:125], v[146:149], v[162:165], v[122:125]
	v_mfma_f32_16x16x32_bf16 v[90:93], v[154:157], v[162:165], v[90:93]
	v_mfma_f32_16x16x32_bf16 v[102:105], v[146:149], v[170:173], v[102:105]
	v_mfma_f32_16x16x32_bf16 v[62:65], v[154:157], v[170:173], v[62:65]
	v_mfma_f32_16x16x32_bf16 v[98:101], v[146:149], v[190:193], v[98:101]
	v_mfma_f32_16x16x32_bf16 v[58:61], v[154:157], v[190:193], v[58:61]
	v_mfma_f32_16x16x32_bf16 v[114:117], v[146:149], v[198:201], v[114:117]
	v_mfma_f32_16x16x32_bf16 v[82:85], v[154:157], v[198:201], v[82:85]
	v_mfma_f32_16x16x32_bf16 v[122:125], v[150:153], v[166:169], v[122:125]
	v_mfma_f32_16x16x32_bf16 v[90:93], v[158:161], v[166:169], v[90:93]
	v_mfma_f32_16x16x32_bf16 v[102:105], v[150:153], v[174:177], v[102:105]
	v_mfma_f32_16x16x32_bf16 v[62:65], v[158:161], v[174:177], v[62:65]
	v_mfma_f32_16x16x32_bf16 v[98:101], v[150:153], v[194:197], v[98:101]
	v_mfma_f32_16x16x32_bf16 v[58:61], v[158:161], v[194:197], v[58:61]
	v_mfma_f32_16x16x32_bf16 v[114:117], v[150:153], v[202:205], v[114:117]
	v_mfma_f32_16x16x32_bf16 v[82:85], v[158:161], v[202:205], v[82:85]
	s_barrier
	s_setprio 0
	s_mov_b32 m0, s51
	s_add_u32 s22, s14, s66
	s_addc_u32 s23, s15, s67
	s_add_u32 s14, s14, 0x80080
	s_addc_u32 s15, s15, 0
	ds_read_b128 v[162:165], v209 offset:49152
	ds_read_b128 v[166:169], v209 offset:50176
	ds_read_b128 v[170:173], v209 offset:51200
	ds_read_b128 v[174:177], v209 offset:52224
	ds_read_b128 v[190:193], v209 offset:53248
	ds_read_b128 v[194:197], v209 offset:54272
	ds_read_b128 v[198:201], v209 offset:55296
	ds_read_b128 v[202:205], v209 offset:56320
	s_cmp_lg_u32 s100, 0
	s_cbranch_scc1 .Ltl_up_2s
	global_load_lds_dwordx4 v180, s[22:23]
	s_mov_b32 m0, s95
	s_nop 0
	global_load_lds_dwordx4 v184, s[22:23]
	s_add_u32 s22, s46, s66
	s_addc_u32 s23, s47, s67
	s_mov_b32 m0, s50
	s_nop 0
	global_load_lds_dwordx4 v180, s[14:15]
	s_mov_b32 m0, s49
	s_nop 0
	global_load_lds_dwordx4 v184, s[14:15]
	s_mov_b32 m0, s58
	s_nop 0
	global_load_lds_dwordx4 v178, s[22:23]
	s_mov_b32 m0, s59
	s_nop 0
	global_load_lds_dwordx4 v182, s[22:23]
	s_waitcnt vmcnt(8)
	s_branch .Ltl_up_2d

; #define PG8_STAGE(bufoff, gbase, voff) do { _Pragma("unroll") for (int _i = 0; _i < 2; ++_i) \
;         __builtin_amdgcn_global_load_lds((const unsigned*)((const char*)(gbase) + (voff)[_i]), (LAS unsigned*)(lds + (bufoff) + ldsw + _i * 8192), 16, 0, 0); } while (0)
; #define PG8_LDA(dst, b, h) do { _Pragma("unroll") for (int m = 0; m < NM; ++m) _Pragma("unroll") for (int k = 0; k < 2; ++k) dst[m][k] = *(const LAS bf16x8*)(lds + PG8_SA(b, h) + aoff + m * 2048 + k * 1024); } while (0)
; #define PG8_MMA(ai, bj, At, Bt) do { __builtin_amdgcn_s_setprio(1); _Pragma("unroll") for (int m = 0; m < NM; ++m) _Pragma("unroll") for (int n = 0; n < 2; ++n) _Pragma("unroll") for (int k = 0; k < 2; ++k) \
;         acc[ai][bj][m][n] = __builtin_amdgcn_mfma_f32_16x16x32_bf16(Bt[n][k], At[m][k], acc[ai][bj][m][n], 0, 0, 0); __builtin_amdgcn_s_setprio(0); } while (0)
; #define PG8_WAIT_V(n) asm volatile("s_waitcnt vmcnt(" #n ")" ::: "memory")
; #define PG8_WAIT_L(n) asm volatile("s_waitcnt lgkmcnt(" #n ")" ::: "memory")
; #define PG8_BAR __builtin_amdgcn_s_barrier()
; #define PG8_SCHED __builtin_amdgcn_sched_barrier(0)
;     ...
;             PG8_WAIT_V(8); PG8_WAIT_L(0); PG8_BAR; PG8_MMA(0, 0, At, B0); PG8_MMA(0, 1, At, B1); PG8_BAR; PG8_SCHED;
;             PG8_LDA(At, 1, 1); PG8_STAGE(PG8_SB(1, 0), b3, voffB); PG8_STAGE(PG8_SB(1, 1), b3 + hstepB, voffB); PG8_STAGE(PG8_SA(1, 0), a3, voffA);
;             PG8_WAIT_V(8); PG8_WAIT_L(0); PG8_BAR; PG8_MMA(1, 0, At, B0); PG8_MMA(1, 1, At, B1); PG8_BAR; PG8_SCHED;
.Ltl_up_2d:
	s_waitcnt lgkmcnt(0)
	s_setprio 1
	s_barrier
	v_mfma_f32_16x16x32_bf16 v[46:49], v[130:133], v[162:165], v[46:49]
	v_mfma_f32_16x16x32_bf16 v[22:25], v[138:141], v[162:165], v[22:25]
	v_mfma_f32_16x16x32_bf16 v[42:45], v[130:133], v[170:173], v[42:45]
	v_mfma_f32_16x16x32_bf16 v[18:21], v[138:141], v[170:173], v[18:21]
	v_mfma_f32_16x16x32_bf16 v[38:41], v[130:133], v[190:193], v[38:41]
	v_mfma_f32_16x16x32_bf16 v[14:17], v[138:141], v[190:193], v[14:17]
	v_mfma_f32_16x16x32_bf16 v[78:81], v[130:133], v[198:201], v[78:81]
	v_mfma_f32_16x16x32_bf16 v[54:57], v[138:141], v[198:201], v[54:57]
	v_mfma_f32_16x16x32_bf16 v[46:49], v[134:137], v[166:169], v[46:49]
	v_mfma_f32_16x16x32_bf16 v[22:25], v[142:145], v[166:169], v[22:25]
	v_mfma_f32_16x16x32_bf16 v[42:45], v[134:137], v[174:177], v[42:45]
	v_mfma_f32_16x16x32_bf16 v[18:21], v[142:145], v[174:177], v[18:21]
	v_mfma_f32_16x16x32_bf16 v[38:41], v[134:137], v[194:197], v[38:41]
	v_mfma_f32_16x16x32_bf16 v[14:17], v[142:145], v[194:197], v[14:17]
	v_mfma_f32_16x16x32_bf16 v[78:81], v[134:137], v[202:205], v[78:81]
	v_mfma_f32_16x16x32_bf16 v[54:57], v[142:145], v[202:205], v[54:57]
	s_setprio 0
	s_setprio 1
	v_mfma_f32_16x16x32_bf16 v[34:37], v[146:149], v[162:165], v[34:37]
	v_mfma_f32_16x16x32_bf16 v[10:13], v[154:157], v[162:165], v[10:13]
	v_mfma_f32_16x16x32_bf16 v[30:33], v[146:149], v[170:173], v[30:33]
	v_mfma_f32_16x16x32_bf16 v[6:9], v[154:157], v[170:173], v[6:9]
	v_mfma_f32_16x16x32_bf16 v[26:29], v[146:149], v[190:193], v[26:29]
	v_mfma_f32_16x16x32_bf16 v[2:5], v[154:157], v[190:193], v[2:5]
	v_mfma_f32_16x16x32_bf16 v[74:77], v[146:149], v[198:201], v[74:77]
	v_mfma_f32_16x16x32_bf16 v[50:53], v[154:157], v[198:201], v[50:53]
	v_mfma_f32_16x16x32_bf16 v[34:37], v[150:153], v[166:169], v[34:37]
	v_mfma_f32_16x16x32_bf16 v[10:13], v[158:161], v[166:169], v[10:13]
	v_mfma_f32_16x16x32_bf16 v[30:33], v[150:153], v[174:177], v[30:33]
	v_mfma_f32_16x16x32_bf16 v[6:9], v[158:161], v[174:177], v[6:9]
	v_mfma_f32_16x16x32_bf16 v[26:29], v[150:153], v[194:197], v[26:29]
	v_mfma_f32_16x16x32_bf16 v[2:5], v[158:161], v[194:197], v[2:5]
	v_mfma_f32_16x16x32_bf16 v[74:77], v[150:153], v[202:205], v[74:77]
	v_mfma_f32_16x16x32_bf16 v[50:53], v[158:161], v[202:205], v[50:53]
	s_barrier
	s_setprio 0
	s_add_i32 vcc_lo, vcc_lo, 2
	s_add_u32 s12, s12, 0x100
	s_addc_u32 s13, s13, 0
	s_add_u32 s37, s37, 0x100
	s_addc_u32 s41, s41, 0
	s_cmp_gt_u32 vcc_lo, 29
	s_cbranch_scc0 .LBB0_1783
	s_and_b64 vcc, exec, s[24:25]
	s_cbranch_vccz .LBB0_1786
	s_barrier

; #define PG8_STAGE(bufoff, gbase, voff) do { _Pragma("unroll") for (int _i = 0; _i < 2; ++_i) \
;         __builtin_amdgcn_global_load_lds((const unsigned*)((const char*)(gbase) + (voff)[_i]), (LAS unsigned*)(lds + (bufoff) + ldsw + _i * 8192), 16, 0, 0); } while (0)
; #define PG8_LDA(dst, b, h) do { _Pragma("unroll") for (int m = 0; m < NM; ++m) _Pragma("unroll") for (int k = 0; k < 2; ++k) dst[m][k] = *(const LAS bf16x8*)(lds + PG8_SA(b, h) + aoff + m * 2048 + k * 1024); } while (0)
; #define PG8_MMA(ai, bj, At, Bt) do { __builtin_amdgcn_s_setprio(1); _Pragma("unroll") for (int m = 0; m < NM; ++m) _Pragma("unroll") for (int n = 0; n < 2; ++n) _Pragma("unroll") for (int k = 0; k < 2; ++k) \
;         acc[ai][bj][m][n] = __builtin_amdgcn_mfma_f32_16x16x32_bf16(Bt[n][k], At[m][k], acc[ai][bj][m][n], 0, 0, 0); __builtin_amdgcn_s_setprio(0); } while (0)
; #define PG8_WAIT_V(n) asm volatile("s_waitcnt vmcnt(" #n ")" ::: "memory")
; #define PG8_WAIT_L(n) asm volatile("s_waitcnt lgkmcnt(" #n ")" ::: "memory")
; #define PG8_BAR __builtin_amdgcn_s_barrier()
; #define PG8_SCHED __builtin_amdgcn_sched_barrier(0)
;     ...
;             PG8_WAIT_V(8); PG8_WAIT_L(0); PG8_BAR; PG8_MMA(0, 0, At, B0); PG8_MMA(0, 1, At, B1); PG8_BAR; PG8_SCHED;
;             PG8_LDA(At, 0, 1); PG8_STAGE(PG8_SB(0, 0), b2, voffB); PG8_STAGE(PG8_SB(0, 1), b2 + hstepB, voffB); PG8_STAGE(PG8_SA(0, 0), a2, voffA);
.Lnm3d_done0:
	s_waitcnt lgkmcnt(0)
	s_setprio 1
	s_barrier
	v_mfma_f32_16x16x32_bf16 v[110:113], v[90:93], v[130:133], v[110:113]
	v_mfma_f32_16x16x32_bf16 v[106:109], v[98:101], v[130:133], v[106:109]
	v_mfma_f32_16x16x32_bf16 v[78:81], v[90:93], v[138:141], v[78:81]
	v_mfma_f32_16x16x32_bf16 v[74:77], v[98:101], v[138:141], v[74:77]
	v_mfma_f32_16x16x32_bf16 v[62:65], v[90:93], v[156:159], v[62:65]
	v_mfma_f32_16x16x32_bf16 v[58:61], v[98:101], v[156:159], v[58:61]
	v_mfma_f32_16x16x32_bf16 v[110:113], v[94:97], v[134:137], v[110:113]
	v_mfma_f32_16x16x32_bf16 v[106:109], v[102:105], v[134:137], v[106:109]
	v_mfma_f32_16x16x32_bf16 v[78:81], v[94:97], v[152:155], v[78:81]
	v_mfma_f32_16x16x32_bf16 v[74:77], v[102:105], v[152:155], v[74:77]
	v_mfma_f32_16x16x32_bf16 v[62:65], v[94:97], v[160:163], v[62:65]
	v_mfma_f32_16x16x32_bf16 v[58:61], v[102:105], v[160:163], v[58:61]
	s_setprio 0
	s_setprio 1
	v_mfma_f32_16x16x32_bf16 v[86:89], v[114:117], v[130:133], v[86:89]
	v_mfma_f32_16x16x32_bf16 v[82:85], v[122:125], v[130:133], v[82:85]
	v_mfma_f32_16x16x32_bf16 v[70:73], v[114:117], v[138:141], v[70:73]
	v_mfma_f32_16x16x32_bf16 v[66:69], v[122:125], v[138:141], v[66:69]
	v_mfma_f32_16x16x32_bf16 v[54:57], v[114:117], v[156:159], v[54:57]
	v_mfma_f32_16x16x32_bf16 v[50:53], v[122:125], v[156:159], v[50:53]
	v_mfma_f32_16x16x32_bf16 v[86:89], v[118:121], v[134:137], v[86:89]
	v_mfma_f32_16x16x32_bf16 v[82:85], v[126:129], v[134:137], v[82:85]
	v_mfma_f32_16x16x32_bf16 v[70:73], v[118:121], v[152:155], v[70:73]
	v_mfma_f32_16x16x32_bf16 v[66:69], v[126:129], v[152:155], v[66:69]
	v_mfma_f32_16x16x32_bf16 v[54:57], v[118:121], v[160:163], v[54:57]
	v_mfma_f32_16x16x32_bf16 v[50:53], v[126:129], v[160:163], v[50:53]
	s_barrier
	s_setprio 0
	s_mov_b32 m0, s27
	v_lshl_add_u64 v[164:165], s[18:19], 0, v[0:1]
	s_add_u32 s14, s18, 0x160000
	s_addc_u32 s15, s19, 0
	ds_read_b128 v[130:133], v167 offset:16384
	ds_read_b128 v[134:137], v167 offset:17408
	ds_read_b128 v[138:141], v167 offset:18432
	ds_read_b128 v[152:155], v167 offset:19456
	ds_read_b128 v[156:159], v167 offset:20480
	ds_read_b128 v[160:163], v167 offset:21504
	s_cmp_lg_u32 s100, 0
	s_cbranch_scc1 .Ltl_dn_0s
	global_load_lds_dwordx4 v0, s[18:19]
	v_lshl_add_u64 v[168:169], s[18:19], 0, v[146:147]
	s_mov_b32 m0, s28
	s_nop 0
	global_load_lds_dwordx4 v146, s[18:19]
	s_mov_b32 m0, s30
	v_lshl_add_u64 v[172:173], s[20:21], 0, v[144:145]
	global_load_lds_dwordx4 v0, s[14:15]
	s_mov_b32 m0, s31
	s_nop 0
	global_load_lds_dwordx4 v146, s[14:15]
	v_lshl_add_u64 v[170:171], s[20:21], 0, v[142:143]
	s_mov_b32 m0, s34
	s_nop 0
	global_load_lds_dwordx4 v142, s[20:21]
	s_mov_b32 m0, s35
	s_nop 0
	s_and_b64 vcc, exec, s[8:9]
	s_cbranch_vccz .Lnm3d_skip1
	global_load_lds_dwordx4 v144, s[20:21]
	s_waitcnt vmcnt(8)
	s_branch .Lnm3d_done1

; #define PG8_STAGE(bufoff, gbase, voff) do { _Pragma("unroll") for (int _i = 0; _i < 2; ++_i) \
;         __builtin_amdgcn_global_load_lds((const unsigned*)((const char*)(gbase) + (voff)[_i]), (LAS unsigned*)(lds + (bufoff) + ldsw + _i * 8192), 16, 0, 0); } while (0)
; #define PG8_LDA(dst, b, h) do { _Pragma("unroll") for (int m = 0; m < NM; ++m) _Pragma("unroll") for (int k = 0; k < 2; ++k) dst[m][k] = *(const LAS bf16x8*)(lds + PG8_SA(b, h) + aoff + m * 2048 + k * 1024); } while (0)
; #define PG8_LDB(dst, b, h) do { _Pragma("unroll") for (int n = 0; n < 2; ++n) _Pragma("unroll") for (int k = 0; k < 2; ++k) dst[n][k] = *(const LAS bf16x8*)(lds + PG8_SB(b, h) + boff + n * 2048 + k * 1024); } while (0)
; #define PG8_MMA(ai, bj, At, Bt) do { __builtin_amdgcn_s_setprio(1); _Pragma("unroll") for (int m = 0; m < NM; ++m) _Pragma("unroll") for (int n = 0; n < 2; ++n) _Pragma("unroll") for (int k = 0; k < 2; ++k) \
;         acc[ai][bj][m][n] = __builtin_amdgcn_mfma_f32_16x16x32_bf16(Bt[n][k], At[m][k], acc[ai][bj][m][n], 0, 0, 0); __builtin_amdgcn_s_setprio(0); } while (0)
; #define PG8_WAIT_V(n) asm volatile("s_waitcnt vmcnt(" #n ")" ::: "memory")
; #define PG8_WAIT_L(n) asm volatile("s_waitcnt lgkmcnt(" #n ")" ::: "memory")
; #define PG8_BAR __builtin_amdgcn_s_barrier()
; #define PG8_SCHED __builtin_amdgcn_sched_barrier(0)
;     ...
;             PG8_WAIT_V(8); PG8_WAIT_L(0); PG8_BAR; PG8_MMA(1, 0, At, B0); PG8_MMA(1, 1, At, B1); PG8_BAR; PG8_SCHED;
;             PG8_LDB(B0, 1, 0); PG8_LDB(B1, 1, 1); PG8_SCHED; PG8_LDA(At, 1, 0); PG8_STAGE(PG8_SA(0, 1), a2 + hstepA, voffA);
.Ltl_dn_0d:
	s_waitcnt lgkmcnt(0)
	s_setprio 1
	s_barrier
	v_mfma_f32_16x16x32_bf16 v[46:49], v[90:93], v[130:133], v[46:49]
	v_mfma_f32_16x16x32_bf16 v[42:45], v[98:101], v[130:133], v[42:45]
	v_mfma_f32_16x16x32_bf16 v[30:33], v[90:93], v[138:141], v[30:33]
	v_mfma_f32_16x16x32_bf16 v[26:29], v[98:101], v[138:141], v[26:29]
	v_mfma_f32_16x16x32_bf16 v[14:17], v[90:93], v[156:159], v[14:17]
	v_mfma_f32_16x16x32_bf16 v[10:13], v[98:101], v[156:159], v[10:13]
	v_mfma_f32_16x16x32_bf16 v[46:49], v[94:97], v[134:137], v[46:49]
	v_mfma_f32_16x16x32_bf16 v[42:45], v[102:105], v[134:137], v[42:45]
	v_mfma_f32_16x16x32_bf16 v[30:33], v[94:97], v[152:155], v[30:33]
	v_mfma_f32_16x16x32_bf16 v[26:29], v[102:105], v[152:155], v[26:29]
	v_mfma_f32_16x16x32_bf16 v[14:17], v[94:97], v[160:163], v[14:17]
	v_mfma_f32_16x16x32_bf16 v[10:13], v[102:105], v[160:163], v[10:13]
	s_setprio 0
	s_setprio 1
	v_mfma_f32_16x16x32_bf16 v[38:41], v[114:117], v[130:133], v[38:41]
	v_mfma_f32_16x16x32_bf16 v[34:37], v[122:125], v[130:133], v[34:37]
	v_mfma_f32_16x16x32_bf16 v[22:25], v[114:117], v[138:141], v[22:25]
	v_mfma_f32_16x16x32_bf16 v[18:21], v[122:125], v[138:141], v[18:21]
	v_mfma_f32_16x16x32_bf16 v[6:9], v[114:117], v[156:159], v[6:9]
	v_mfma_f32_16x16x32_bf16 v[2:5], v[122:125], v[156:159], v[2:5]
	v_mfma_f32_16x16x32_bf16 v[38:41], v[118:121], v[134:137], v[38:41]
	v_mfma_f32_16x16x32_bf16 v[34:37], v[126:129], v[134:137], v[34:37]
	v_mfma_f32_16x16x32_bf16 v[22:25], v[118:121], v[152:155], v[22:25]
	v_mfma_f32_16x16x32_bf16 v[18:21], v[126:129], v[152:155], v[18:21]
	v_mfma_f32_16x16x32_bf16 v[6:9], v[118:121], v[160:163], v[6:9]
	v_mfma_f32_16x16x32_bf16 v[2:5], v[126:129], v[160:163], v[2:5]
	s_barrier
	s_setprio 0
	v_add_u32_e32 v102, s38, v166
	v_add_u32_e32 v126, s45, v166
	ds_read_b128 v[90:93], v102
	ds_read_b128 v[94:97], v102 offset:1024
	ds_read_b128 v[98:101], v102 offset:2048
	ds_read_b128 v[102:105], v102 offset:3072
	ds_read_b128 v[114:117], v126
	ds_read_b128 v[118:121], v126 offset:1024
	ds_read_b128 v[122:125], v126 offset:2048
	ds_read_b128 v[126:129], v126 offset:3072
	s_add_u32 s14, s20, 0x108000
	s_addc_u32 s15, s21, 0
	s_mov_b32 m0, s36
	ds_read_b128 v[130:133], v167 offset:32768
	ds_read_b128 v[134:137], v167 offset:33792
	ds_read_b128 v[138:141], v167 offset:34816
	ds_read_b128 v[152:155], v167 offset:35840
	ds_read_b128 v[156:159], v167 offset:36864
	ds_read_b128 v[160:163], v167 offset:37888
	s_cmp_lg_u32 s100, 0
	s_cbranch_scc1 .Ltl_dn_1s
	global_load_lds_dwordx4 v142, s[14:15]
	s_mov_b32 m0, s37
	s_nop 0
	s_and_b64 vcc, exec, s[8:9]
	s_cbranch_vccz .Lnm3d_skip2
	global_load_lds_dwordx4 v144, s[14:15]
	s_waitcnt vmcnt(8)
	s_branch .Lnm3d_done2

; #define PG8_STAGE(bufoff, gbase, voff) do { _Pragma("unroll") for (int _i = 0; _i < 2; ++_i) \
;         __builtin_amdgcn_global_load_lds((const unsigned*)((const char*)(gbase) + (voff)[_i]), (LAS unsigned*)(lds + (bufoff) + ldsw + _i * 8192), 16, 0, 0); } while (0)
; #define PG8_LDA(dst, b, h) do { _Pragma("unroll") for (int m = 0; m < NM; ++m) _Pragma("unroll") for (int k = 0; k < 2; ++k) dst[m][k] = *(const LAS bf16x8*)(lds + PG8_SA(b, h) + aoff + m * 2048 + k * 1024); } while (0)
; #define PG8_MMA(ai, bj, At, Bt) do { __builtin_amdgcn_s_setprio(1); _Pragma("unroll") for (int m = 0; m < NM; ++m) _Pragma("unroll") for (int n = 0; n < 2; ++n) _Pragma("unroll") for (int k = 0; k < 2; ++k) \
;         acc[ai][bj][m][n] = __builtin_amdgcn_mfma_f32_16x16x32_bf16(Bt[n][k], At[m][k], acc[ai][bj][m][n], 0, 0, 0); __builtin_amdgcn_s_setprio(0); } while (0)
; #define PG8_WAIT_V(n) asm volatile("s_waitcnt vmcnt(" #n ")" ::: "memory")
; #define PG8_WAIT_L(n) asm volatile("s_waitcnt lgkmcnt(" #n ")" ::: "memory")
; #define PG8_BAR __builtin_amdgcn_s_barrier()
; #define PG8_SCHED __builtin_amdgcn_sched_barrier(0)
;     ...
;             PG8_WAIT_V(8); PG8_WAIT_L(0); PG8_BAR; PG8_MMA(0, 0, At, B0); PG8_MMA(0, 1, At, B1); PG8_BAR; PG8_SCHED;
;             PG8_LDA(At, 1, 1); PG8_STAGE(PG8_SB(1, 0), b3, voffB); PG8_STAGE(PG8_SB(1, 1), b3 + hstepB, voffB); PG8_STAGE(PG8_SA(1, 0), a3, voffA);
.Ltl_dn_1d:
	s_waitcnt lgkmcnt(0)
	s_setprio 1
	s_barrier
	v_mfma_f32_16x16x32_bf16 v[110:113], v[90:93], v[130:133], v[110:113]
	v_mfma_f32_16x16x32_bf16 v[106:109], v[98:101], v[130:133], v[106:109]
	v_mfma_f32_16x16x32_bf16 v[78:81], v[90:93], v[138:141], v[78:81]
	v_mfma_f32_16x16x32_bf16 v[74:77], v[98:101], v[138:141], v[74:77]
	v_mfma_f32_16x16x32_bf16 v[62:65], v[90:93], v[156:159], v[62:65]
	v_mfma_f32_16x16x32_bf16 v[58:61], v[98:101], v[156:159], v[58:61]
	v_mfma_f32_16x16x32_bf16 v[110:113], v[94:97], v[134:137], v[110:113]
	v_mfma_f32_16x16x32_bf16 v[106:109], v[102:105], v[134:137], v[106:109]
	v_mfma_f32_16x16x32_bf16 v[78:81], v[94:97], v[152:155], v[78:81]
	v_mfma_f32_16x16x32_bf16 v[74:77], v[102:105], v[152:155], v[74:77]
	v_mfma_f32_16x16x32_bf16 v[62:65], v[94:97], v[160:163], v[62:65]
	v_mfma_f32_16x16x32_bf16 v[58:61], v[102:105], v[160:163], v[58:61]
	s_setprio 0
	s_setprio 1
	v_mfma_f32_16x16x32_bf16 v[86:89], v[114:117], v[130:133], v[86:89]
	v_mfma_f32_16x16x32_bf16 v[82:85], v[122:125], v[130:133], v[82:85]
	v_mfma_f32_16x16x32_bf16 v[70:73], v[114:117], v[138:141], v[70:73]
	v_mfma_f32_16x16x32_bf16 v[66:69], v[122:125], v[138:141], v[66:69]
	v_mfma_f32_16x16x32_bf16 v[54:57], v[114:117], v[156:159], v[54:57]
	v_mfma_f32_16x16x32_bf16 v[50:53], v[122:125], v[156:159], v[50:53]
	v_mfma_f32_16x16x32_bf16 v[86:89], v[118:121], v[134:137], v[86:89]
	v_mfma_f32_16x16x32_bf16 v[82:85], v[126:129], v[134:137], v[82:85]
	v_mfma_f32_16x16x32_bf16 v[70:73], v[118:121], v[152:155], v[70:73]
	v_mfma_f32_16x16x32_bf16 v[66:69], v[126:129], v[152:155], v[66:69]
	v_mfma_f32_16x16x32_bf16 v[54:57], v[118:121], v[160:163], v[54:57]
	v_mfma_f32_16x16x32_bf16 v[50:53], v[126:129], v[160:163], v[50:53]
	s_barrier
	s_setprio 0
	s_mov_b32 m0, s41
	v_lshl_add_u64 v[164:165], v[164:165], 0, s[66:67]
	s_add_u32 s14, s18, 0x160080
	s_addc_u32 s15, s19, 0
	ds_read_b128 v[130:133], v167 offset:49152
	ds_read_b128 v[134:137], v167 offset:50176
	ds_read_b128 v[138:141], v167 offset:51200
	ds_read_b128 v[152:155], v167 offset:52224
	ds_read_b128 v[156:159], v167 offset:53248
	ds_read_b128 v[160:163], v167 offset:54272
	s_cmp_lg_u32 s100, 0
	s_cbranch_scc1 .Ltl_dn_2s
	global_load_lds_dwordx4 v[164:165], off
	v_lshl_add_u64 v[164:165], v[168:169], 0, s[66:67]
	s_mov_b32 m0, s42
	s_nop 0
	global_load_lds_dwordx4 v[164:165], off
	s_mov_b32 m0, s46
	s_nop 0
	global_load_lds_dwordx4 v0, s[14:15]
	s_mov_b32 m0, s47
	s_nop 0
	global_load_lds_dwordx4 v146, s[14:15]
	v_lshl_add_u64 v[164:165], v[170:171], 0, s[66:67]
	s_mov_b32 m0, s43
	s_nop 0
	global_load_lds_dwordx4 v[164:165], off
	v_lshl_add_u64 v[164:165], v[172:173], 0, s[66:67]
	s_mov_b32 m0, s44
	s_nop 0
	s_and_b64 vcc, exec, s[8:9]
	s_cbranch_vccz .Lnm3d_skip3
	global_load_lds_dwordx4 v[164:165], off
	s_waitcnt vmcnt(8)
	s_branch .Lnm3d_done3

; #define PG8_STAGE(bufoff, gbase, voff) do { _Pragma("unroll") for (int _i = 0; _i < 2; ++_i) \
;         __builtin_amdgcn_global_load_lds((const unsigned*)((const char*)(gbase) + (voff)[_i]), (LAS unsigned*)(lds + (bufoff) + ldsw + _i * 8192), 16, 0, 0); } while (0)
; #define PG8_LDA(dst, b, h) do { _Pragma("unroll") for (int m = 0; m < NM; ++m) _Pragma("unroll") for (int k = 0; k < 2; ++k) dst[m][k] = *(const LAS bf16x8*)(lds + PG8_SA(b, h) + aoff + m * 2048 + k * 1024); } while (0)
; #define PG8_MMA(ai, bj, At, Bt) do { __builtin_amdgcn_s_setprio(1); _Pragma("unroll") for (int m = 0; m < NM; ++m) _Pragma("unroll") for (int n = 0; n < 2; ++n) _Pragma("unroll") for (int k = 0; k < 2; ++k) \
;         acc[ai][bj][m][n] = __builtin_amdgcn_mfma_f32_16x16x32_bf16(Bt[n][k], At[m][k], acc[ai][bj][m][n], 0, 0, 0); __builtin_amdgcn_s_setprio(0); } while (0)
; #define PG8_WAIT_V(n) asm volatile("s_waitcnt vmcnt(" #n ")" ::: "memory")
; #define PG8_WAIT_L(n) asm volatile("s_waitcnt lgkmcnt(" #n ")" ::: "memory")
; #define PG8_BAR __builtin_amdgcn_s_barrier()
; #define PG8_SCHED __builtin_amdgcn_sched_barrier(0)
;     ...
;             PG8_LDA(At, 1, 1); PG8_STAGE(PG8_SB(1, 0), b3, voffB); PG8_STAGE(PG8_SB(1, 1), b3 + hstepB, voffB); PG8_STAGE(PG8_SA(1, 0), a3, voffA);
;             PG8_WAIT_V(8); PG8_WAIT_L(0); PG8_BAR; PG8_MMA(1, 0, At, B0); PG8_MMA(1, 1, At, B1); PG8_BAR; PG8_SCHED;
.Ltl_dn_2d:
	s_waitcnt lgkmcnt(0)
	s_setprio 1
	s_barrier
	v_mfma_f32_16x16x32_bf16 v[46:49], v[90:93], v[130:133], v[46:49]
	v_mfma_f32_16x16x32_bf16 v[42:45], v[98:101], v[130:133], v[42:45]
	v_mfma_f32_16x16x32_bf16 v[30:33], v[90:93], v[138:141], v[30:33]
	v_mfma_f32_16x16x32_bf16 v[26:29], v[98:101], v[138:141], v[26:29]
	v_mfma_f32_16x16x32_bf16 v[14:17], v[90:93], v[156:159], v[14:17]
	v_mfma_f32_16x16x32_bf16 v[10:13], v[98:101], v[156:159], v[10:13]
	v_mfma_f32_16x16x32_bf16 v[46:49], v[94:97], v[134:137], v[46:49]
	v_mfma_f32_16x16x32_bf16 v[42:45], v[102:105], v[134:137], v[42:45]
	v_mfma_f32_16x16x32_bf16 v[30:33], v[94:97], v[152:155], v[30:33]
	v_mfma_f32_16x16x32_bf16 v[26:29], v[102:105], v[152:155], v[26:29]
	v_mfma_f32_16x16x32_bf16 v[14:17], v[94:97], v[160:163], v[14:17]
	v_mfma_f32_16x16x32_bf16 v[10:13], v[102:105], v[160:163], v[10:13]
	s_setprio 0
	s_setprio 1
	v_mfma_f32_16x16x32_bf16 v[38:41], v[114:117], v[130:133], v[38:41]
	v_mfma_f32_16x16x32_bf16 v[34:37], v[122:125], v[130:133], v[34:37]
	v_mfma_f32_16x16x32_bf16 v[22:25], v[114:117], v[138:141], v[22:25]
	v_mfma_f32_16x16x32_bf16 v[18:21], v[122:125], v[138:141], v[18:21]
	v_mfma_f32_16x16x32_bf16 v[6:9], v[114:117], v[156:159], v[6:9]
	v_mfma_f32_16x16x32_bf16 v[2:5], v[122:125], v[156:159], v[2:5]
	v_mfma_f32_16x16x32_bf16 v[38:41], v[118:121], v[134:137], v[38:41]
	v_mfma_f32_16x16x32_bf16 v[34:37], v[126:129], v[134:137], v[34:37]
	v_mfma_f32_16x16x32_bf16 v[22:25], v[118:121], v[152:155], v[22:25]
	v_mfma_f32_16x16x32_bf16 v[18:21], v[126:129], v[152:155], v[18:21]
	v_mfma_f32_16x16x32_bf16 v[6:9], v[118:121], v[160:163], v[6:9]
	v_mfma_f32_16x16x32_bf16 v[2:5], v[126:129], v[160:163], v[2:5]
	s_barrier
	s_setprio 0
	s_add_i32 s60, s60, 2
	s_add_u32 s2, s2, 0x100
	s_addc_u32 s3, s3, 0
	s_cmpk_gt_u32 s60, 0x55
	s_mov_b64 s[14:15], s[16:17]
	s_cbranch_scc0 .LBB0_2158
	s_and_b64 vcc, exec, s[8:9]
	s_cbranch_vccz .LBB0_2161
	s_barrier
